# plus: windowed-attention loop max3/scalar-add rewrite, rowop next-row loads overlap compute (wait moved to the copies), conv-epilogue fast path without boundary masks
# speedup vs baseline: 1.0339x; 1.0061x over previous
;     DI void operator()(const f32x4 (&acc)[2][2][4][2], const Unit& u, int wr, int wc, int fr_in, int fq_in) const {
;     ...
;         asm volatile("s_waitcnt lgkmcnt(0)" ::: "memory"); __builtin_amdgcn_s_barrier(); asm volatile("" ::: "memory");
;         const int ch = 128 * u.pn + qpos;
; #pragma unroll
;         for (int ai = 0; ai < 2; ++ai) {
;             const int blk = 2 * ai + wr;
;             const int tr0 = 128 * ai + 64 * wr + fr;
;             u32x2 pk0[4];
; #pragma unroll
;             for (int n = 0; n < 2; ++n) {
;                 f32x4 ga[4];
; #pragma unroll
;                 for (int bj = 0; bj < 2; ++bj) {
;                     const LAS float* wp = wlb + 128 * bj + qpos + 4 * n;
;                     const f32x4 w0 = *(const LAS f32x4*)(wp), w1 = *(const LAS f32x4*)(wp + 256), w2 = *(const LAS f32x4*)(wp + 512), bb = *(const LAS f32x4*)(wp + 768);
;                     const f32x4 eprev = *(const LAS f32x4*)(exb + (((blk + 3) & 3) * 2 + 1) * 256 + 128 * bj + qpos + 4 * n);
;                     const f32x4 enext = *(const LAS f32x4*)(exb + (((blk + 1) & 3) * 2 + 0) * 256 + 128 * bj + qpos + 4 * n);
; #pragma unroll
;                     for (int m = 0; m < 4; ++m) {
;                         const int g = 254 * u.pm - 1 + tr0 + 16 * m;
;                         const int lmask = (g < NLAT) ? (T - 1) : (CL - 1);
;                         const bool hp = (g & lmask) != 0, hn = ((g + 1) & lmask) != 0;
;                         f32x4 sp = acc[ai][bj][m][n], sn = acc[ai][bj][m][n];
;                         if (m > 0 && fr == 15) sp = acc[ai][bj][m > 0 ? m - 1 : 0][n];
;                         if (m < 3 && fr == 0) sn = acc[ai][bj][m < 3 ? m + 1 : 3][n];
;                         f32x4 pv, nv;
;                         dpp_rot4<0>(pv, sp); dpp_rot4<1>(nv, sn);
;                         if (m == 0 && fr == 0) pv = eprev;
;                         if (m == 3 && fr == 15) nv = enext;
;                         if (!hp) pv = (f32x4){0.f, 0.f, 0.f, 0.f};
;                         if (!hn) nv = (f32x4){0.f, 0.f, 0.f, 0.f};
;                         const f32x4 uu = pv * w0 + acc[ai][bj][m][n] * w1 + nv * w2 + bb;
;                         if (bj == 0) { ga[m][0] = gelu_tanh(uu[0]); ga[m][1] = gelu_tanh(uu[1]); ga[m][2] = gelu_tanh(uu[2]); ga[m][3] = gelu_tanh(uu[3]); }
;                         else ga[m] = ga[m] * uu;
.LBB0_95:
	s_or_b64 exec, exec, s[0:1]
	s_mul_i32 s100, s52, 0xfe
	s_add_i32 s100, s100, -1
	s_cmp_gt_i32 s100, 0xfeff
	s_cbranch_scc1 .Lfp_slow
	s_and_b32 s100, s100, 0xfff
	s_add_i32 s100, s100, -1
	s_cmp_lt_u32 s100, 0xeff
	s_cbranch_scc1 .Lfp_body
.Lfp_slow:
	v_readlane_b32 s0, v254, 51
	v_lshlrev_b32_e32 v130, 2, v181
	v_lshl_add_u32 v131, s39, 12, v130
	v_add_u32_e32 v180, s0, v161
	v_readlane_b32 s0, v254, 18
	s_lshl_b32 s0, s0, 2
	s_add_i32 s0, s38, s0
	s_waitcnt lgkmcnt(0)
	s_barrier
	v_add_u32_e32 v179, 0x24000, v131
	v_add_u32_e32 v191, s0, v130
	v_readlane_b32 s0, v254, 50
	v_add_u32_e32 v184, -1, v180
	s_mul_i32 s65, s52, 0xfe
	v_lshl_add_u32 v192, s0, 2, v182
	s_waitcnt vmcnt(0)
	ds_read_b128 v[146:149], v179
	ds_read_b128 v[138:141], v179 offset:1024
	ds_read_b128 v[134:137], v179 offset:2048
	ds_read_b128 v[130:133], v179 offset:3072
	ds_read_b128 v[162:165], v191 offset:1024
	ds_read_b128 v[142:145], v192
	v_add_u32_e32 v183, s65, v184
	s_mov_b32 s33, 0x10000
	v_cmp_gt_i32_e32 vcc, s33, v183
	v_add_u32_e32 v168, s65, v180
	s_nop 1
	v_mov_b32_dpp v187, v124 row_ror:1 row_mask:0xf bank_mask:0xf
	v_mov_b32_dpp v188, v125 row_ror:1 row_mask:0xf bank_mask:0xf
	v_mov_b32_dpp v189, v126 row_ror:1 row_mask:0xf bank_mask:0xf
	v_mov_b32_dpp v190, v127 row_ror:1 row_mask:0xf bank_mask:0xf
	v_lshl_add_u32 v160, s42, 7, v181
	v_cndmask_b32_e32 v166, v204, v205, vcc
	v_cmp_eq_u32_e32 vcc, 0, v161
	v_and_b32_e32 v167, v166, v183
	v_and_b32_e32 v166, v166, v168
	v_cndmask_b32_e32 v168, v124, v120, vcc
	v_cndmask_b32_e32 v169, v125, v121, vcc
	v_cndmask_b32_e32 v185, v126, v122, vcc
	v_cndmask_b32_e32 v186, v127, v123, vcc
	s_nop 1
	v_mov_b32_dpp v193, v168 row_ror:15 row_mask:0xf bank_mask:0xf
	v_mov_b32_dpp v194, v169 row_ror:15 row_mask:0xf bank_mask:0xf
	v_mov_b32_dpp v195, v185 row_ror:15 row_mask:0xf bank_mask:0xf
	v_mov_b32_dpp v196, v186 row_ror:15 row_mask:0xf bank_mask:0xf
	s_waitcnt lgkmcnt(1)
	v_cndmask_b32_e32 v168, v187, v162, vcc
	v_cndmask_b32_e32 v169, v188, v163, vcc
	v_cmp_eq_u32_e64 s[44:45], 0, v167
	v_cndmask_b32_e32 v162, v189, v164, vcc
	v_cndmask_b32_e32 v163, v190, v165, vcc
	v_cndmask_b32_e64 v165, v169, 0, s[44:45]
	v_cndmask_b32_e64 v164, v168, 0, s[44:45]
	v_pk_mul_f32 v[164:165], v[146:147], v[164:165]
	v_cmp_eq_u32_e64 s[46:47], 0, v166
	v_cndmask_b32_e64 v163, v163, 0, s[44:45]
	v_cndmask_b32_e64 v162, v162, 0, s[44:45]
	v_pk_fma_f32 v[164:165], v[124:125], v[138:139], v[164:165]
	v_cndmask_b32_e64 v169, v194, 0, s[46:47]
	v_cndmask_b32_e64 v168, v193, 0, s[46:47]
	v_pk_mul_f32 v[162:163], v[148:149], v[162:163]
	v_pk_fma_f32 v[164:165], v[134:135], v[168:169], v[164:165]
	v_pk_fma_f32 v[162:163], v[126:127], v[140:141], v[162:163]
	v_cndmask_b32_e64 v167, v196, 0, s[46:47]
	v_cndmask_b32_e64 v166, v195, 0, s[46:47]
	v_pk_add_f32 v[164:165], v[130:131], v[164:165]
	v_pk_fma_f32 v[162:163], v[136:137], v[166:167], v[162:163]
	v_mul_f32_e32 v166, v164, v164
	v_fmamk_f32 v166, v166, 0xbdd2d3e7, v198
	v_mul_f32_e32 v167, v165, v165
	v_pk_add_f32 v[162:163], v[132:133], v[162:163]
	v_mul_f32_e32 v166, v164, v166
	v_fmamk_f32 v167, v167, 0xbdd2d3e7, v198
	v_mul_f32_e32 v168, v162, v162
	v_exp_f32_e32 v166, v166
	v_mul_f32_e32 v167, v165, v167
	v_fmamk_f32 v168, v168, 0xbdd2d3e7, v198
	v_exp_f32_e32 v167, v167
	v_mul_f32_e32 v168, v162, v168
	v_mul_f32_e32 v169, v163, v163
	v_exp_f32_e32 v168, v168
	v_fmamk_f32 v169, v169, 0xbdd2d3e7, v198
	v_mul_f32_e32 v169, v163, v169
	v_add_f32_e32 v166, 1.0, v166
	v_exp_f32_e32 v169, v169
	v_rcp_f32_e32 v166, v166
	v_add_f32_e32 v167, 1.0, v167
	v_rcp_f32_e32 v167, v167
	v_add_f32_e32 v168, 1.0, v168
	v_add_u32_e32 v186, 15, v180
	v_rcp_f32_e32 v168, v168
	v_add_u32_e32 v185, s65, v186
	v_add_f32_e32 v169, 1.0, v169
	v_cmp_gt_i32_e64 s[0:1], s33, v185
	v_rcp_f32_e32 v169, v169
	v_mul_f32_e32 v164, v164, v166
	v_cndmask_b32_e64 v166, v204, v205, s[0:1]
	v_mul_f32_e32 v165, v165, v167
	v_and_b32_e32 v167, v166, v185
	v_cmp_eq_u32_e64 s[42:43], 15, v161
	v_mul_f32_e32 v162, v162, v168
	v_add_u32_e32 v168, 1, v185
	v_cndmask_b32_e64 v126, v122, v126, s[42:43]
	v_cndmask_b32_e64 v127, v123, v127, s[42:43]
	v_cmp_eq_u32_e64 s[48:49], 0, v167
	v_and_b32_e32 v166, v166, v168
	v_cndmask_b32_e64 v124, v120, v124, s[42:43]
	v_cndmask_b32_e64 v125, v121, v125, s[42:43]
	s_nop 1
	v_mov_b32_dpp v188, v124 row_ror:1 row_mask:0xf bank_mask:0xf
	v_mov_b32_dpp v189, v125 row_ror:1 row_mask:0xf bank_mask:0xf
	v_mov_b32_dpp v190, v126 row_ror:1 row_mask:0xf bank_mask:0xf
	v_mov_b32_dpp v193, v127 row_ror:1 row_mask:0xf bank_mask:0xf
	v_mul_f32_e32 v163, v163, v169
	v_cndmask_b32_e64 v127, v189, 0, s[48:49]
	v_cndmask_b32_e64 v126, v188, 0, s[48:49]
	v_cndmask_b32_e32 v168, v121, v117, vcc
	v_cndmask_b32_e32 v169, v122, v118, vcc
	v_pk_mul_f32 v[126:127], v[146:147], v[126:127]
	v_cmp_eq_u32_e64 s[50:51], 0, v166
	v_cndmask_b32_e32 v161, v120, v116, vcc
	v_cndmask_b32_e32 v187, v123, v119, vcc
	s_nop 1
	v_mov_b32_dpp v194, v161 row_ror:15 row_mask:0xf bank_mask:0xf
	v_mov_b32_dpp v195, v168 row_ror:15 row_mask:0xf bank_mask:0xf
	v_mov_b32_dpp v196, v169 row_ror:15 row_mask:0xf bank_mask:0xf
	v_mov_b32_dpp v197, v187 row_ror:15 row_mask:0xf bank_mask:0xf
	v_cndmask_b32_e64 v125, v193, 0, s[48:49]
	v_cndmask_b32_e64 v124, v190, 0, s[48:49]
	v_pk_fma_f32 v[126:127], v[120:121], v[138:139], v[126:127]
	v_cndmask_b32_e64 v169, v195, 0, s[50:51]
	v_cndmask_b32_e64 v168, v194, 0, s[50:51]
	v_pk_mul_f32 v[124:125], v[148:149], v[124:125]
	v_pk_fma_f32 v[126:127], v[134:135], v[168:169], v[126:127]
	v_pk_fma_f32 v[124:125], v[122:123], v[140:141], v[124:125]
	v_cndmask_b32_e64 v167, v197, 0, s[50:51]
; #define LAS __attribute__((address_space(3)))
;     DI void operator()(const f32x4 (&acc)[2][2][4][2], const Unit& u, int wr, int wc, int fr_in, int fq_in) const {
;     ...
;                     const LAS float* wp = wlb + 128 * bj + qpos + 4 * n;
;                     const f32x4 w0 = *(const LAS f32x4*)(wp), w1 = *(const LAS f32x4*)(wp + 256), w2 = *(const LAS f32x4*)(wp + 512), bb = *(const LAS f32x4*)(wp + 768);
;                     const f32x4 eprev = *(const LAS f32x4*)(exb + (((blk + 3) & 3) * 2 + 1) * 256 + 128 * bj + qpos + 4 * n);
;                     const f32x4 enext = *(const LAS f32x4*)(exb + (((blk + 1) & 3) * 2 + 0) * 256 + 128 * bj + qpos + 4 * n);
; #pragma unroll
;                     for (int m = 0; m < 4; ++m) {
;                         const int g = 254 * u.pm - 1 + tr0 + 16 * m;
;                         const int lmask = (g < NLAT) ? (T - 1) : (CL - 1);
;                         const bool hp = (g & lmask) != 0, hn = ((g + 1) & lmask) != 0;
;                         f32x4 sp = acc[ai][bj][m][n], sn = acc[ai][bj][m][n];
;                         if (m > 0 && fr == 15) sp = acc[ai][bj][m > 0 ? m - 1 : 0][n];
;                         if (m < 3 && fr == 0) sn = acc[ai][bj][m < 3 ? m + 1 : 3][n];
;                         f32x4 pv, nv;
;                         dpp_rot4<0>(pv, sp); dpp_rot4<1>(nv, sn);
;                         if (m == 0 && fr == 0) pv = eprev;
;                         if (m == 3 && fr == 15) nv = enext;
;                         if (!hp) pv = (f32x4){0.f, 0.f, 0.f, 0.f};
;                         if (!hn) nv = (f32x4){0.f, 0.f, 0.f, 0.f};
;                         const f32x4 uu = pv * w0 + acc[ai][bj][m][n] * w1 + nv * w2 + bb;
;                         if (bj == 0) { ga[m][0] = gelu_tanh(uu[0]); ga[m][1] = gelu_tanh(uu[1]); ga[m][2] = gelu_tanh(uu[2]); ga[m][3] = gelu_tanh(uu[3]); }
;                         else ga[m] = ga[m] * uu;
	v_cndmask_b32_e64 v166, v196, 0, s[50:51]
	v_pk_add_f32 v[126:127], v[130:131], v[126:127]
	v_pk_fma_f32 v[124:125], v[136:137], v[166:167], v[124:125]
	v_mul_f32_e32 v161, v126, v126
	v_fmamk_f32 v161, v161, 0xbdd2d3e7, v198
	v_mul_f32_e32 v166, v127, v127
	v_pk_add_f32 v[124:125], v[132:133], v[124:125]
	v_mul_f32_e32 v161, v126, v161
	v_fmamk_f32 v166, v166, 0xbdd2d3e7, v198
	v_mul_f32_e32 v167, v124, v124
	v_exp_f32_e32 v161, v161
	v_mul_f32_e32 v166, v127, v166
	v_fmamk_f32 v167, v167, 0xbdd2d3e7, v198
	v_exp_f32_e32 v166, v166
	v_mul_f32_e32 v167, v124, v167
	v_mul_f32_e32 v168, v125, v125
	v_exp_f32_e32 v167, v167
	v_fmamk_f32 v168, v168, 0xbdd2d3e7, v198
	v_mul_f32_e32 v168, v125, v168
	v_add_f32_e32 v161, 1.0, v161
	v_exp_f32_e32 v168, v168
	v_rcp_f32_e32 v161, v161
	v_add_f32_e32 v166, 1.0, v166
	v_rcp_f32_e32 v166, v166
	v_add_f32_e32 v167, 1.0, v167
	v_add_u32_e32 v188, 31, v180
	v_rcp_f32_e32 v167, v167
	v_add_u32_e32 v187, s65, v188
	v_add_f32_e32 v168, 1.0, v168
	v_cmp_gt_i32_e64 s[0:1], s33, v187
	v_rcp_f32_e32 v168, v168
	v_mul_f32_e32 v126, v126, v161
	v_cndmask_b32_e64 v161, v204, v205, s[0:1]
	v_mul_f32_e32 v127, v127, v166
	v_and_b32_e32 v166, v161, v187
	v_mul_f32_e32 v124, v124, v167
	v_add_u32_e32 v167, 1, v187
	v_cndmask_b32_e64 v120, v116, v120, s[42:43]
	v_cndmask_b32_e64 v121, v117, v121, s[42:43]
	v_cndmask_b32_e64 v122, v118, v122, s[42:43]
	v_cndmask_b32_e64 v123, v119, v123, s[42:43]
	v_cmp_eq_u32_e64 s[52:53], 0, v166
	v_and_b32_e32 v161, v161, v167
	s_nop 1
	v_mov_b32_dpp v190, v120 row_ror:1 row_mask:0xf bank_mask:0xf
	v_mov_b32_dpp v193, v121 row_ror:1 row_mask:0xf bank_mask:0xf
	v_mov_b32_dpp v194, v122 row_ror:1 row_mask:0xf bank_mask:0xf
	v_mov_b32_dpp v195, v123 row_ror:1 row_mask:0xf bank_mask:0xf
	v_mul_f32_e32 v125, v125, v168
	v_cndmask_b32_e64 v121, v195, 0, s[52:53]
	v_cndmask_b32_e64 v120, v194, 0, s[52:53]
	v_cndmask_b32_e64 v123, v193, 0, s[52:53]
	v_cndmask_b32_e64 v122, v190, 0, s[52:53]
	v_cndmask_b32_e32 v167, v116, v112, vcc
	v_cndmask_b32_e32 v168, v117, v113, vcc
	v_cndmask_b32_e32 v169, v118, v114, vcc
	v_pk_mul_f32 v[122:123], v[146:147], v[122:123]
	v_pk_mul_f32 v[120:121], v[148:149], v[120:121]
	v_cmp_eq_u32_e64 s[54:55], 0, v161
	v_cndmask_b32_e32 v189, v119, v115, vcc
	s_nop 1
	v_mov_b32_dpp v196, v167 row_ror:15 row_mask:0xf bank_mask:0xf
	v_mov_b32_dpp v197, v168 row_ror:15 row_mask:0xf bank_mask:0xf
	v_mov_b32_dpp v200, v169 row_ror:15 row_mask:0xf bank_mask:0xf
	v_mov_b32_dpp v201, v189 row_ror:15 row_mask:0xf bank_mask:0xf
	v_pk_fma_f32 v[120:121], v[118:119], v[140:141], v[120:121]
	v_pk_fma_f32 v[122:123], v[116:117], v[138:139], v[122:123]
	v_cndmask_b32_e64 v167, v201, 0, s[54:55]
	v_cndmask_b32_e64 v166, v200, 0, s[54:55]
	v_cndmask_b32_e64 v169, v197, 0, s[54:55]
	v_cndmask_b32_e64 v168, v196, 0, s[54:55]
	v_pk_fma_f32 v[122:123], v[134:135], v[168:169], v[122:123]
	v_pk_fma_f32 v[120:121], v[136:137], v[166:167], v[120:121]
	v_pk_add_f32 v[122:123], v[130:131], v[122:123]
	v_pk_add_f32 v[120:121], v[132:133], v[120:121]
	v_mul_f32_e32 v166, v123, v123
	v_mul_f32_e32 v167, v120, v120
	v_mul_f32_e32 v168, v121, v121
	v_fmamk_f32 v166, v166, 0xbdd2d3e7, v198
	v_fmamk_f32 v167, v167, 0xbdd2d3e7, v198
	v_fmamk_f32 v168, v168, 0xbdd2d3e7, v198
	v_mul_f32_e32 v166, v123, v166
	v_mul_f32_e32 v167, v120, v167
	v_mul_f32_e32 v168, v121, v168
	v_exp_f32_e32 v166, v166
	v_exp_f32_e32 v167, v167
	v_exp_f32_e32 v168, v168
	v_mul_f32_e32 v161, v122, v122
	v_fmamk_f32 v161, v161, 0xbdd2d3e7, v198
	v_mul_f32_e32 v161, v122, v161
	v_exp_f32_e32 v161, v161
	v_add_f32_e32 v166, 1.0, v166
	v_add_f32_e32 v167, 1.0, v167
	v_add_f32_e32 v168, 1.0, v168
	v_rcp_f32_e32 v166, v166
	v_rcp_f32_e32 v167, v167
	v_rcp_f32_e32 v189, v168
	v_add_f32_e32 v161, 1.0, v161
	v_add_u32_e32 v190, 47, v180
	v_rcp_f32_e32 v161, v161
	v_mul_f32_e32 v169, v123, v166
	v_mul_f32_e32 v166, v120, v167
	v_mul_f32_e32 v167, v121, v189
	v_add_u32_e32 v189, s65, v190
	v_cmp_gt_i32_e64 s[0:1], s33, v189
	v_mul_f32_e32 v168, v122, v161
	v_add_u32_e32 v122, 1, v189
	v_cndmask_b32_e64 v120, v204, v205, s[0:1]
	v_and_b32_e32 v121, v120, v189
	v_cndmask_b32_e64 v116, v112, v116, s[42:43]
	v_cndmask_b32_e64 v117, v113, v117, s[42:43]
	v_cndmask_b32_e64 v118, v114, v118, s[42:43]
	v_cndmask_b32_e64 v119, v115, v119, s[42:43]
	v_cmp_eq_u32_e64 s[56:57], 0, v121
	v_and_b32_e32 v120, v120, v122
	s_nop 1
	v_mov_b32_dpp v122, v116 row_ror:1 row_mask:0xf bank_mask:0xf
	v_mov_b32_dpp v123, v117 row_ror:1 row_mask:0xf bank_mask:0xf
	v_mov_b32_dpp v161, v118 row_ror:1 row_mask:0xf bank_mask:0xf
	v_mov_b32_dpp v193, v119 row_ror:1 row_mask:0xf bank_mask:0xf
	s_nop 1
	v_mov_b32_dpp v194, v112 row_ror:15 row_mask:0xf bank_mask:0xf
	v_mov_b32_dpp v195, v113 row_ror:15 row_mask:0xf bank_mask:0xf
	v_mov_b32_dpp v196, v114 row_ror:15 row_mask:0xf bank_mask:0xf
	v_mov_b32_dpp v197, v115 row_ror:15 row_mask:0xf bank_mask:0xf
	v_cmp_eq_u32_e64 s[58:59], 0, v120
	v_cndmask_b32_e64 v117, v193, 0, s[56:57]
	v_cndmask_b32_e64 v116, v161, 0, s[56:57]
	v_cndmask_b32_e64 v119, v123, 0, s[56:57]
	v_cndmask_b32_e64 v118, v122, 0, s[56:57]
	v_pk_mul_f32 v[118:119], v[146:147], v[118:119]
	v_pk_mul_f32 v[116:117], v[148:149], v[116:117]
	v_pk_fma_f32 v[112:113], v[112:113], v[138:139], v[118:119]
	v_pk_fma_f32 v[114:115], v[114:115], v[140:141], v[116:117]
	s_waitcnt lgkmcnt(0)
; #define LAS __attribute__((address_space(3)))
;     DI void operator()(const f32x4 (&acc)[2][2][4][2], const Unit& u, int wr, int wc, int fr_in, int fq_in) const {
;     ...
;                 f32x4 ga[4];
; #pragma unroll
;                 for (int bj = 0; bj < 2; ++bj) {
;                     const LAS float* wp = wlb + 128 * bj + qpos + 4 * n;
;                     const f32x4 w0 = *(const LAS f32x4*)(wp), w1 = *(const LAS f32x4*)(wp + 256), w2 = *(const LAS f32x4*)(wp + 512), bb = *(const LAS f32x4*)(wp + 768);
;                     const f32x4 eprev = *(const LAS f32x4*)(exb + (((blk + 3) & 3) * 2 + 1) * 256 + 128 * bj + qpos + 4 * n);
;                     const f32x4 enext = *(const LAS f32x4*)(exb + (((blk + 1) & 3) * 2 + 0) * 256 + 128 * bj + qpos + 4 * n);
; #pragma unroll
;                     for (int m = 0; m < 4; ++m) {
;                         const int g = 254 * u.pm - 1 + tr0 + 16 * m;
;                         const int lmask = (g < NLAT) ? (T - 1) : (CL - 1);
;                         const bool hp = (g & lmask) != 0, hn = ((g + 1) & lmask) != 0;
;                         f32x4 sp = acc[ai][bj][m][n], sn = acc[ai][bj][m][n];
;                         if (m > 0 && fr == 15) sp = acc[ai][bj][m > 0 ? m - 1 : 0][n];
;                         if (m < 3 && fr == 0) sn = acc[ai][bj][m < 3 ? m + 1 : 3][n];
;                         f32x4 pv, nv;
;                         dpp_rot4<0>(pv, sp); dpp_rot4<1>(nv, sn);
;                         if (m == 0 && fr == 0) pv = eprev;
;                         if (m == 3 && fr == 15) nv = enext;
;                         if (!hp) pv = (f32x4){0.f, 0.f, 0.f, 0.f};
;                         if (!hn) nv = (f32x4){0.f, 0.f, 0.f, 0.f};
;                         const f32x4 uu = pv * w0 + acc[ai][bj][m][n] * w1 + nv * w2 + bb;
;                         if (bj == 0) { ga[m][0] = gelu_tanh(uu[0]); ga[m][1] = gelu_tanh(uu[1]); ga[m][2] = gelu_tanh(uu[2]); ga[m][3] = gelu_tanh(uu[3]); }
;                         else ga[m] = ga[m] * uu;
	v_cndmask_b32_e64 v118, v194, v142, s[42:43]
	v_cndmask_b32_e64 v119, v195, v143, s[42:43]
	v_cndmask_b32_e64 v116, v196, v144, s[42:43]
	v_cndmask_b32_e64 v117, v197, v145, s[42:43]
	v_cndmask_b32_e64 v117, v117, 0, s[58:59]
	v_cndmask_b32_e64 v116, v116, 0, s[58:59]
	v_cndmask_b32_e64 v119, v119, 0, s[58:59]
	v_cndmask_b32_e64 v118, v118, 0, s[58:59]
	v_pk_fma_f32 v[112:113], v[134:135], v[118:119], v[112:113]
	v_pk_fma_f32 v[114:115], v[136:137], v[116:117], v[114:115]
	v_pk_add_f32 v[112:113], v[130:131], v[112:113]
	v_pk_add_f32 v[114:115], v[132:133], v[114:115]
	v_mul_f32_e32 v116, v112, v112
	v_mul_f32_e32 v117, v113, v113
	v_mul_f32_e32 v118, v114, v114
	v_mul_f32_e32 v119, v115, v115
	v_fmamk_f32 v116, v116, 0xbdd2d3e7, v198
	v_fmamk_f32 v117, v117, 0xbdd2d3e7, v198
	v_fmamk_f32 v118, v118, 0xbdd2d3e7, v198
	v_fmamk_f32 v119, v119, 0xbdd2d3e7, v198
	v_mul_f32_e32 v116, v112, v116
	v_mul_f32_e32 v117, v113, v117
	v_mul_f32_e32 v118, v114, v118
	v_mul_f32_e32 v119, v115, v119
	v_exp_f32_e32 v116, v116
	v_exp_f32_e32 v117, v117
	v_exp_f32_e32 v118, v118
	v_exp_f32_e32 v119, v119
	v_add_f32_e32 v116, 1.0, v116
	v_add_f32_e32 v117, 1.0, v117
	v_add_f32_e32 v118, 1.0, v118
	v_add_f32_e32 v119, 1.0, v119
	v_rcp_f32_e32 v116, v116
	v_rcp_f32_e32 v117, v117
	v_rcp_f32_e32 v118, v118
	v_rcp_f32_e32 v119, v119
	v_mul_f32_e32 v146, v112, v116
	v_mul_f32_e32 v147, v113, v117
	v_mul_f32_e32 v148, v114, v118
	v_mul_f32_e32 v149, v115, v119
	ds_read_b128 v[112:115], v179 offset:512
	ds_read_b128 v[130:133], v179 offset:1536
	ds_read_b128 v[134:137], v179 offset:2560
	ds_read_b128 v[138:141], v179 offset:3584
	ds_read_b128 v[116:119], v191 offset:1536
	ds_read_b128 v[142:145], v192 offset:512
	v_cndmask_b32_e32 v120, v104, v108, vcc
	v_cndmask_b32_e32 v121, v105, v109, vcc
	v_cndmask_b32_e32 v122, v106, v110, vcc
	v_cndmask_b32_e32 v123, v107, v111, vcc
	s_nop 1
	v_mov_b32_dpp v161, v104 row_ror:1 row_mask:0xf bank_mask:0xf
	v_mov_b32_dpp v193, v105 row_ror:1 row_mask:0xf bank_mask:0xf
	v_mov_b32_dpp v194, v106 row_ror:1 row_mask:0xf bank_mask:0xf
	v_mov_b32_dpp v195, v107 row_ror:1 row_mask:0xf bank_mask:0xf
	s_nop 1
	v_mov_b32_dpp v196, v120 row_ror:15 row_mask:0xf bank_mask:0xf
	v_mov_b32_dpp v197, v121 row_ror:15 row_mask:0xf bank_mask:0xf
	v_mov_b32_dpp v200, v122 row_ror:15 row_mask:0xf bank_mask:0xf
	v_mov_b32_dpp v201, v123 row_ror:15 row_mask:0xf bank_mask:0xf
	s_movk_i32 s0, 0xfe
	s_waitcnt lgkmcnt(1)
	v_cndmask_b32_e32 v120, v161, v116, vcc
	v_cndmask_b32_e32 v121, v193, v117, vcc
	v_cndmask_b32_e32 v116, v194, v118, vcc
	v_cndmask_b32_e32 v117, v195, v119, vcc
	v_cndmask_b32_e64 v117, v117, 0, s[44:45]
	v_cndmask_b32_e64 v116, v116, 0, s[44:45]
	v_cndmask_b32_e64 v119, v121, 0, s[44:45]
	v_cndmask_b32_e64 v118, v120, 0, s[44:45]
	v_pk_mul_f32 v[118:119], v[112:113], v[118:119]
	v_pk_mul_f32 v[116:117], v[114:115], v[116:117]
	v_pk_fma_f32 v[118:119], v[104:105], v[130:131], v[118:119]
	v_pk_fma_f32 v[116:117], v[106:107], v[132:133], v[116:117]
	v_cndmask_b32_e64 v121, v201, 0, s[46:47]
	v_cndmask_b32_e64 v120, v200, 0, s[46:47]
	v_cndmask_b32_e64 v123, v197, 0, s[46:47]
	v_cndmask_b32_e64 v122, v196, 0, s[46:47]
	v_pk_fma_f32 v[118:119], v[134:135], v[122:123], v[118:119]
	v_pk_fma_f32 v[116:117], v[136:137], v[120:121], v[116:117]
	v_cndmask_b32_e64 v104, v108, v104, s[42:43]
	v_pk_add_f32 v[120:121], v[140:141], v[116:117]
	v_pk_add_f32 v[116:117], v[138:139], v[118:119]
	v_cndmask_b32_e64 v105, v109, v105, s[42:43]
	v_cndmask_b32_e64 v106, v110, v106, s[42:43]
	v_cndmask_b32_e64 v107, v111, v107, s[42:43]
	v_pk_mul_f32 v[116:117], v[164:165], v[116:117]
	v_pk_mul_f32 v[118:119], v[162:163], v[120:121]
	s_nop 1
	v_mov_b32_dpp v161, v104 row_ror:1 row_mask:0xf bank_mask:0xf
	v_mov_b32_dpp v162, v105 row_ror:1 row_mask:0xf bank_mask:0xf
	v_mov_b32_dpp v163, v106 row_ror:1 row_mask:0xf bank_mask:0xf
	v_mov_b32_dpp v164, v107 row_ror:1 row_mask:0xf bank_mask:0xf
	v_cndmask_b32_e32 v120, v108, v100, vcc
	v_cndmask_b32_e64 v105, v164, 0, s[48:49]
	v_cndmask_b32_e64 v104, v163, 0, s[48:49]
	v_cndmask_b32_e64 v107, v162, 0, s[48:49]
	v_cndmask_b32_e64 v106, v161, 0, s[48:49]
	v_cndmask_b32_e32 v121, v109, v101, vcc
	v_cndmask_b32_e32 v122, v110, v102, vcc
	v_cndmask_b32_e32 v123, v111, v103, vcc
	v_pk_mul_f32 v[106:107], v[112:113], v[106:107]
	v_pk_mul_f32 v[104:105], v[114:115], v[104:105]
	s_nop 1
	v_mov_b32_dpp v165, v120 row_ror:15 row_mask:0xf bank_mask:0xf
	v_mov_b32_dpp v193, v121 row_ror:15 row_mask:0xf bank_mask:0xf
	v_mov_b32_dpp v194, v122 row_ror:15 row_mask:0xf bank_mask:0xf
	v_mov_b32_dpp v195, v123 row_ror:15 row_mask:0xf bank_mask:0xf
	v_pk_fma_f32 v[106:107], v[108:109], v[130:131], v[106:107]
	v_pk_fma_f32 v[104:105], v[110:111], v[132:133], v[104:105]
	v_cndmask_b32_e64 v121, v195, 0, s[50:51]
	v_cndmask_b32_e64 v120, v194, 0, s[50:51]
	v_cndmask_b32_e64 v123, v193, 0, s[50:51]
	v_cndmask_b32_e64 v122, v165, 0, s[50:51]
	v_pk_fma_f32 v[106:107], v[134:135], v[122:123], v[106:107]
	v_pk_fma_f32 v[104:105], v[136:137], v[120:121], v[104:105]
	v_pk_add_f32 v[106:107], v[138:139], v[106:107]
	v_pk_add_f32 v[104:105], v[140:141], v[104:105]
	v_pk_mul_f32 v[120:121], v[126:127], v[106:107]
	v_pk_mul_f32 v[122:123], v[124:125], v[104:105]
	v_cndmask_b32_e64 v104, v100, v108, s[42:43]
	v_cndmask_b32_e64 v105, v101, v109, s[42:43]
	v_cndmask_b32_e64 v106, v102, v110, s[42:43]
	v_cndmask_b32_e64 v107, v103, v111, s[42:43]
	s_nop 1
	v_mov_b32_dpp v124, v104 row_ror:1 row_mask:0xf bank_mask:0xf
	v_mov_b32_dpp v125, v105 row_ror:1 row_mask:0xf bank_mask:0xf
	v_mov_b32_dpp v126, v106 row_ror:1 row_mask:0xf bank_mask:0xf
; #define LAS __attribute__((address_space(3)))
;     DI void operator()(const f32x4 (&acc)[2][2][4][2], const Unit& u, int wr, int wc, int fr_in, int fq_in) const {
;     ...
;                 f32x4 ga[4];
; #pragma unroll
;                 for (int bj = 0; bj < 2; ++bj) {
;                     const LAS float* wp = wlb + 128 * bj + qpos + 4 * n;
;                     const f32x4 w0 = *(const LAS f32x4*)(wp), w1 = *(const LAS f32x4*)(wp + 256), w2 = *(const LAS f32x4*)(wp + 512), bb = *(const LAS f32x4*)(wp + 768);
;                     const f32x4 eprev = *(const LAS f32x4*)(exb + (((blk + 3) & 3) * 2 + 1) * 256 + 128 * bj + qpos + 4 * n);
;                     const f32x4 enext = *(const LAS f32x4*)(exb + (((blk + 1) & 3) * 2 + 0) * 256 + 128 * bj + qpos + 4 * n);
; #pragma unroll
;                     for (int m = 0; m < 4; ++m) {
;                         const int g = 254 * u.pm - 1 + tr0 + 16 * m;
;                         const int lmask = (g < NLAT) ? (T - 1) : (CL - 1);
;                         const bool hp = (g & lmask) != 0, hn = ((g + 1) & lmask) != 0;
;                         f32x4 sp = acc[ai][bj][m][n], sn = acc[ai][bj][m][n];
;                         if (m > 0 && fr == 15) sp = acc[ai][bj][m > 0 ? m - 1 : 0][n];
;                         if (m < 3 && fr == 0) sn = acc[ai][bj][m < 3 ? m + 1 : 3][n];
;                         f32x4 pv, nv;
;                         dpp_rot4<0>(pv, sp); dpp_rot4<1>(nv, sn);
;                         if (m == 0 && fr == 0) pv = eprev;
;                         if (m == 3 && fr == 15) nv = enext;
;                         if (!hp) pv = (f32x4){0.f, 0.f, 0.f, 0.f};
;                         if (!hn) nv = (f32x4){0.f, 0.f, 0.f, 0.f};
;                         const f32x4 uu = pv * w0 + acc[ai][bj][m][n] * w1 + nv * w2 + bb;
;                         if (bj == 0) { ga[m][0] = gelu_tanh(uu[0]); ga[m][1] = gelu_tanh(uu[1]); ga[m][2] = gelu_tanh(uu[2]); ga[m][3] = gelu_tanh(uu[3]); }
;                         else ga[m] = ga[m] * uu;
	v_mov_b32_dpp v127, v107 row_ror:1 row_mask:0xf bank_mask:0xf
	v_cndmask_b32_e32 v108, v100, v96, vcc
	v_cndmask_b32_e64 v105, v127, 0, s[52:53]
	v_cndmask_b32_e64 v104, v126, 0, s[52:53]
	v_cndmask_b32_e64 v107, v125, 0, s[52:53]
	v_cndmask_b32_e64 v106, v124, 0, s[52:53]
	v_cndmask_b32_e32 v109, v101, v97, vcc
	v_cndmask_b32_e32 v110, v102, v98, vcc
	v_cndmask_b32_e32 v111, v103, v99, vcc
	v_pk_mul_f32 v[106:107], v[112:113], v[106:107]
	v_pk_mul_f32 v[104:105], v[114:115], v[104:105]
	s_nop 1
	v_mov_b32_dpp v161, v108 row_ror:15 row_mask:0xf bank_mask:0xf
	v_mov_b32_dpp v162, v109 row_ror:15 row_mask:0xf bank_mask:0xf
	v_mov_b32_dpp v163, v110 row_ror:15 row_mask:0xf bank_mask:0xf
	v_mov_b32_dpp v164, v111 row_ror:15 row_mask:0xf bank_mask:0xf
	v_pk_fma_f32 v[106:107], v[100:101], v[130:131], v[106:107]
	v_pk_fma_f32 v[104:105], v[102:103], v[132:133], v[104:105]
	v_cndmask_b32_e64 v109, v164, 0, s[54:55]
	v_cndmask_b32_e64 v108, v163, 0, s[54:55]
	v_cndmask_b32_e64 v111, v162, 0, s[54:55]
	v_cndmask_b32_e64 v110, v161, 0, s[54:55]
	v_pk_fma_f32 v[106:107], v[134:135], v[110:111], v[106:107]
	v_pk_fma_f32 v[104:105], v[136:137], v[108:109], v[104:105]
	v_pk_add_f32 v[106:107], v[138:139], v[106:107]
	v_pk_add_f32 v[104:105], v[140:141], v[104:105]
	v_cndmask_b32_e64 v100, v96, v100, s[42:43]
	v_cndmask_b32_e64 v101, v97, v101, s[42:43]
	v_cndmask_b32_e64 v102, v98, v102, s[42:43]
	v_cndmask_b32_e64 v103, v99, v103, s[42:43]
	v_pk_mul_f32 v[124:125], v[168:169], v[106:107]
	v_pk_mul_f32 v[126:127], v[166:167], v[104:105]
	s_nop 1
	v_mov_b32_dpp v104, v100 row_ror:1 row_mask:0xf bank_mask:0xf
	v_mov_b32_dpp v105, v101 row_ror:1 row_mask:0xf bank_mask:0xf
	v_mov_b32_dpp v106, v102 row_ror:1 row_mask:0xf bank_mask:0xf
	v_mov_b32_dpp v107, v103 row_ror:1 row_mask:0xf bank_mask:0xf
	s_nop 1
	v_mov_b32_dpp v108, v96 row_ror:15 row_mask:0xf bank_mask:0xf
	v_mov_b32_dpp v109, v97 row_ror:15 row_mask:0xf bank_mask:0xf
	v_mov_b32_dpp v110, v98 row_ror:15 row_mask:0xf bank_mask:0xf
	v_mov_b32_dpp v111, v99 row_ror:15 row_mask:0xf bank_mask:0xf
	v_cmp_gt_u32_e64 s[0:1], s0, v184
	v_cndmask_b32_e64 v101, v105, 0, s[56:57]
	v_cndmask_b32_e64 v100, v104, 0, s[56:57]
	v_cndmask_b32_e64 v103, v107, 0, s[56:57]
	v_cndmask_b32_e64 v102, v106, 0, s[56:57]
	v_pk_mul_f32 v[102:103], v[114:115], v[102:103]
	v_pk_mul_f32 v[100:101], v[112:113], v[100:101]
	v_pk_fma_f32 v[98:99], v[98:99], v[132:133], v[102:103]
	v_pk_fma_f32 v[96:97], v[96:97], v[130:131], v[100:101]
	s_waitcnt lgkmcnt(0)
	v_cndmask_b32_e64 v102, v110, v144, s[42:43]
	v_cndmask_b32_e64 v103, v111, v145, s[42:43]
	v_cndmask_b32_e64 v100, v108, v142, s[42:43]
	v_cndmask_b32_e64 v101, v109, v143, s[42:43]
	v_cndmask_b32_e64 v101, v101, 0, s[58:59]
	v_cndmask_b32_e64 v100, v100, 0, s[58:59]
	v_cndmask_b32_e64 v103, v103, 0, s[58:59]
	v_cndmask_b32_e64 v102, v102, 0, s[58:59]
	v_pk_fma_f32 v[98:99], v[136:137], v[102:103], v[98:99]
	v_pk_fma_f32 v[96:97], v[134:135], v[100:101], v[96:97]
	v_pk_add_f32 v[98:99], v[140:141], v[98:99]
	v_pk_add_f32 v[96:97], v[138:139], v[96:97]
	v_pk_mul_f32 v[130:131], v[148:149], v[98:99]
	v_pk_mul_f32 v[132:133], v[146:147], v[96:97]
	s_nop 1
	v_mov_b32_dpp v142, v88 row_ror:1 row_mask:0xf bank_mask:0xf
	v_mov_b32_dpp v143, v89 row_ror:1 row_mask:0xf bank_mask:0xf
	v_mov_b32_dpp v144, v90 row_ror:1 row_mask:0xf bank_mask:0xf
	v_mov_b32_dpp v145, v91 row_ror:1 row_mask:0xf bank_mask:0xf
	v_cndmask_b32_e32 v138, v88, v92, vcc
	ds_read_b128 v[112:115], v179 offset:16
	ds_read_b128 v[104:107], v179 offset:1040
	ds_read_b128 v[100:103], v179 offset:2064
	ds_read_b128 v[96:99], v179 offset:3088
	ds_read_b128 v[134:137], v191 offset:1040
	ds_read_b128 v[108:111], v192 offset:16
	v_cndmask_b32_e32 v139, v89, v93, vcc
	v_cndmask_b32_e32 v140, v90, v94, vcc
	v_cndmask_b32_e32 v141, v91, v95, vcc
	s_waitcnt lgkmcnt(1)
	v_cndmask_b32_e32 v136, v144, v136, vcc
	v_cndmask_b32_e32 v137, v145, v137, vcc
	v_cndmask_b32_e32 v134, v142, v134, vcc
	v_cndmask_b32_e32 v135, v143, v135, vcc
	v_cndmask_b32_e64 v135, v135, 0, s[44:45]
	v_cndmask_b32_e64 v134, v134, 0, s[44:45]
	v_cndmask_b32_e64 v137, v137, 0, s[44:45]
	v_cndmask_b32_e64 v136, v136, 0, s[44:45]
	v_pk_mul_f32 v[136:137], v[114:115], v[136:137]
	v_pk_mul_f32 v[134:135], v[112:113], v[134:135]
	s_nop 1
	v_mov_b32_dpp v146, v138 row_ror:15 row_mask:0xf bank_mask:0xf
	v_mov_b32_dpp v147, v139 row_ror:15 row_mask:0xf bank_mask:0xf
	v_mov_b32_dpp v148, v140 row_ror:15 row_mask:0xf bank_mask:0xf
	v_mov_b32_dpp v149, v141 row_ror:15 row_mask:0xf bank_mask:0xf
	v_pk_fma_f32 v[136:137], v[90:91], v[106:107], v[136:137]
	v_pk_fma_f32 v[134:135], v[88:89], v[104:105], v[134:135]
	v_cndmask_b32_e64 v139, v147, 0, s[46:47]
	v_cndmask_b32_e64 v138, v146, 0, s[46:47]
	v_cndmask_b32_e64 v141, v149, 0, s[46:47]
	v_cndmask_b32_e64 v140, v148, 0, s[46:47]
	v_pk_fma_f32 v[136:137], v[102:103], v[140:141], v[136:137]
	v_pk_fma_f32 v[134:135], v[100:101], v[138:139], v[134:135]
	v_cndmask_b32_e64 v88, v92, v88, s[42:43]
	v_pk_add_f32 v[138:139], v[96:97], v[134:135]
	v_pk_add_f32 v[134:135], v[98:99], v[136:137]
	v_mul_f32_e32 v137, v138, v138
	v_mul_f32_e32 v136, v135, v135
	v_mul_f32_e32 v140, v139, v139
	v_mul_f32_e32 v141, v134, v134
	v_fmamk_f32 v136, v136, 0xbdd2d3e7, v198
	v_fmamk_f32 v137, v137, 0xbdd2d3e7, v198
	v_fmamk_f32 v140, v140, 0xbdd2d3e7, v198
	v_fmamk_f32 v141, v141, 0xbdd2d3e7, v198
	v_mul_f32_e32 v136, v135, v136
	v_mul_f32_e32 v137, v138, v137
	v_mul_f32_e32 v140, v139, v140
	v_mul_f32_e32 v141, v134, v141
	v_exp_f32_e32 v136, v136
	v_exp_f32_e32 v137, v137
	v_exp_f32_e32 v140, v140
	v_exp_f32_e32 v141, v141
; #define LAS __attribute__((address_space(3)))
;     DI void operator()(const f32x4 (&acc)[2][2][4][2], const Unit& u, int wr, int wc, int fr_in, int fq_in) const {
;     ...
;                     const LAS float* wp = wlb + 128 * bj + qpos + 4 * n;
;                     const f32x4 w0 = *(const LAS f32x4*)(wp), w1 = *(const LAS f32x4*)(wp + 256), w2 = *(const LAS f32x4*)(wp + 512), bb = *(const LAS f32x4*)(wp + 768);
;                     const f32x4 eprev = *(const LAS f32x4*)(exb + (((blk + 3) & 3) * 2 + 1) * 256 + 128 * bj + qpos + 4 * n);
;                     const f32x4 enext = *(const LAS f32x4*)(exb + (((blk + 1) & 3) * 2 + 0) * 256 + 128 * bj + qpos + 4 * n);
; #pragma unroll
;                     for (int m = 0; m < 4; ++m) {
;                         const int g = 254 * u.pm - 1 + tr0 + 16 * m;
;                         const int lmask = (g < NLAT) ? (T - 1) : (CL - 1);
;                         const bool hp = (g & lmask) != 0, hn = ((g + 1) & lmask) != 0;
;                         f32x4 sp = acc[ai][bj][m][n], sn = acc[ai][bj][m][n];
;                         if (m > 0 && fr == 15) sp = acc[ai][bj][m > 0 ? m - 1 : 0][n];
;                         if (m < 3 && fr == 0) sn = acc[ai][bj][m < 3 ? m + 1 : 3][n];
;                         f32x4 pv, nv;
;                         dpp_rot4<0>(pv, sp); dpp_rot4<1>(nv, sn);
;                         if (m == 0 && fr == 0) pv = eprev;
;                         if (m == 3 && fr == 15) nv = enext;
;                         if (!hp) pv = (f32x4){0.f, 0.f, 0.f, 0.f};
;                         if (!hn) nv = (f32x4){0.f, 0.f, 0.f, 0.f};
;                         const f32x4 uu = pv * w0 + acc[ai][bj][m][n] * w1 + nv * w2 + bb;
;                         if (bj == 0) { ga[m][0] = gelu_tanh(uu[0]); ga[m][1] = gelu_tanh(uu[1]); ga[m][2] = gelu_tanh(uu[2]); ga[m][3] = gelu_tanh(uu[3]); }
;                         else ga[m] = ga[m] * uu;
	v_add_f32_e32 v136, 1.0, v136
	v_add_f32_e32 v137, 1.0, v137
	v_add_f32_e32 v140, 1.0, v140
	v_add_f32_e32 v141, 1.0, v141
	v_rcp_f32_e32 v136, v136
	v_rcp_f32_e32 v137, v137
	v_rcp_f32_e32 v140, v140
	v_rcp_f32_e32 v141, v141
	v_cndmask_b32_e64 v89, v93, v89, s[42:43]
	v_cndmask_b32_e64 v90, v94, v90, s[42:43]
	v_cndmask_b32_e64 v91, v95, v91, s[42:43]
	s_nop 1
	v_mov_b32_dpp v142, v88 row_ror:1 row_mask:0xf bank_mask:0xf
	v_mov_b32_dpp v143, v89 row_ror:1 row_mask:0xf bank_mask:0xf
	v_mov_b32_dpp v144, v90 row_ror:1 row_mask:0xf bank_mask:0xf
	v_mov_b32_dpp v145, v91 row_ror:1 row_mask:0xf bank_mask:0xf
	v_mul_f32_e32 v135, v135, v136
	v_cndmask_b32_e64 v89, v143, 0, s[48:49]
	v_cndmask_b32_e64 v88, v142, 0, s[48:49]
	v_cndmask_b32_e64 v91, v145, 0, s[48:49]
	v_cndmask_b32_e64 v90, v144, 0, s[48:49]
	v_mul_f32_e32 v136, v138, v137
	v_mul_f32_e32 v137, v139, v140
	v_mul_f32_e32 v134, v134, v141
	v_cndmask_b32_e32 v138, v92, v84, vcc
	v_cndmask_b32_e32 v139, v93, v85, vcc
	v_cndmask_b32_e32 v140, v94, v86, vcc
	v_cndmask_b32_e32 v141, v95, v87, vcc
	v_pk_mul_f32 v[90:91], v[114:115], v[90:91]
	v_pk_mul_f32 v[88:89], v[112:113], v[88:89]
	s_nop 1
	v_mov_b32_dpp v146, v138 row_ror:15 row_mask:0xf bank_mask:0xf
	v_mov_b32_dpp v147, v139 row_ror:15 row_mask:0xf bank_mask:0xf
	v_mov_b32_dpp v148, v140 row_ror:15 row_mask:0xf bank_mask:0xf
	v_mov_b32_dpp v149, v141 row_ror:15 row_mask:0xf bank_mask:0xf
	v_pk_fma_f32 v[90:91], v[94:95], v[106:107], v[90:91]
	v_pk_fma_f32 v[88:89], v[92:93], v[104:105], v[88:89]
	v_cndmask_b32_e64 v139, v147, 0, s[50:51]
	v_cndmask_b32_e64 v138, v146, 0, s[50:51]
	v_cndmask_b32_e64 v141, v149, 0, s[50:51]
	v_cndmask_b32_e64 v140, v148, 0, s[50:51]
	v_pk_fma_f32 v[90:91], v[102:103], v[140:141], v[90:91]
	v_pk_fma_f32 v[88:89], v[100:101], v[138:139], v[88:89]
	v_cndmask_b32_e64 v92, v84, v92, s[42:43]
	v_pk_add_f32 v[138:139], v[96:97], v[88:89]
	v_pk_add_f32 v[88:89], v[98:99], v[90:91]
	v_mul_f32_e32 v91, v138, v138
	v_mul_f32_e32 v90, v89, v89
	v_mul_f32_e32 v140, v139, v139
	v_fmamk_f32 v90, v90, 0xbdd2d3e7, v198
	v_fmamk_f32 v91, v91, 0xbdd2d3e7, v198
	v_fmamk_f32 v140, v140, 0xbdd2d3e7, v198
	v_mul_f32_e32 v141, v88, v88
	v_mul_f32_e32 v90, v89, v90
	v_mul_f32_e32 v91, v138, v91
	v_mul_f32_e32 v140, v139, v140
	v_fmamk_f32 v141, v141, 0xbdd2d3e7, v198
	v_exp_f32_e32 v90, v90
	v_exp_f32_e32 v91, v91
	v_exp_f32_e32 v140, v140
	v_mul_f32_e32 v141, v88, v141
	v_exp_f32_e32 v141, v141
	v_add_f32_e32 v90, 1.0, v90
	v_add_f32_e32 v91, 1.0, v91
	v_add_f32_e32 v140, 1.0, v140
	v_rcp_f32_e32 v90, v90
	v_rcp_f32_e32 v91, v91
	v_rcp_f32_e32 v140, v140
	v_add_f32_e32 v141, 1.0, v141
	v_rcp_f32_e32 v141, v141
	v_cndmask_b32_e64 v93, v85, v93, s[42:43]
	v_cndmask_b32_e64 v94, v86, v94, s[42:43]
	v_cndmask_b32_e64 v95, v87, v95, s[42:43]
	s_nop 1
	v_mov_b32_dpp v142, v92 row_ror:1 row_mask:0xf bank_mask:0xf
	v_mov_b32_dpp v143, v93 row_ror:1 row_mask:0xf bank_mask:0xf
	v_mov_b32_dpp v144, v94 row_ror:1 row_mask:0xf bank_mask:0xf
	v_mov_b32_dpp v145, v95 row_ror:1 row_mask:0xf bank_mask:0xf
	v_mul_f32_e32 v89, v89, v90
	v_cndmask_b32_e64 v93, v143, 0, s[52:53]
	v_cndmask_b32_e64 v92, v142, 0, s[52:53]
	v_mul_f32_e32 v90, v138, v91
	v_mul_f32_e32 v91, v139, v140
	v_cndmask_b32_e32 v138, v84, v80, vcc
	v_cndmask_b32_e32 v139, v85, v81, vcc
	v_pk_mul_f32 v[92:93], v[112:113], v[92:93]
	v_mul_f32_e32 v88, v88, v141
	v_cndmask_b32_e32 v140, v86, v82, vcc
	v_cndmask_b32_e32 v141, v87, v83, vcc
	s_nop 1
	v_mov_b32_dpp v146, v138 row_ror:15 row_mask:0xf bank_mask:0xf
	v_mov_b32_dpp v147, v139 row_ror:15 row_mask:0xf bank_mask:0xf
	v_mov_b32_dpp v148, v140 row_ror:15 row_mask:0xf bank_mask:0xf
	v_mov_b32_dpp v149, v141 row_ror:15 row_mask:0xf bank_mask:0xf
	v_cndmask_b32_e64 v95, v145, 0, s[52:53]
	v_cndmask_b32_e64 v94, v144, 0, s[52:53]
	v_pk_fma_f32 v[92:93], v[84:85], v[104:105], v[92:93]
	v_cndmask_b32_e64 v139, v147, 0, s[54:55]
	v_cndmask_b32_e64 v138, v146, 0, s[54:55]
	v_pk_mul_f32 v[94:95], v[114:115], v[94:95]
	v_pk_fma_f32 v[92:93], v[100:101], v[138:139], v[92:93]
	v_pk_fma_f32 v[94:95], v[86:87], v[106:107], v[94:95]
	v_cndmask_b32_e64 v141, v149, 0, s[54:55]
	v_cndmask_b32_e64 v140, v148, 0, s[54:55]
	v_pk_add_f32 v[92:93], v[96:97], v[92:93]
	v_pk_fma_f32 v[94:95], v[102:103], v[140:141], v[94:95]
	v_mul_f32_e32 v139, v92, v92
	v_pk_add_f32 v[94:95], v[98:99], v[94:95]
	v_fmamk_f32 v139, v139, 0xbdd2d3e7, v198
	v_mul_f32_e32 v140, v93, v93
	v_mul_f32_e32 v138, v95, v95
	v_mul_f32_e32 v139, v92, v139
	v_fmamk_f32 v140, v140, 0xbdd2d3e7, v198
	v_mul_f32_e32 v141, v94, v94
	v_fmamk_f32 v138, v138, 0xbdd2d3e7, v198
	v_exp_f32_e32 v139, v139
	v_mul_f32_e32 v140, v93, v140
	v_fmamk_f32 v141, v141, 0xbdd2d3e7, v198
	v_mul_f32_e32 v138, v95, v138
	v_exp_f32_e32 v140, v140
	v_mul_f32_e32 v141, v94, v141
	v_exp_f32_e32 v138, v138
	v_exp_f32_e32 v141, v141
	v_add_f32_e32 v139, 1.0, v139
	v_rcp_f32_e32 v142, v139
	v_add_f32_e32 v139, 1.0, v140
	v_add_f32_e32 v138, 1.0, v138
	v_rcp_f32_e32 v143, v139
	v_add_f32_e32 v139, 1.0, v141
	v_rcp_f32_e32 v138, v138
	v_rcp_f32_e32 v144, v139
	v_cndmask_b32_e64 v84, v80, v84, s[42:43]
	v_cndmask_b32_e64 v85, v81, v85, s[42:43]
	v_cndmask_b32_e64 v86, v82, v86, s[42:43]
	v_cndmask_b32_e64 v87, v83, v87, s[42:43]
	v_mul_f32_e32 v139, v95, v138
	v_mul_f32_e32 v140, v92, v142
	v_mul_f32_e32 v141, v93, v143
	v_mul_f32_e32 v138, v94, v144
	s_nop 1
	v_mov_b32_dpp v92, v84 row_ror:1 row_mask:0xf bank_mask:0xf
	v_mov_b32_dpp v93, v85 row_ror:1 row_mask:0xf bank_mask:0xf
	v_mov_b32_dpp v94, v86 row_ror:1 row_mask:0xf bank_mask:0xf
	v_mov_b32_dpp v95, v87 row_ror:1 row_mask:0xf bank_mask:0xf
	s_nop 1
	v_mov_b32_dpp v142, v80 row_ror:15 row_mask:0xf bank_mask:0xf
	v_mov_b32_dpp v143, v81 row_ror:15 row_mask:0xf bank_mask:0xf
	v_mov_b32_dpp v144, v82 row_ror:15 row_mask:0xf bank_mask:0xf
	v_mov_b32_dpp v145, v83 row_ror:15 row_mask:0xf bank_mask:0xf
	v_ashrrev_i32_e32 v161, 31, v160
	v_cndmask_b32_e64 v85, v93, 0, s[56:57]
	v_cndmask_b32_e64 v84, v92, 0, s[56:57]
	v_cndmask_b32_e64 v87, v95, 0, s[56:57]
	v_cndmask_b32_e64 v86, v94, 0, s[56:57]
	v_pk_mul_f32 v[86:87], v[114:115], v[86:87]
	v_pk_mul_f32 v[84:85], v[112:113], v[84:85]
	v_pk_fma_f32 v[82:83], v[82:83], v[106:107], v[86:87]
	v_pk_fma_f32 v[80:81], v[80:81], v[104:105], v[84:85]
	s_waitcnt lgkmcnt(0)
; #define LAS __attribute__((address_space(3)))
;     DI void operator()(const f32x4 (&acc)[2][2][4][2], const Unit& u, int wr, int wc, int fr_in, int fq_in) const {
;     ...
;                 f32x4 ga[4];
; #pragma unroll
;                 for (int bj = 0; bj < 2; ++bj) {
;                     const LAS float* wp = wlb + 128 * bj + qpos + 4 * n;
;                     const f32x4 w0 = *(const LAS f32x4*)(wp), w1 = *(const LAS f32x4*)(wp + 256), w2 = *(const LAS f32x4*)(wp + 512), bb = *(const LAS f32x4*)(wp + 768);
;                     const f32x4 eprev = *(const LAS f32x4*)(exb + (((blk + 3) & 3) * 2 + 1) * 256 + 128 * bj + qpos + 4 * n);
;                     const f32x4 enext = *(const LAS f32x4*)(exb + (((blk + 1) & 3) * 2 + 0) * 256 + 128 * bj + qpos + 4 * n);
; #pragma unroll
;                     for (int m = 0; m < 4; ++m) {
;                         const int g = 254 * u.pm - 1 + tr0 + 16 * m;
;                         const int lmask = (g < NLAT) ? (T - 1) : (CL - 1);
;                         const bool hp = (g & lmask) != 0, hn = ((g + 1) & lmask) != 0;
;                         f32x4 sp = acc[ai][bj][m][n], sn = acc[ai][bj][m][n];
;                         if (m > 0 && fr == 15) sp = acc[ai][bj][m > 0 ? m - 1 : 0][n];
;                         if (m < 3 && fr == 0) sn = acc[ai][bj][m < 3 ? m + 1 : 3][n];
;                         f32x4 pv, nv;
;                         dpp_rot4<0>(pv, sp); dpp_rot4<1>(nv, sn);
;                         if (m == 0 && fr == 0) pv = eprev;
;                         if (m == 3 && fr == 15) nv = enext;
;                         if (!hp) pv = (f32x4){0.f, 0.f, 0.f, 0.f};
;                         if (!hn) nv = (f32x4){0.f, 0.f, 0.f, 0.f};
;                         const f32x4 uu = pv * w0 + acc[ai][bj][m][n] * w1 + nv * w2 + bb;
;                         if (bj == 0) { ga[m][0] = gelu_tanh(uu[0]); ga[m][1] = gelu_tanh(uu[1]); ga[m][2] = gelu_tanh(uu[2]); ga[m][3] = gelu_tanh(uu[3]); }
;                         else ga[m] = ga[m] * uu;
	v_cndmask_b32_e64 v86, v144, v110, s[42:43]
	v_cndmask_b32_e64 v87, v145, v111, s[42:43]
	v_cndmask_b32_e64 v84, v142, v108, s[42:43]
	v_cndmask_b32_e64 v85, v143, v109, s[42:43]
	v_cndmask_b32_e64 v85, v85, 0, s[58:59]
	v_cndmask_b32_e64 v84, v84, 0, s[58:59]
	v_cndmask_b32_e64 v87, v87, 0, s[58:59]
	v_cndmask_b32_e64 v86, v86, 0, s[58:59]
	v_pk_fma_f32 v[82:83], v[102:103], v[86:87], v[82:83]
	v_pk_fma_f32 v[80:81], v[100:101], v[84:85], v[80:81]
	v_pk_add_f32 v[82:83], v[98:99], v[82:83]
	v_pk_add_f32 v[80:81], v[96:97], v[80:81]
	v_mul_f32_e32 v84, v83, v83
	v_mul_f32_e32 v85, v80, v80
	v_mul_f32_e32 v86, v81, v81
	v_mul_f32_e32 v87, v82, v82
	v_fmamk_f32 v84, v84, 0xbdd2d3e7, v198
	v_fmamk_f32 v85, v85, 0xbdd2d3e7, v198
	v_fmamk_f32 v86, v86, 0xbdd2d3e7, v198
	v_fmamk_f32 v87, v87, 0xbdd2d3e7, v198
	v_mul_f32_e32 v84, v83, v84
	v_mul_f32_e32 v85, v80, v85
	v_mul_f32_e32 v86, v81, v86
	v_mul_f32_e32 v87, v82, v87
	v_exp_f32_e32 v84, v84
	v_exp_f32_e32 v85, v85
	v_exp_f32_e32 v86, v86
	v_exp_f32_e32 v87, v87
	v_add_f32_e32 v84, 1.0, v84
	v_add_f32_e32 v85, 1.0, v85
	v_add_f32_e32 v86, 1.0, v86
	v_add_f32_e32 v87, 1.0, v87
	v_rcp_f32_e32 v84, v84
	v_rcp_f32_e32 v85, v85
	v_rcp_f32_e32 v86, v86
	v_rcp_f32_e32 v87, v87
	v_mul_f32_e32 v109, v83, v84
	v_mul_f32_e32 v110, v80, v85
	v_mul_f32_e32 v111, v81, v86
	v_mul_f32_e32 v108, v82, v87
	ds_read_b128 v[84:87], v179 offset:528
	ds_read_b128 v[92:95], v179 offset:1552
	ds_read_b128 v[96:99], v179 offset:2576
	ds_read_b128 v[100:103], v179 offset:3600
	ds_read_b128 v[80:83], v191 offset:1552
	ds_read_b128 v[104:107], v192 offset:528
	v_cndmask_b32_e32 v112, v72, v76, vcc
	v_cndmask_b32_e32 v113, v73, v77, vcc
	v_cndmask_b32_e32 v114, v74, v78, vcc
	v_cndmask_b32_e32 v115, v75, v79, vcc
	s_nop 1
	v_mov_b32_dpp v142, v72 row_ror:1 row_mask:0xf bank_mask:0xf
	v_mov_b32_dpp v143, v73 row_ror:1 row_mask:0xf bank_mask:0xf
	v_mov_b32_dpp v144, v74 row_ror:1 row_mask:0xf bank_mask:0xf
	v_mov_b32_dpp v145, v75 row_ror:1 row_mask:0xf bank_mask:0xf
	s_nop 1
	v_mov_b32_dpp v146, v112 row_ror:15 row_mask:0xf bank_mask:0xf
	v_mov_b32_dpp v147, v113 row_ror:15 row_mask:0xf bank_mask:0xf
	v_mov_b32_dpp v148, v114 row_ror:15 row_mask:0xf bank_mask:0xf
	v_mov_b32_dpp v149, v115 row_ror:15 row_mask:0xf bank_mask:0xf
	s_waitcnt lgkmcnt(1)
;     DI void operator()(const f32x4 (&acc)[2][2][4][2], const Unit& u, int wr, int wc, int fr_in, int fq_in) const {
;     ...
;                     const LAS float* wp = wlb + 128 * bj + qpos + 4 * n;
;                     const f32x4 w0 = *(const LAS f32x4*)(wp), w1 = *(const LAS f32x4*)(wp + 256), w2 = *(const LAS f32x4*)(wp + 512), bb = *(const LAS f32x4*)(wp + 768);
;                     const f32x4 eprev = *(const LAS f32x4*)(exb + (((blk + 3) & 3) * 2 + 1) * 256 + 128 * bj + qpos + 4 * n);
;                     const f32x4 enext = *(const LAS f32x4*)(exb + (((blk + 1) & 3) * 2 + 0) * 256 + 128 * bj + qpos + 4 * n);
; #pragma unroll
;                     for (int m = 0; m < 4; ++m) {
;                         const int g = 254 * u.pm - 1 + tr0 + 16 * m;
;                         const int lmask = (g < NLAT) ? (T - 1) : (CL - 1);
;                         const bool hp = (g & lmask) != 0, hn = ((g + 1) & lmask) != 0;
;                         f32x4 sp = acc[ai][bj][m][n], sn = acc[ai][bj][m][n];
;                         if (m > 0 && fr == 15) sp = acc[ai][bj][m > 0 ? m - 1 : 0][n];
;                         if (m < 3 && fr == 0) sn = acc[ai][bj][m < 3 ? m + 1 : 3][n];
;                         f32x4 pv, nv;
;                         dpp_rot4<0>(pv, sp); dpp_rot4<1>(nv, sn);
;                         if (m == 0 && fr == 0) pv = eprev;
;                         if (m == 3 && fr == 15) nv = enext;
;                         if (!hp) pv = (f32x4){0.f, 0.f, 0.f, 0.f};
;                         if (!hn) nv = (f32x4){0.f, 0.f, 0.f, 0.f};
;                         const f32x4 uu = pv * w0 + acc[ai][bj][m][n] * w1 + nv * w2 + bb;
;                         if (bj == 0) { ga[m][0] = gelu_tanh(uu[0]); ga[m][1] = gelu_tanh(uu[1]); ga[m][2] = gelu_tanh(uu[2]); ga[m][3] = gelu_tanh(uu[3]); }
;                         else ga[m] = ga[m] * uu;
;                         asm volatile("" : "+v"(ga[m][0]), "+v"(ga[m][1]), "+v"(ga[m][2]), "+v"(ga[m][3]));
;                     }
;                 }
; #pragma unroll
;                 for (int m = 0; m < 4; ++m) {
;                     const int tr = tr0 + 16 * m;
;                     const int g = 254 * u.pm - 1 + tr;
;                     u32x2 w; w.x = pack2(ga[m][0], ga[m][1]); w.y = pack2(ga[m][2], ga[m][3]);
;                     if (n == 0) pk0[m] = w;
;                     else if (tr >= 1 && tr <= 254 && g < nrows) {
	v_cndmask_b32_e32 v112, v142, v80, vcc
	v_cndmask_b32_e32 v113, v143, v81, vcc
	v_cndmask_b32_e32 v80, v144, v82, vcc
	v_cndmask_b32_e32 v81, v145, v83, vcc
	v_cndmask_b32_e64 v81, v81, 0, s[44:45]
	v_cndmask_b32_e64 v80, v80, 0, s[44:45]
	v_cndmask_b32_e64 v83, v113, 0, s[44:45]
	v_cndmask_b32_e64 v82, v112, 0, s[44:45]
	v_pk_mul_f32 v[82:83], v[84:85], v[82:83]
	v_pk_mul_f32 v[80:81], v[86:87], v[80:81]
	v_pk_fma_f32 v[82:83], v[72:73], v[92:93], v[82:83]
	v_pk_fma_f32 v[80:81], v[74:75], v[94:95], v[80:81]
	v_cndmask_b32_e64 v113, v149, 0, s[46:47]
	v_cndmask_b32_e64 v112, v148, 0, s[46:47]
	v_cndmask_b32_e64 v115, v147, 0, s[46:47]
	v_cndmask_b32_e64 v114, v146, 0, s[46:47]
	v_pk_fma_f32 v[82:83], v[96:97], v[114:115], v[82:83]
	v_pk_fma_f32 v[80:81], v[98:99], v[112:113], v[80:81]
	v_cndmask_b32_e64 v72, v76, v72, s[42:43]
	v_pk_add_f32 v[112:113], v[102:103], v[80:81]
	v_pk_add_f32 v[80:81], v[100:101], v[82:83]
	v_cndmask_b32_e64 v73, v77, v73, s[42:43]
	v_pk_mul_f32 v[80:81], v[136:137], v[80:81]
	v_pk_mul_f32 v[82:83], v[134:135], v[112:113]
	v_cndmask_b32_e64 v74, v78, v74, s[42:43]
	v_cndmask_b32_e64 v75, v79, v75, s[42:43]
	s_nop 1
	v_mov_b32_dpp v134, v72 row_ror:1 row_mask:0xf bank_mask:0xf
	v_mov_b32_dpp v135, v73 row_ror:1 row_mask:0xf bank_mask:0xf
	v_mov_b32_dpp v136, v74 row_ror:1 row_mask:0xf bank_mask:0xf
	v_mov_b32_dpp v137, v75 row_ror:1 row_mask:0xf bank_mask:0xf
	v_cndmask_b32_e32 v112, v76, v68, vcc
	v_cndmask_b32_e64 v73, v137, 0, s[48:49]
	v_cndmask_b32_e64 v72, v136, 0, s[48:49]
	v_cndmask_b32_e32 v113, v77, v69, vcc
	v_cndmask_b32_e64 v75, v135, 0, s[48:49]
	v_cndmask_b32_e64 v74, v134, 0, s[48:49]
	v_pk_mul_f32 v[72:73], v[86:87], v[72:73]
	v_cndmask_b32_e32 v114, v78, v70, vcc
	v_cndmask_b32_e32 v115, v79, v71, vcc
	s_nop 1
	v_mov_b32_dpp v142, v112 row_ror:15 row_mask:0xf bank_mask:0xf
	v_mov_b32_dpp v143, v113 row_ror:15 row_mask:0xf bank_mask:0xf
	v_mov_b32_dpp v144, v114 row_ror:15 row_mask:0xf bank_mask:0xf
	v_mov_b32_dpp v145, v115 row_ror:15 row_mask:0xf bank_mask:0xf
	v_pk_mul_f32 v[74:75], v[84:85], v[74:75]
	v_pk_fma_f32 v[72:73], v[78:79], v[94:95], v[72:73]
	v_cndmask_b32_e64 v113, v145, 0, s[50:51]
	v_cndmask_b32_e64 v112, v144, 0, s[50:51]
	v_pk_fma_f32 v[74:75], v[76:77], v[92:93], v[74:75]
	v_cndmask_b32_e64 v115, v143, 0, s[50:51]
	v_cndmask_b32_e64 v114, v142, 0, s[50:51]
	v_pk_fma_f32 v[72:73], v[98:99], v[112:113], v[72:73]
	v_pk_fma_f32 v[74:75], v[96:97], v[114:115], v[74:75]
	v_pk_add_f32 v[112:113], v[102:103], v[72:73]
	v_cndmask_b32_e64 v76, v68, v76, s[42:43]
	v_cndmask_b32_e64 v77, v69, v77, s[42:43]
	v_pk_add_f32 v[72:73], v[100:101], v[74:75]
	v_pk_mul_f32 v[74:75], v[88:89], v[112:113]
	v_cndmask_b32_e64 v78, v70, v78, s[42:43]
	v_cndmask_b32_e64 v79, v71, v79, s[42:43]
	s_nop 1
	v_mov_b32_dpp v112, v76 row_ror:1 row_mask:0xf bank_mask:0xf
	v_mov_b32_dpp v113, v77 row_ror:1 row_mask:0xf bank_mask:0xf
	v_mov_b32_dpp v114, v78 row_ror:1 row_mask:0xf bank_mask:0xf
	v_mov_b32_dpp v115, v79 row_ror:1 row_mask:0xf bank_mask:0xf
	v_cndmask_b32_e32 v88, v68, v64, vcc
	v_cndmask_b32_e64 v77, v115, 0, s[52:53]
	v_cndmask_b32_e64 v76, v114, 0, s[52:53]
	v_cndmask_b32_e32 v89, v69, v65, vcc
	v_cndmask_b32_e64 v79, v113, 0, s[52:53]
	v_cndmask_b32_e64 v78, v112, 0, s[52:53]
	v_pk_mul_f32 v[76:77], v[86:87], v[76:77]
	v_pk_mul_f32 v[72:73], v[90:91], v[72:73]
	v_cndmask_b32_e32 v90, v70, v66, vcc
	v_cndmask_b32_e32 v91, v71, v67, vcc
	s_nop 1
	v_mov_b32_dpp v134, v88 row_ror:15 row_mask:0xf bank_mask:0xf
	v_mov_b32_dpp v135, v89 row_ror:15 row_mask:0xf bank_mask:0xf
	v_mov_b32_dpp v136, v90 row_ror:15 row_mask:0xf bank_mask:0xf
	v_mov_b32_dpp v137, v91 row_ror:15 row_mask:0xf bank_mask:0xf
	v_pk_mul_f32 v[78:79], v[84:85], v[78:79]
	v_pk_fma_f32 v[76:77], v[70:71], v[94:95], v[76:77]
	v_cndmask_b32_e64 v89, v137, 0, s[54:55]
	v_cndmask_b32_e64 v88, v136, 0, s[54:55]
	v_pk_fma_f32 v[78:79], v[68:69], v[92:93], v[78:79]
	v_cndmask_b32_e64 v91, v135, 0, s[54:55]
	v_cndmask_b32_e64 v90, v134, 0, s[54:55]
	v_pk_fma_f32 v[76:77], v[98:99], v[88:89], v[76:77]
	v_pk_fma_f32 v[78:79], v[96:97], v[90:91], v[78:79]
	v_pk_add_f32 v[88:89], v[102:103], v[76:77]
	v_cndmask_b32_e64 v68, v64, v68, s[42:43]
	v_cndmask_b32_e64 v69, v65, v69, s[42:43]
	v_cndmask_b32_e64 v70, v66, v70, s[42:43]
	v_cndmask_b32_e64 v71, v67, v71, s[42:43]
	v_pk_add_f32 v[76:77], v[100:101], v[78:79]
	v_pk_mul_f32 v[78:79], v[138:139], v[88:89]
	s_nop 1
	v_mov_b32_dpp v88, v68 row_ror:1 row_mask:0xf bank_mask:0xf
	v_mov_b32_dpp v89, v69 row_ror:1 row_mask:0xf bank_mask:0xf
	v_mov_b32_dpp v90, v70 row_ror:1 row_mask:0xf bank_mask:0xf
	v_mov_b32_dpp v91, v71 row_ror:1 row_mask:0xf bank_mask:0xf
	s_nop 1
	v_mov_b32_dpp v112, v64 row_ror:15 row_mask:0xf bank_mask:0xf
	v_mov_b32_dpp v113, v65 row_ror:15 row_mask:0xf bank_mask:0xf
	v_mov_b32_dpp v114, v66 row_ror:15 row_mask:0xf bank_mask:0xf
	v_mov_b32_dpp v115, v67 row_ror:15 row_mask:0xf bank_mask:0xf
	v_cmp_gt_i32_e64 s[44:45], s61, v183
	v_cndmask_b32_e64 v69, v89, 0, s[56:57]
	v_cndmask_b32_e64 v68, v88, 0, s[56:57]
	v_cndmask_b32_e64 v71, v91, 0, s[56:57]
	v_cndmask_b32_e64 v70, v90, 0, s[56:57]
	v_pk_mul_f32 v[70:71], v[86:87], v[70:71]
	v_pk_mul_f32 v[68:69], v[84:85], v[68:69]
	v_pk_fma_f32 v[66:67], v[66:67], v[94:95], v[70:71]
	v_pk_fma_f32 v[64:65], v[64:65], v[92:93], v[68:69]
	s_waitcnt lgkmcnt(0)
	v_cndmask_b32_e64 v70, v114, v106, s[42:43]
	v_cndmask_b32_e64 v71, v115, v107, s[42:43]
	v_cndmask_b32_e64 v68, v112, v104, s[42:43]
	v_cndmask_b32_e64 v69, v113, v105, s[42:43]
	v_cndmask_b32_e64 v69, v69, 0, s[58:59]
	v_cndmask_b32_e64 v68, v68, 0, s[58:59]
	v_cndmask_b32_e64 v71, v71, 0, s[58:59]
	v_cndmask_b32_e64 v70, v70, 0, s[58:59]
	v_pk_fma_f32 v[66:67], v[98:99], v[70:71], v[66:67]
	v_pk_fma_f32 v[64:65], v[96:97], v[68:69], v[64:65]
	v_pk_mul_f32 v[76:77], v[140:141], v[76:77]
	v_pk_add_f32 v[68:69], v[100:101], v[64:65]
	v_pk_add_f32 v[64:65], v[102:103], v[66:67]
	v_pk_mul_f32 v[66:67], v[110:111], v[68:69]
	v_pk_mul_f32 v[64:65], v[108:109], v[64:65]
	s_and_b64 s[44:45], s[0:1], s[44:45]
	s_and_saveexec_b64 s[0:1], s[44:45]
	s_cbranch_execz .LBB0_97
	v_cvt_pk_bf16_f32 v70, v80, v81
	v_mov_b64_e32 v[80:81], s[82:83]
	s_movk_i32 s33, 0x1500
	v_mad_i64_i32 v[80:81], s[44:45], v183, s33, v[80:81]
	v_cvt_pk_bf16_f32 v71, v82, v83
	v_cvt_pk_bf16_f32 v68, v116, v117
	v_cvt_pk_bf16_f32 v69, v118, v119
	v_lshl_add_u64 v[80:81], v[160:161], 1, v[80:81]
	global_store_dwordx4 v[80:81], v[68:71], off nt

;     DI void operator()(const f32x4 (&acc)[2][2][4][2], const Unit& u, int wr, int wc, int fr_in, int fq_in) const {
;     ...
;         asm volatile("s_waitcnt lgkmcnt(0)" ::: "memory"); __builtin_amdgcn_s_barrier(); asm volatile("" ::: "memory");
;         const int ch = 128 * u.pn + qpos;
; #pragma unroll
;         for (int ai = 0; ai < 2; ++ai) {
;             const int blk = 2 * ai + wr;
;             const int tr0 = 128 * ai + 64 * wr + fr;
;             u32x2 pk0[4];
; #pragma unroll
;             for (int n = 0; n < 2; ++n) {
;                 f32x4 ga[4];
; #pragma unroll
;                 for (int bj = 0; bj < 2; ++bj) {
;                     const LAS float* wp = wlb + 128 * bj + qpos + 4 * n;
;                     const f32x4 w0 = *(const LAS f32x4*)(wp), w1 = *(const LAS f32x4*)(wp + 256), w2 = *(const LAS f32x4*)(wp + 512), bb = *(const LAS f32x4*)(wp + 768);
;                     const f32x4 eprev = *(const LAS f32x4*)(exb + (((blk + 3) & 3) * 2 + 1) * 256 + 128 * bj + qpos + 4 * n);
;                     const f32x4 enext = *(const LAS f32x4*)(exb + (((blk + 1) & 3) * 2 + 0) * 256 + 128 * bj + qpos + 4 * n);
; #pragma unroll
;                     for (int m = 0; m < 4; ++m) {
;                         const int g = 254 * u.pm - 1 + tr0 + 16 * m;
;                         const int lmask = (g < NLAT) ? (T - 1) : (CL - 1);
;                         const bool hp = (g & lmask) != 0, hn = ((g + 1) & lmask) != 0;
;                         f32x4 sp = acc[ai][bj][m][n], sn = acc[ai][bj][m][n];
;                         if (m > 0 && fr == 15) sp = acc[ai][bj][m > 0 ? m - 1 : 0][n];
;                         if (m < 3 && fr == 0) sn = acc[ai][bj][m < 3 ? m + 1 : 3][n];
;                         f32x4 pv, nv;
;                         dpp_rot4<0>(pv, sp); dpp_rot4<1>(nv, sn);
;                         if (m == 0 && fr == 0) pv = eprev;
;                         if (m == 3 && fr == 15) nv = enext;
;                         if (!hp) pv = (f32x4){0.f, 0.f, 0.f, 0.f};
;                         if (!hn) nv = (f32x4){0.f, 0.f, 0.f, 0.f};
;                         const f32x4 uu = pv * w0 + acc[ai][bj][m][n] * w1 + nv * w2 + bb;
;                         if (bj == 0) { ga[m][0] = gelu_tanh(uu[0]); ga[m][1] = gelu_tanh(uu[1]); ga[m][2] = gelu_tanh(uu[2]); ga[m][3] = gelu_tanh(uu[3]); }
;                         else ga[m] = ga[m] * uu;
.LBB0_111:
	s_or_b64 exec, exec, s[0:1]
	s_andn2_b64 vcc, exec, s[40:41]
	s_cbranch_vccnz .LBB0_113
	s_not_b32 s0, s37
	s_lshl_b32 s0, s0, 12
	s_and_b32 s0, s0, 0x1000
	v_lshl_add_u32 v0, v176, 2, s0
	v_add_u32_e32 v0, 0x24000, v0
	ds_write2st64_b32 v0, v177, v178 offset1:8
	s_branch .LBB0_113
.Lfp_body:
	v_readlane_b32 s0, v254, 51
	v_lshlrev_b32_e32 v130, 2, v181
	v_lshl_add_u32 v131, s39, 12, v130
	v_add_u32_e32 v180, s0, v161
	v_readlane_b32 s0, v254, 18
	s_lshl_b32 s0, s0, 2
	s_add_i32 s0, s38, s0
	s_waitcnt lgkmcnt(0)
	s_barrier
	v_add_u32_e32 v179, 0x24000, v131
	v_add_u32_e32 v191, s0, v130
	v_readlane_b32 s0, v254, 50
	v_add_u32_e32 v184, -1, v180
	s_mul_i32 s65, s52, 0xfe
	v_lshl_add_u32 v192, s0, 2, v182
	s_waitcnt vmcnt(0)
	ds_read_b128 v[146:149], v179
	ds_read_b128 v[138:141], v179 offset:1024
	ds_read_b128 v[134:137], v179 offset:2048
	ds_read_b128 v[130:133], v179 offset:3072
	ds_read_b128 v[162:165], v191 offset:1024
	ds_read_b128 v[142:145], v192
	v_add_u32_e32 v183, s65, v184
	s_mov_b32 s33, 0x10000
	v_cmp_gt_i32_e32 vcc, s33, v183
	v_add_u32_e32 v168, s65, v180
	s_nop 1
	v_mov_b32_dpp v187, v124 row_ror:1 row_mask:0xf bank_mask:0xf
	v_mov_b32_dpp v188, v125 row_ror:1 row_mask:0xf bank_mask:0xf
	v_mov_b32_dpp v189, v126 row_ror:1 row_mask:0xf bank_mask:0xf
	v_mov_b32_dpp v190, v127 row_ror:1 row_mask:0xf bank_mask:0xf
	v_lshl_add_u32 v160, s42, 7, v181
	v_cndmask_b32_e32 v166, v204, v205, vcc
	v_cmp_eq_u32_e32 vcc, 0, v161
	v_and_b32_e32 v167, v166, v183
	v_and_b32_e32 v166, v166, v168
	v_cndmask_b32_e32 v168, v124, v120, vcc
	v_cndmask_b32_e32 v169, v125, v121, vcc
	v_cndmask_b32_e32 v185, v126, v122, vcc
	v_cndmask_b32_e32 v186, v127, v123, vcc
	s_nop 1
	v_mov_b32_dpp v193, v168 row_ror:15 row_mask:0xf bank_mask:0xf
	v_mov_b32_dpp v194, v169 row_ror:15 row_mask:0xf bank_mask:0xf
	v_mov_b32_dpp v195, v185 row_ror:15 row_mask:0xf bank_mask:0xf
	v_mov_b32_dpp v196, v186 row_ror:15 row_mask:0xf bank_mask:0xf
	s_waitcnt lgkmcnt(1)
	v_cndmask_b32_e32 v168, v187, v162, vcc
	v_cndmask_b32_e32 v169, v188, v163, vcc
	v_cmp_eq_u32_e64 s[44:45], 0, v167
	v_cndmask_b32_e32 v162, v189, v164, vcc
	v_cndmask_b32_e32 v163, v190, v165, vcc
	v_pk_mul_f32 v[164:165], v[146:147], v[168:169]
	v_cmp_eq_u32_e64 s[46:47], 0, v166
	v_pk_fma_f32 v[164:165], v[124:125], v[138:139], v[164:165]
	v_mov_b32_e32 v169, v194
	v_mov_b32_e32 v168, v193
	v_pk_mul_f32 v[162:163], v[148:149], v[162:163]
	v_pk_fma_f32 v[164:165], v[134:135], v[168:169], v[164:165]
	v_pk_fma_f32 v[162:163], v[126:127], v[140:141], v[162:163]
	v_mov_b32_e32 v167, v196
	v_mov_b32_e32 v166, v195
	v_pk_add_f32 v[164:165], v[130:131], v[164:165]
	v_pk_fma_f32 v[162:163], v[136:137], v[166:167], v[162:163]
	v_mul_f32_e32 v166, v164, v164
	v_fmamk_f32 v166, v166, 0xbdd2d3e7, v198
	v_mul_f32_e32 v167, v165, v165
	v_pk_add_f32 v[162:163], v[132:133], v[162:163]
	v_mul_f32_e32 v166, v164, v166
	v_fmamk_f32 v167, v167, 0xbdd2d3e7, v198
	v_mul_f32_e32 v168, v162, v162
	v_exp_f32_e32 v166, v166
	v_mul_f32_e32 v167, v165, v167
	v_fmamk_f32 v168, v168, 0xbdd2d3e7, v198
	v_exp_f32_e32 v167, v167
	v_mul_f32_e32 v168, v162, v168
	v_mul_f32_e32 v169, v163, v163
	v_exp_f32_e32 v168, v168
	v_fmamk_f32 v169, v169, 0xbdd2d3e7, v198
	v_mul_f32_e32 v169, v163, v169
	v_add_f32_e32 v166, 1.0, v166
	v_exp_f32_e32 v169, v169
	v_rcp_f32_e32 v166, v166
	v_add_f32_e32 v167, 1.0, v167
	v_rcp_f32_e32 v167, v167
	v_add_f32_e32 v168, 1.0, v168
	v_add_u32_e32 v186, 15, v180
	v_rcp_f32_e32 v168, v168
	v_add_u32_e32 v185, s65, v186
	v_add_f32_e32 v169, 1.0, v169
	v_cmp_gt_i32_e64 s[0:1], s33, v185
	v_rcp_f32_e32 v169, v169
	v_mul_f32_e32 v164, v164, v166
	v_cndmask_b32_e64 v166, v204, v205, s[0:1]
	v_mul_f32_e32 v165, v165, v167
	v_and_b32_e32 v167, v166, v185
	v_cmp_eq_u32_e64 s[42:43], 15, v161
	v_mul_f32_e32 v162, v162, v168
	v_add_u32_e32 v168, 1, v185
	v_cndmask_b32_e64 v126, v122, v126, s[42:43]
	v_cndmask_b32_e64 v127, v123, v127, s[42:43]
	v_cmp_eq_u32_e64 s[48:49], 0, v167
	v_and_b32_e32 v166, v166, v168
	v_cndmask_b32_e64 v124, v120, v124, s[42:43]
	v_cndmask_b32_e64 v125, v121, v125, s[42:43]
	s_nop 1
	v_mov_b32_dpp v188, v124 row_ror:1 row_mask:0xf bank_mask:0xf
	v_mov_b32_dpp v189, v125 row_ror:1 row_mask:0xf bank_mask:0xf
	v_mov_b32_dpp v190, v126 row_ror:1 row_mask:0xf bank_mask:0xf
	v_mov_b32_dpp v193, v127 row_ror:1 row_mask:0xf bank_mask:0xf
	v_mul_f32_e32 v163, v163, v169
	v_cndmask_b32_e32 v168, v121, v117, vcc
	v_cndmask_b32_e32 v169, v122, v118, vcc
	v_pk_mul_f32 v[126:127], v[146:147], v[188:189]
	v_cmp_eq_u32_e64 s[50:51], 0, v166
	v_cndmask_b32_e32 v161, v120, v116, vcc
	v_cndmask_b32_e32 v187, v123, v119, vcc
	s_nop 1
	v_mov_b32_dpp v194, v161 row_ror:15 row_mask:0xf bank_mask:0xf
	v_mov_b32_dpp v195, v168 row_ror:15 row_mask:0xf bank_mask:0xf
	v_mov_b32_dpp v196, v169 row_ror:15 row_mask:0xf bank_mask:0xf
	v_mov_b32_dpp v197, v187 row_ror:15 row_mask:0xf bank_mask:0xf
	v_mov_b32_e32 v125, v193
	v_mov_b32_e32 v124, v190
	v_pk_fma_f32 v[126:127], v[120:121], v[138:139], v[126:127]
	v_pk_mul_f32 v[124:125], v[148:149], v[124:125]
	v_pk_fma_f32 v[126:127], v[134:135], v[194:195], v[126:127]
	v_pk_fma_f32 v[124:125], v[122:123], v[140:141], v[124:125]
	v_pk_add_f32 v[126:127], v[130:131], v[126:127]
	v_pk_fma_f32 v[124:125], v[136:137], v[196:197], v[124:125]
	v_mul_f32_e32 v161, v126, v126
	v_fmamk_f32 v161, v161, 0xbdd2d3e7, v198
	v_mul_f32_e32 v166, v127, v127
	v_pk_add_f32 v[124:125], v[132:133], v[124:125]
	v_mul_f32_e32 v161, v126, v161
	v_fmamk_f32 v166, v166, 0xbdd2d3e7, v198
	v_mul_f32_e32 v167, v124, v124
	v_exp_f32_e32 v161, v161
	v_mul_f32_e32 v166, v127, v166
; #define LAS __attribute__((address_space(3)))
;     DI void operator()(const f32x4 (&acc)[2][2][4][2], const Unit& u, int wr, int wc, int fr_in, int fq_in) const {
;     ...
;                     const LAS float* wp = wlb + 128 * bj + qpos + 4 * n;
;                     const f32x4 w0 = *(const LAS f32x4*)(wp), w1 = *(const LAS f32x4*)(wp + 256), w2 = *(const LAS f32x4*)(wp + 512), bb = *(const LAS f32x4*)(wp + 768);
;                     const f32x4 eprev = *(const LAS f32x4*)(exb + (((blk + 3) & 3) * 2 + 1) * 256 + 128 * bj + qpos + 4 * n);
;                     const f32x4 enext = *(const LAS f32x4*)(exb + (((blk + 1) & 3) * 2 + 0) * 256 + 128 * bj + qpos + 4 * n);
; #pragma unroll
;                     for (int m = 0; m < 4; ++m) {
;                         const int g = 254 * u.pm - 1 + tr0 + 16 * m;
;                         const int lmask = (g < NLAT) ? (T - 1) : (CL - 1);
;                         const bool hp = (g & lmask) != 0, hn = ((g + 1) & lmask) != 0;
;                         f32x4 sp = acc[ai][bj][m][n], sn = acc[ai][bj][m][n];
;                         if (m > 0 && fr == 15) sp = acc[ai][bj][m > 0 ? m - 1 : 0][n];
;                         if (m < 3 && fr == 0) sn = acc[ai][bj][m < 3 ? m + 1 : 3][n];
;                         f32x4 pv, nv;
;                         dpp_rot4<0>(pv, sp); dpp_rot4<1>(nv, sn);
;                         if (m == 0 && fr == 0) pv = eprev;
;                         if (m == 3 && fr == 15) nv = enext;
;                         if (!hp) pv = (f32x4){0.f, 0.f, 0.f, 0.f};
;                         if (!hn) nv = (f32x4){0.f, 0.f, 0.f, 0.f};
;                         const f32x4 uu = pv * w0 + acc[ai][bj][m][n] * w1 + nv * w2 + bb;
;                         if (bj == 0) { ga[m][0] = gelu_tanh(uu[0]); ga[m][1] = gelu_tanh(uu[1]); ga[m][2] = gelu_tanh(uu[2]); ga[m][3] = gelu_tanh(uu[3]); }
;                         else ga[m] = ga[m] * uu;
;                         asm volatile("" : "+v"(ga[m][0]), "+v"(ga[m][1]), "+v"(ga[m][2]), "+v"(ga[m][3]));
;                     }
;                 }
	v_fmamk_f32 v167, v167, 0xbdd2d3e7, v198
	v_exp_f32_e32 v166, v166
	v_mul_f32_e32 v167, v124, v167
	v_mul_f32_e32 v168, v125, v125
	v_exp_f32_e32 v167, v167
	v_fmamk_f32 v168, v168, 0xbdd2d3e7, v198
	v_mul_f32_e32 v168, v125, v168
	v_add_f32_e32 v161, 1.0, v161
	v_exp_f32_e32 v168, v168
	v_rcp_f32_e32 v161, v161
	v_add_f32_e32 v166, 1.0, v166
	v_rcp_f32_e32 v166, v166
	v_add_f32_e32 v167, 1.0, v167
	v_add_u32_e32 v188, 31, v180
	v_rcp_f32_e32 v167, v167
	v_add_u32_e32 v187, s65, v188
	v_add_f32_e32 v168, 1.0, v168
	v_cmp_gt_i32_e64 s[0:1], s33, v187
	v_rcp_f32_e32 v168, v168
	v_mul_f32_e32 v126, v126, v161
	v_cndmask_b32_e64 v161, v204, v205, s[0:1]
	v_mul_f32_e32 v127, v127, v166
	v_and_b32_e32 v166, v161, v187
	v_mul_f32_e32 v124, v124, v167
	v_add_u32_e32 v167, 1, v187
	v_cndmask_b32_e64 v120, v116, v120, s[42:43]
	v_cndmask_b32_e64 v121, v117, v121, s[42:43]
	v_cndmask_b32_e64 v122, v118, v122, s[42:43]
	v_cndmask_b32_e64 v123, v119, v123, s[42:43]
	v_cmp_eq_u32_e64 s[52:53], 0, v166
	v_and_b32_e32 v161, v161, v167
	s_nop 1
	v_mov_b32_dpp v190, v120 row_ror:1 row_mask:0xf bank_mask:0xf
	v_mov_b32_dpp v193, v121 row_ror:1 row_mask:0xf bank_mask:0xf
	v_mov_b32_dpp v194, v122 row_ror:1 row_mask:0xf bank_mask:0xf
	v_mov_b32_dpp v195, v123 row_ror:1 row_mask:0xf bank_mask:0xf
	v_mul_f32_e32 v125, v125, v168
	v_mov_b32_e32 v123, v193
	v_mov_b32_e32 v122, v190
	v_cndmask_b32_e32 v167, v116, v112, vcc
	v_cndmask_b32_e32 v168, v117, v113, vcc
	v_cndmask_b32_e32 v169, v118, v114, vcc
	v_pk_mul_f32 v[122:123], v[146:147], v[122:123]
	v_pk_mul_f32 v[120:121], v[148:149], v[194:195]
	v_cmp_eq_u32_e64 s[54:55], 0, v161
	v_cndmask_b32_e32 v189, v119, v115, vcc
	s_nop 1
	v_mov_b32_dpp v196, v167 row_ror:15 row_mask:0xf bank_mask:0xf
	v_mov_b32_dpp v197, v168 row_ror:15 row_mask:0xf bank_mask:0xf
	v_mov_b32_dpp v200, v169 row_ror:15 row_mask:0xf bank_mask:0xf
	v_mov_b32_dpp v201, v189 row_ror:15 row_mask:0xf bank_mask:0xf
	v_pk_fma_f32 v[120:121], v[118:119], v[140:141], v[120:121]
	v_pk_fma_f32 v[122:123], v[116:117], v[138:139], v[122:123]
	v_pk_fma_f32 v[122:123], v[134:135], v[196:197], v[122:123]
	v_pk_fma_f32 v[120:121], v[136:137], v[200:201], v[120:121]
	v_pk_add_f32 v[122:123], v[130:131], v[122:123]
	v_pk_add_f32 v[120:121], v[132:133], v[120:121]
	v_mul_f32_e32 v166, v123, v123
	v_mul_f32_e32 v167, v120, v120
	v_mul_f32_e32 v168, v121, v121
	v_fmamk_f32 v166, v166, 0xbdd2d3e7, v198
	v_fmamk_f32 v167, v167, 0xbdd2d3e7, v198
	v_fmamk_f32 v168, v168, 0xbdd2d3e7, v198
	v_mul_f32_e32 v166, v123, v166
	v_mul_f32_e32 v167, v120, v167
	v_mul_f32_e32 v168, v121, v168
	v_exp_f32_e32 v166, v166
	v_exp_f32_e32 v167, v167
	v_exp_f32_e32 v168, v168
	v_mul_f32_e32 v161, v122, v122
	v_fmamk_f32 v161, v161, 0xbdd2d3e7, v198
	v_mul_f32_e32 v161, v122, v161
	v_exp_f32_e32 v161, v161
	v_add_f32_e32 v166, 1.0, v166
	v_add_f32_e32 v167, 1.0, v167
	v_add_f32_e32 v168, 1.0, v168
	v_rcp_f32_e32 v166, v166
	v_rcp_f32_e32 v167, v167
	v_rcp_f32_e32 v189, v168
	v_add_f32_e32 v161, 1.0, v161
	v_add_u32_e32 v190, 47, v180
	v_rcp_f32_e32 v161, v161
	v_mul_f32_e32 v169, v123, v166
	v_mul_f32_e32 v166, v120, v167
	v_mul_f32_e32 v167, v121, v189
	v_add_u32_e32 v189, s65, v190
	v_cmp_gt_i32_e64 s[0:1], s33, v189
	v_mul_f32_e32 v168, v122, v161
	v_add_u32_e32 v122, 1, v189
	v_cndmask_b32_e64 v120, v204, v205, s[0:1]
	v_and_b32_e32 v121, v120, v189
	v_cndmask_b32_e64 v116, v112, v116, s[42:43]
	v_cndmask_b32_e64 v117, v113, v117, s[42:43]
	v_cndmask_b32_e64 v118, v114, v118, s[42:43]
	v_cndmask_b32_e64 v119, v115, v119, s[42:43]
	v_cmp_eq_u32_e64 s[56:57], 0, v121
	v_and_b32_e32 v120, v120, v122
	s_nop 1
	v_mov_b32_dpp v122, v116 row_ror:1 row_mask:0xf bank_mask:0xf
	v_mov_b32_dpp v123, v117 row_ror:1 row_mask:0xf bank_mask:0xf
	v_mov_b32_dpp v161, v118 row_ror:1 row_mask:0xf bank_mask:0xf
	v_mov_b32_dpp v193, v119 row_ror:1 row_mask:0xf bank_mask:0xf
	s_nop 1
	v_mov_b32_dpp v194, v112 row_ror:15 row_mask:0xf bank_mask:0xf
	v_mov_b32_dpp v195, v113 row_ror:15 row_mask:0xf bank_mask:0xf
	v_mov_b32_dpp v196, v114 row_ror:15 row_mask:0xf bank_mask:0xf
	v_mov_b32_dpp v197, v115 row_ror:15 row_mask:0xf bank_mask:0xf
	v_cmp_eq_u32_e64 s[58:59], 0, v120
	v_mov_b32_e32 v117, v193
	v_mov_b32_e32 v116, v161
	v_pk_mul_f32 v[118:119], v[146:147], v[122:123]
	v_pk_mul_f32 v[116:117], v[148:149], v[116:117]
	v_pk_fma_f32 v[112:113], v[112:113], v[138:139], v[118:119]
	v_pk_fma_f32 v[114:115], v[114:115], v[140:141], v[116:117]
	s_waitcnt lgkmcnt(0)
	v_cndmask_b32_e64 v118, v194, v142, s[42:43]
	v_cndmask_b32_e64 v119, v195, v143, s[42:43]
	v_cndmask_b32_e64 v116, v196, v144, s[42:43]
	v_cndmask_b32_e64 v117, v197, v145, s[42:43]
	v_pk_fma_f32 v[112:113], v[134:135], v[118:119], v[112:113]
	v_pk_fma_f32 v[114:115], v[136:137], v[116:117], v[114:115]
	v_pk_add_f32 v[112:113], v[130:131], v[112:113]
	v_pk_add_f32 v[114:115], v[132:133], v[114:115]
	v_mul_f32_e32 v116, v112, v112
	v_mul_f32_e32 v117, v113, v113
	v_mul_f32_e32 v118, v114, v114
	v_mul_f32_e32 v119, v115, v115
	v_fmamk_f32 v116, v116, 0xbdd2d3e7, v198
	v_fmamk_f32 v117, v117, 0xbdd2d3e7, v198
	v_fmamk_f32 v118, v118, 0xbdd2d3e7, v198
	v_fmamk_f32 v119, v119, 0xbdd2d3e7, v198
	v_mul_f32_e32 v116, v112, v116
	v_mul_f32_e32 v117, v113, v117
	v_mul_f32_e32 v118, v114, v118
	v_mul_f32_e32 v119, v115, v119
	v_exp_f32_e32 v116, v116
	v_exp_f32_e32 v117, v117
	v_exp_f32_e32 v118, v118
	v_exp_f32_e32 v119, v119
	v_add_f32_e32 v116, 1.0, v116
	v_add_f32_e32 v117, 1.0, v117
	v_add_f32_e32 v118, 1.0, v118
	v_add_f32_e32 v119, 1.0, v119
	v_rcp_f32_e32 v116, v116
	v_rcp_f32_e32 v117, v117
	v_rcp_f32_e32 v118, v118
	v_rcp_f32_e32 v119, v119
	v_mul_f32_e32 v146, v112, v116
	v_mul_f32_e32 v147, v113, v117
	v_mul_f32_e32 v148, v114, v118
	v_mul_f32_e32 v149, v115, v119
	ds_read_b128 v[112:115], v179 offset:512
	ds_read_b128 v[130:133], v179 offset:1536
	ds_read_b128 v[134:137], v179 offset:2560
	ds_read_b128 v[138:141], v179 offset:3584
	ds_read_b128 v[116:119], v191 offset:1536
	ds_read_b128 v[142:145], v192 offset:512
	v_cndmask_b32_e32 v120, v104, v108, vcc
	v_cndmask_b32_e32 v121, v105, v109, vcc
	v_cndmask_b32_e32 v122, v106, v110, vcc
	v_cndmask_b32_e32 v123, v107, v111, vcc
	s_nop 1
	v_mov_b32_dpp v161, v104 row_ror:1 row_mask:0xf bank_mask:0xf
	v_mov_b32_dpp v193, v105 row_ror:1 row_mask:0xf bank_mask:0xf
	v_mov_b32_dpp v194, v106 row_ror:1 row_mask:0xf bank_mask:0xf
	v_mov_b32_dpp v195, v107 row_ror:1 row_mask:0xf bank_mask:0xf
	s_nop 1
	v_mov_b32_dpp v196, v120 row_ror:15 row_mask:0xf bank_mask:0xf
	v_mov_b32_dpp v197, v121 row_ror:15 row_mask:0xf bank_mask:0xf
	v_mov_b32_dpp v200, v122 row_ror:15 row_mask:0xf bank_mask:0xf
	v_mov_b32_dpp v201, v123 row_ror:15 row_mask:0xf bank_mask:0xf
	s_movk_i32 s0, 0xfe
	s_waitcnt lgkmcnt(1)
; #define LAS __attribute__((address_space(3)))
;     DI void operator()(const f32x4 (&acc)[2][2][4][2], const Unit& u, int wr, int wc, int fr_in, int fq_in) const {
;     ...
;                 f32x4 ga[4];
; #pragma unroll
;                 for (int bj = 0; bj < 2; ++bj) {
;                     const LAS float* wp = wlb + 128 * bj + qpos + 4 * n;
;                     const f32x4 w0 = *(const LAS f32x4*)(wp), w1 = *(const LAS f32x4*)(wp + 256), w2 = *(const LAS f32x4*)(wp + 512), bb = *(const LAS f32x4*)(wp + 768);
;                     const f32x4 eprev = *(const LAS f32x4*)(exb + (((blk + 3) & 3) * 2 + 1) * 256 + 128 * bj + qpos + 4 * n);
;                     const f32x4 enext = *(const LAS f32x4*)(exb + (((blk + 1) & 3) * 2 + 0) * 256 + 128 * bj + qpos + 4 * n);
; #pragma unroll
;                     for (int m = 0; m < 4; ++m) {
;                         const int g = 254 * u.pm - 1 + tr0 + 16 * m;
;                         const int lmask = (g < NLAT) ? (T - 1) : (CL - 1);
;                         const bool hp = (g & lmask) != 0, hn = ((g + 1) & lmask) != 0;
;                         f32x4 sp = acc[ai][bj][m][n], sn = acc[ai][bj][m][n];
;                         if (m > 0 && fr == 15) sp = acc[ai][bj][m > 0 ? m - 1 : 0][n];
;                         if (m < 3 && fr == 0) sn = acc[ai][bj][m < 3 ? m + 1 : 3][n];
;                         f32x4 pv, nv;
;                         dpp_rot4<0>(pv, sp); dpp_rot4<1>(nv, sn);
;                         if (m == 0 && fr == 0) pv = eprev;
;                         if (m == 3 && fr == 15) nv = enext;
;                         if (!hp) pv = (f32x4){0.f, 0.f, 0.f, 0.f};
;                         if (!hn) nv = (f32x4){0.f, 0.f, 0.f, 0.f};
;                         const f32x4 uu = pv * w0 + acc[ai][bj][m][n] * w1 + nv * w2 + bb;
;                         if (bj == 0) { ga[m][0] = gelu_tanh(uu[0]); ga[m][1] = gelu_tanh(uu[1]); ga[m][2] = gelu_tanh(uu[2]); ga[m][3] = gelu_tanh(uu[3]); }
;                         else ga[m] = ga[m] * uu;
;                         asm volatile("" : "+v"(ga[m][0]), "+v"(ga[m][1]), "+v"(ga[m][2]), "+v"(ga[m][3]));
;                     }
;                 }
	v_cndmask_b32_e32 v120, v161, v116, vcc
	v_cndmask_b32_e32 v121, v193, v117, vcc
	v_cndmask_b32_e32 v116, v194, v118, vcc
	v_cndmask_b32_e32 v117, v195, v119, vcc
	v_pk_mul_f32 v[118:119], v[112:113], v[120:121]
	v_pk_mul_f32 v[116:117], v[114:115], v[116:117]
	v_pk_fma_f32 v[118:119], v[104:105], v[130:131], v[118:119]
	v_pk_fma_f32 v[116:117], v[106:107], v[132:133], v[116:117]
	v_pk_fma_f32 v[118:119], v[134:135], v[196:197], v[118:119]
	v_pk_fma_f32 v[116:117], v[136:137], v[200:201], v[116:117]
	v_cndmask_b32_e64 v104, v108, v104, s[42:43]
	v_pk_add_f32 v[120:121], v[140:141], v[116:117]
	v_pk_add_f32 v[116:117], v[138:139], v[118:119]
	v_cndmask_b32_e64 v105, v109, v105, s[42:43]
	v_cndmask_b32_e64 v106, v110, v106, s[42:43]
	v_cndmask_b32_e64 v107, v111, v107, s[42:43]
	v_pk_mul_f32 v[116:117], v[164:165], v[116:117]
	v_pk_mul_f32 v[118:119], v[162:163], v[120:121]
	s_nop 1
	v_mov_b32_dpp v161, v104 row_ror:1 row_mask:0xf bank_mask:0xf
	v_mov_b32_dpp v162, v105 row_ror:1 row_mask:0xf bank_mask:0xf
	v_mov_b32_dpp v163, v106 row_ror:1 row_mask:0xf bank_mask:0xf
	v_mov_b32_dpp v164, v107 row_ror:1 row_mask:0xf bank_mask:0xf
	v_cndmask_b32_e32 v120, v108, v100, vcc
	v_mov_b32_e32 v105, v164
	v_mov_b32_e32 v104, v163
	v_mov_b32_e32 v107, v162
	v_mov_b32_e32 v106, v161
	v_cndmask_b32_e32 v121, v109, v101, vcc
	v_cndmask_b32_e32 v122, v110, v102, vcc
	v_cndmask_b32_e32 v123, v111, v103, vcc
	v_pk_mul_f32 v[106:107], v[112:113], v[106:107]
	v_pk_mul_f32 v[104:105], v[114:115], v[104:105]
	s_nop 1
	v_mov_b32_dpp v165, v120 row_ror:15 row_mask:0xf bank_mask:0xf
	v_mov_b32_dpp v193, v121 row_ror:15 row_mask:0xf bank_mask:0xf
	v_mov_b32_dpp v194, v122 row_ror:15 row_mask:0xf bank_mask:0xf
	v_mov_b32_dpp v195, v123 row_ror:15 row_mask:0xf bank_mask:0xf
	v_pk_fma_f32 v[106:107], v[108:109], v[130:131], v[106:107]
	v_pk_fma_f32 v[104:105], v[110:111], v[132:133], v[104:105]
	v_mov_b32_e32 v123, v193
	v_mov_b32_e32 v122, v165
	v_pk_fma_f32 v[106:107], v[134:135], v[122:123], v[106:107]
	v_pk_fma_f32 v[104:105], v[136:137], v[194:195], v[104:105]
	v_pk_add_f32 v[106:107], v[138:139], v[106:107]
	v_pk_add_f32 v[104:105], v[140:141], v[104:105]
	v_pk_mul_f32 v[120:121], v[126:127], v[106:107]
	v_pk_mul_f32 v[122:123], v[124:125], v[104:105]
	v_cndmask_b32_e64 v104, v100, v108, s[42:43]
	v_cndmask_b32_e64 v105, v101, v109, s[42:43]
	v_cndmask_b32_e64 v106, v102, v110, s[42:43]
	v_cndmask_b32_e64 v107, v103, v111, s[42:43]
	s_nop 1
	v_mov_b32_dpp v124, v104 row_ror:1 row_mask:0xf bank_mask:0xf
	v_mov_b32_dpp v125, v105 row_ror:1 row_mask:0xf bank_mask:0xf
	v_mov_b32_dpp v126, v106 row_ror:1 row_mask:0xf bank_mask:0xf
	v_mov_b32_dpp v127, v107 row_ror:1 row_mask:0xf bank_mask:0xf
	v_cndmask_b32_e32 v108, v100, v96, vcc
	v_cndmask_b32_e32 v109, v101, v97, vcc
	v_cndmask_b32_e32 v110, v102, v98, vcc
	v_cndmask_b32_e32 v111, v103, v99, vcc
	v_pk_mul_f32 v[106:107], v[112:113], v[124:125]
	v_pk_mul_f32 v[104:105], v[114:115], v[126:127]
	s_nop 1
	v_mov_b32_dpp v161, v108 row_ror:15 row_mask:0xf bank_mask:0xf
	v_mov_b32_dpp v162, v109 row_ror:15 row_mask:0xf bank_mask:0xf
	v_mov_b32_dpp v163, v110 row_ror:15 row_mask:0xf bank_mask:0xf
	v_mov_b32_dpp v164, v111 row_ror:15 row_mask:0xf bank_mask:0xf
	v_pk_fma_f32 v[106:107], v[100:101], v[130:131], v[106:107]
	v_pk_fma_f32 v[104:105], v[102:103], v[132:133], v[104:105]
	v_mov_b32_e32 v109, v164
	v_mov_b32_e32 v108, v163
	v_mov_b32_e32 v111, v162
	v_mov_b32_e32 v110, v161
	v_pk_fma_f32 v[106:107], v[134:135], v[110:111], v[106:107]
	v_pk_fma_f32 v[104:105], v[136:137], v[108:109], v[104:105]
	v_pk_add_f32 v[106:107], v[138:139], v[106:107]
	v_pk_add_f32 v[104:105], v[140:141], v[104:105]
	v_cndmask_b32_e64 v100, v96, v100, s[42:43]
	v_cndmask_b32_e64 v101, v97, v101, s[42:43]
	v_cndmask_b32_e64 v102, v98, v102, s[42:43]
	v_cndmask_b32_e64 v103, v99, v103, s[42:43]
	v_pk_mul_f32 v[124:125], v[168:169], v[106:107]
	v_pk_mul_f32 v[126:127], v[166:167], v[104:105]
	s_nop 1
	v_mov_b32_dpp v104, v100 row_ror:1 row_mask:0xf bank_mask:0xf
	v_mov_b32_dpp v105, v101 row_ror:1 row_mask:0xf bank_mask:0xf
	v_mov_b32_dpp v106, v102 row_ror:1 row_mask:0xf bank_mask:0xf
	v_mov_b32_dpp v107, v103 row_ror:1 row_mask:0xf bank_mask:0xf
	s_nop 1
	v_mov_b32_dpp v108, v96 row_ror:15 row_mask:0xf bank_mask:0xf
	v_mov_b32_dpp v109, v97 row_ror:15 row_mask:0xf bank_mask:0xf
	v_mov_b32_dpp v110, v98 row_ror:15 row_mask:0xf bank_mask:0xf
	v_mov_b32_dpp v111, v99 row_ror:15 row_mask:0xf bank_mask:0xf
	v_cmp_gt_u32_e64 s[0:1], s0, v184
	v_pk_mul_f32 v[102:103], v[114:115], v[106:107]
	v_pk_mul_f32 v[100:101], v[112:113], v[104:105]
	v_pk_fma_f32 v[98:99], v[98:99], v[132:133], v[102:103]
	v_pk_fma_f32 v[96:97], v[96:97], v[130:131], v[100:101]
	s_waitcnt lgkmcnt(0)
	v_cndmask_b32_e64 v102, v110, v144, s[42:43]
	v_cndmask_b32_e64 v103, v111, v145, s[42:43]
	v_cndmask_b32_e64 v100, v108, v142, s[42:43]
	v_cndmask_b32_e64 v101, v109, v143, s[42:43]
	v_pk_fma_f32 v[98:99], v[136:137], v[102:103], v[98:99]
	v_pk_fma_f32 v[96:97], v[134:135], v[100:101], v[96:97]
	v_pk_add_f32 v[98:99], v[140:141], v[98:99]
	v_pk_add_f32 v[96:97], v[138:139], v[96:97]
	v_pk_mul_f32 v[130:131], v[148:149], v[98:99]
	v_pk_mul_f32 v[132:133], v[146:147], v[96:97]
	s_nop 1
	v_mov_b32_dpp v142, v88 row_ror:1 row_mask:0xf bank_mask:0xf
	v_mov_b32_dpp v143, v89 row_ror:1 row_mask:0xf bank_mask:0xf
	v_mov_b32_dpp v144, v90 row_ror:1 row_mask:0xf bank_mask:0xf
	v_mov_b32_dpp v145, v91 row_ror:1 row_mask:0xf bank_mask:0xf
	v_cndmask_b32_e32 v138, v88, v92, vcc
	ds_read_b128 v[112:115], v179 offset:16
	ds_read_b128 v[104:107], v179 offset:1040
	ds_read_b128 v[100:103], v179 offset:2064
	ds_read_b128 v[96:99], v179 offset:3088
	ds_read_b128 v[134:137], v191 offset:1040
	ds_read_b128 v[108:111], v192 offset:16
	v_cndmask_b32_e32 v139, v89, v93, vcc
	v_cndmask_b32_e32 v140, v90, v94, vcc
	v_cndmask_b32_e32 v141, v91, v95, vcc
	s_waitcnt lgkmcnt(1)
; #define LAS __attribute__((address_space(3)))
;     DI void operator()(const f32x4 (&acc)[2][2][4][2], const Unit& u, int wr, int wc, int fr_in, int fq_in) const {
;     ...
;                     const LAS float* wp = wlb + 128 * bj + qpos + 4 * n;
;                     const f32x4 w0 = *(const LAS f32x4*)(wp), w1 = *(const LAS f32x4*)(wp + 256), w2 = *(const LAS f32x4*)(wp + 512), bb = *(const LAS f32x4*)(wp + 768);
;                     const f32x4 eprev = *(const LAS f32x4*)(exb + (((blk + 3) & 3) * 2 + 1) * 256 + 128 * bj + qpos + 4 * n);
;                     const f32x4 enext = *(const LAS f32x4*)(exb + (((blk + 1) & 3) * 2 + 0) * 256 + 128 * bj + qpos + 4 * n);
; #pragma unroll
;                     for (int m = 0; m < 4; ++m) {
;                         const int g = 254 * u.pm - 1 + tr0 + 16 * m;
;                         const int lmask = (g < NLAT) ? (T - 1) : (CL - 1);
;                         const bool hp = (g & lmask) != 0, hn = ((g + 1) & lmask) != 0;
;                         f32x4 sp = acc[ai][bj][m][n], sn = acc[ai][bj][m][n];
;                         if (m > 0 && fr == 15) sp = acc[ai][bj][m > 0 ? m - 1 : 0][n];
;                         if (m < 3 && fr == 0) sn = acc[ai][bj][m < 3 ? m + 1 : 3][n];
;                         f32x4 pv, nv;
;                         dpp_rot4<0>(pv, sp); dpp_rot4<1>(nv, sn);
;                         if (m == 0 && fr == 0) pv = eprev;
;                         if (m == 3 && fr == 15) nv = enext;
;                         if (!hp) pv = (f32x4){0.f, 0.f, 0.f, 0.f};
;                         if (!hn) nv = (f32x4){0.f, 0.f, 0.f, 0.f};
;                         const f32x4 uu = pv * w0 + acc[ai][bj][m][n] * w1 + nv * w2 + bb;
;                         if (bj == 0) { ga[m][0] = gelu_tanh(uu[0]); ga[m][1] = gelu_tanh(uu[1]); ga[m][2] = gelu_tanh(uu[2]); ga[m][3] = gelu_tanh(uu[3]); }
;                         else ga[m] = ga[m] * uu;
;                         asm volatile("" : "+v"(ga[m][0]), "+v"(ga[m][1]), "+v"(ga[m][2]), "+v"(ga[m][3]));
;                     }
;                 }
	v_cndmask_b32_e32 v136, v144, v136, vcc
	v_cndmask_b32_e32 v137, v145, v137, vcc
	v_cndmask_b32_e32 v134, v142, v134, vcc
	v_cndmask_b32_e32 v135, v143, v135, vcc
	v_pk_mul_f32 v[136:137], v[114:115], v[136:137]
	v_pk_mul_f32 v[134:135], v[112:113], v[134:135]
	s_nop 1
	v_mov_b32_dpp v146, v138 row_ror:15 row_mask:0xf bank_mask:0xf
	v_mov_b32_dpp v147, v139 row_ror:15 row_mask:0xf bank_mask:0xf
	v_mov_b32_dpp v148, v140 row_ror:15 row_mask:0xf bank_mask:0xf
	v_mov_b32_dpp v149, v141 row_ror:15 row_mask:0xf bank_mask:0xf
	v_pk_fma_f32 v[136:137], v[90:91], v[106:107], v[136:137]
	v_pk_fma_f32 v[134:135], v[88:89], v[104:105], v[134:135]
	v_pk_fma_f32 v[136:137], v[102:103], v[148:149], v[136:137]
	v_pk_fma_f32 v[134:135], v[100:101], v[146:147], v[134:135]
	v_cndmask_b32_e64 v88, v92, v88, s[42:43]
	v_pk_add_f32 v[138:139], v[96:97], v[134:135]
	v_pk_add_f32 v[134:135], v[98:99], v[136:137]
	v_mul_f32_e32 v137, v138, v138
	v_mul_f32_e32 v136, v135, v135
	v_mul_f32_e32 v140, v139, v139
	v_mul_f32_e32 v141, v134, v134
	v_fmamk_f32 v136, v136, 0xbdd2d3e7, v198
	v_fmamk_f32 v137, v137, 0xbdd2d3e7, v198
	v_fmamk_f32 v140, v140, 0xbdd2d3e7, v198
	v_fmamk_f32 v141, v141, 0xbdd2d3e7, v198
	v_mul_f32_e32 v136, v135, v136
	v_mul_f32_e32 v137, v138, v137
	v_mul_f32_e32 v140, v139, v140
	v_mul_f32_e32 v141, v134, v141
	v_exp_f32_e32 v136, v136
	v_exp_f32_e32 v137, v137
	v_exp_f32_e32 v140, v140
	v_exp_f32_e32 v141, v141
	v_add_f32_e32 v136, 1.0, v136
	v_add_f32_e32 v137, 1.0, v137
	v_add_f32_e32 v140, 1.0, v140
	v_add_f32_e32 v141, 1.0, v141
	v_rcp_f32_e32 v136, v136
	v_rcp_f32_e32 v137, v137
	v_rcp_f32_e32 v140, v140
	v_rcp_f32_e32 v141, v141
	v_cndmask_b32_e64 v89, v93, v89, s[42:43]
	v_cndmask_b32_e64 v90, v94, v90, s[42:43]
	v_cndmask_b32_e64 v91, v95, v91, s[42:43]
	s_nop 1
	v_mov_b32_dpp v142, v88 row_ror:1 row_mask:0xf bank_mask:0xf
	v_mov_b32_dpp v143, v89 row_ror:1 row_mask:0xf bank_mask:0xf
	v_mov_b32_dpp v144, v90 row_ror:1 row_mask:0xf bank_mask:0xf
	v_mov_b32_dpp v145, v91 row_ror:1 row_mask:0xf bank_mask:0xf
	v_mul_f32_e32 v135, v135, v136
	v_mul_f32_e32 v136, v138, v137
	v_mul_f32_e32 v137, v139, v140
	v_mul_f32_e32 v134, v134, v141
	v_cndmask_b32_e32 v138, v92, v84, vcc
	v_cndmask_b32_e32 v139, v93, v85, vcc
	v_cndmask_b32_e32 v140, v94, v86, vcc
	v_cndmask_b32_e32 v141, v95, v87, vcc
	v_pk_mul_f32 v[90:91], v[114:115], v[144:145]
	v_pk_mul_f32 v[88:89], v[112:113], v[142:143]
	s_nop 1
	v_mov_b32_dpp v146, v138 row_ror:15 row_mask:0xf bank_mask:0xf
	v_mov_b32_dpp v147, v139 row_ror:15 row_mask:0xf bank_mask:0xf
	v_mov_b32_dpp v148, v140 row_ror:15 row_mask:0xf bank_mask:0xf
	v_mov_b32_dpp v149, v141 row_ror:15 row_mask:0xf bank_mask:0xf
	v_pk_fma_f32 v[90:91], v[94:95], v[106:107], v[90:91]
	v_pk_fma_f32 v[88:89], v[92:93], v[104:105], v[88:89]
	v_pk_fma_f32 v[90:91], v[102:103], v[148:149], v[90:91]
	v_pk_fma_f32 v[88:89], v[100:101], v[146:147], v[88:89]
	v_cndmask_b32_e64 v92, v84, v92, s[42:43]
	v_pk_add_f32 v[138:139], v[96:97], v[88:89]
	v_pk_add_f32 v[88:89], v[98:99], v[90:91]
	v_mul_f32_e32 v91, v138, v138
	v_mul_f32_e32 v90, v89, v89
	v_mul_f32_e32 v140, v139, v139
	v_fmamk_f32 v90, v90, 0xbdd2d3e7, v198
	v_fmamk_f32 v91, v91, 0xbdd2d3e7, v198
	v_fmamk_f32 v140, v140, 0xbdd2d3e7, v198
	v_mul_f32_e32 v141, v88, v88
	v_mul_f32_e32 v90, v89, v90
	v_mul_f32_e32 v91, v138, v91
	v_mul_f32_e32 v140, v139, v140
	v_fmamk_f32 v141, v141, 0xbdd2d3e7, v198
	v_exp_f32_e32 v90, v90
	v_exp_f32_e32 v91, v91
	v_exp_f32_e32 v140, v140
	v_mul_f32_e32 v141, v88, v141
	v_exp_f32_e32 v141, v141
	v_add_f32_e32 v90, 1.0, v90
	v_add_f32_e32 v91, 1.0, v91
	v_add_f32_e32 v140, 1.0, v140
	v_rcp_f32_e32 v90, v90
	v_rcp_f32_e32 v91, v91
	v_rcp_f32_e32 v140, v140
	v_add_f32_e32 v141, 1.0, v141
	v_rcp_f32_e32 v141, v141
	v_cndmask_b32_e64 v93, v85, v93, s[42:43]
	v_cndmask_b32_e64 v94, v86, v94, s[42:43]
	v_cndmask_b32_e64 v95, v87, v95, s[42:43]
	s_nop 1
	v_mov_b32_dpp v142, v92 row_ror:1 row_mask:0xf bank_mask:0xf
	v_mov_b32_dpp v143, v93 row_ror:1 row_mask:0xf bank_mask:0xf
	v_mov_b32_dpp v144, v94 row_ror:1 row_mask:0xf bank_mask:0xf
	v_mov_b32_dpp v145, v95 row_ror:1 row_mask:0xf bank_mask:0xf
	v_mul_f32_e32 v89, v89, v90
	v_mul_f32_e32 v90, v138, v91
	v_mul_f32_e32 v91, v139, v140
	v_cndmask_b32_e32 v138, v84, v80, vcc
	v_cndmask_b32_e32 v139, v85, v81, vcc
	v_pk_mul_f32 v[92:93], v[112:113], v[142:143]
	v_mul_f32_e32 v88, v88, v141
	v_cndmask_b32_e32 v140, v86, v82, vcc
	v_cndmask_b32_e32 v141, v87, v83, vcc
	s_nop 1
	v_mov_b32_dpp v146, v138 row_ror:15 row_mask:0xf bank_mask:0xf
	v_mov_b32_dpp v147, v139 row_ror:15 row_mask:0xf bank_mask:0xf
	v_mov_b32_dpp v148, v140 row_ror:15 row_mask:0xf bank_mask:0xf
	v_mov_b32_dpp v149, v141 row_ror:15 row_mask:0xf bank_mask:0xf
	v_pk_fma_f32 v[92:93], v[84:85], v[104:105], v[92:93]
	v_pk_mul_f32 v[94:95], v[114:115], v[144:145]
	v_pk_fma_f32 v[92:93], v[100:101], v[146:147], v[92:93]
	v_pk_fma_f32 v[94:95], v[86:87], v[106:107], v[94:95]
	v_pk_add_f32 v[92:93], v[96:97], v[92:93]
	v_pk_fma_f32 v[94:95], v[102:103], v[148:149], v[94:95]
	v_mul_f32_e32 v139, v92, v92
	v_pk_add_f32 v[94:95], v[98:99], v[94:95]
	v_fmamk_f32 v139, v139, 0xbdd2d3e7, v198
	v_mul_f32_e32 v140, v93, v93
	v_mul_f32_e32 v138, v95, v95
	v_mul_f32_e32 v139, v92, v139
	v_fmamk_f32 v140, v140, 0xbdd2d3e7, v198
	v_mul_f32_e32 v141, v94, v94
	v_fmamk_f32 v138, v138, 0xbdd2d3e7, v198
	v_exp_f32_e32 v139, v139
	v_mul_f32_e32 v140, v93, v140
	v_fmamk_f32 v141, v141, 0xbdd2d3e7, v198
	v_mul_f32_e32 v138, v95, v138
	v_exp_f32_e32 v140, v140
	v_mul_f32_e32 v141, v94, v141
	v_exp_f32_e32 v138, v138
	v_exp_f32_e32 v141, v141
	v_add_f32_e32 v139, 1.0, v139
	v_rcp_f32_e32 v142, v139
	v_add_f32_e32 v139, 1.0, v140
	v_add_f32_e32 v138, 1.0, v138
	v_rcp_f32_e32 v143, v139
	v_add_f32_e32 v139, 1.0, v141
	v_rcp_f32_e32 v138, v138
	v_rcp_f32_e32 v144, v139
	v_cndmask_b32_e64 v84, v80, v84, s[42:43]
	v_cndmask_b32_e64 v85, v81, v85, s[42:43]
	v_cndmask_b32_e64 v86, v82, v86, s[42:43]
	v_cndmask_b32_e64 v87, v83, v87, s[42:43]
	v_mul_f32_e32 v139, v95, v138
	v_mul_f32_e32 v140, v92, v142
	v_mul_f32_e32 v141, v93, v143
	v_mul_f32_e32 v138, v94, v144
	s_nop 1
	v_mov_b32_dpp v92, v84 row_ror:1 row_mask:0xf bank_mask:0xf
	v_mov_b32_dpp v93, v85 row_ror:1 row_mask:0xf bank_mask:0xf
	v_mov_b32_dpp v94, v86 row_ror:1 row_mask:0xf bank_mask:0xf
	v_mov_b32_dpp v95, v87 row_ror:1 row_mask:0xf bank_mask:0xf
	s_nop 1
	v_mov_b32_dpp v142, v80 row_ror:15 row_mask:0xf bank_mask:0xf
	v_mov_b32_dpp v143, v81 row_ror:15 row_mask:0xf bank_mask:0xf
	v_mov_b32_dpp v144, v82 row_ror:15 row_mask:0xf bank_mask:0xf
	v_mov_b32_dpp v145, v83 row_ror:15 row_mask:0xf bank_mask:0xf
	v_ashrrev_i32_e32 v161, 31, v160
	v_pk_mul_f32 v[86:87], v[114:115], v[94:95]
	v_pk_mul_f32 v[84:85], v[112:113], v[92:93]
	v_pk_fma_f32 v[82:83], v[82:83], v[106:107], v[86:87]
	v_pk_fma_f32 v[80:81], v[80:81], v[104:105], v[84:85]
	s_waitcnt lgkmcnt(0)
;     DI void operator()(const f32x4 (&acc)[2][2][4][2], const Unit& u, int wr, int wc, int fr_in, int fq_in) const {
;     ...
;                     const LAS float* wp = wlb + 128 * bj + qpos + 4 * n;
;                     const f32x4 w0 = *(const LAS f32x4*)(wp), w1 = *(const LAS f32x4*)(wp + 256), w2 = *(const LAS f32x4*)(wp + 512), bb = *(const LAS f32x4*)(wp + 768);
;                     const f32x4 eprev = *(const LAS f32x4*)(exb + (((blk + 3) & 3) * 2 + 1) * 256 + 128 * bj + qpos + 4 * n);
;                     const f32x4 enext = *(const LAS f32x4*)(exb + (((blk + 1) & 3) * 2 + 0) * 256 + 128 * bj + qpos + 4 * n);
; #pragma unroll
;                     for (int m = 0; m < 4; ++m) {
;                         const int g = 254 * u.pm - 1 + tr0 + 16 * m;
;                         const int lmask = (g < NLAT) ? (T - 1) : (CL - 1);
;                         const bool hp = (g & lmask) != 0, hn = ((g + 1) & lmask) != 0;
;                         f32x4 sp = acc[ai][bj][m][n], sn = acc[ai][bj][m][n];
;                         if (m > 0 && fr == 15) sp = acc[ai][bj][m > 0 ? m - 1 : 0][n];
;                         if (m < 3 && fr == 0) sn = acc[ai][bj][m < 3 ? m + 1 : 3][n];
;                         f32x4 pv, nv;
;                         dpp_rot4<0>(pv, sp); dpp_rot4<1>(nv, sn);
;                         if (m == 0 && fr == 0) pv = eprev;
;                         if (m == 3 && fr == 15) nv = enext;
;                         if (!hp) pv = (f32x4){0.f, 0.f, 0.f, 0.f};
;                         if (!hn) nv = (f32x4){0.f, 0.f, 0.f, 0.f};
;                         const f32x4 uu = pv * w0 + acc[ai][bj][m][n] * w1 + nv * w2 + bb;
;                         if (bj == 0) { ga[m][0] = gelu_tanh(uu[0]); ga[m][1] = gelu_tanh(uu[1]); ga[m][2] = gelu_tanh(uu[2]); ga[m][3] = gelu_tanh(uu[3]); }
;                         else ga[m] = ga[m] * uu;
;                         asm volatile("" : "+v"(ga[m][0]), "+v"(ga[m][1]), "+v"(ga[m][2]), "+v"(ga[m][3]));
;                     }
;                 }
; #pragma unroll
;                 for (int m = 0; m < 4; ++m) {
;                     const int tr = tr0 + 16 * m;
;                     const int g = 254 * u.pm - 1 + tr;
;                     u32x2 w; w.x = pack2(ga[m][0], ga[m][1]); w.y = pack2(ga[m][2], ga[m][3]);
;                     if (n == 0) pk0[m] = w;
;                     else if (tr >= 1 && tr <= 254 && g < nrows) {
	v_cndmask_b32_e64 v86, v144, v110, s[42:43]
	v_cndmask_b32_e64 v87, v145, v111, s[42:43]
	v_cndmask_b32_e64 v84, v142, v108, s[42:43]
	v_cndmask_b32_e64 v85, v143, v109, s[42:43]
	v_pk_fma_f32 v[82:83], v[102:103], v[86:87], v[82:83]
	v_pk_fma_f32 v[80:81], v[100:101], v[84:85], v[80:81]
	v_pk_add_f32 v[82:83], v[98:99], v[82:83]
	v_pk_add_f32 v[80:81], v[96:97], v[80:81]
	v_mul_f32_e32 v84, v83, v83
	v_mul_f32_e32 v85, v80, v80
	v_mul_f32_e32 v86, v81, v81
	v_mul_f32_e32 v87, v82, v82
	v_fmamk_f32 v84, v84, 0xbdd2d3e7, v198
	v_fmamk_f32 v85, v85, 0xbdd2d3e7, v198
	v_fmamk_f32 v86, v86, 0xbdd2d3e7, v198
	v_fmamk_f32 v87, v87, 0xbdd2d3e7, v198
	v_mul_f32_e32 v84, v83, v84
	v_mul_f32_e32 v85, v80, v85
	v_mul_f32_e32 v86, v81, v86
	v_mul_f32_e32 v87, v82, v87
	v_exp_f32_e32 v84, v84
	v_exp_f32_e32 v85, v85
	v_exp_f32_e32 v86, v86
	v_exp_f32_e32 v87, v87
	v_add_f32_e32 v84, 1.0, v84
	v_add_f32_e32 v85, 1.0, v85
	v_add_f32_e32 v86, 1.0, v86
	v_add_f32_e32 v87, 1.0, v87
	v_rcp_f32_e32 v84, v84
	v_rcp_f32_e32 v85, v85
	v_rcp_f32_e32 v86, v86
	v_rcp_f32_e32 v87, v87
	v_mul_f32_e32 v109, v83, v84
	v_mul_f32_e32 v110, v80, v85
	v_mul_f32_e32 v111, v81, v86
	v_mul_f32_e32 v108, v82, v87
	ds_read_b128 v[84:87], v179 offset:528
	ds_read_b128 v[92:95], v179 offset:1552
	ds_read_b128 v[96:99], v179 offset:2576
	ds_read_b128 v[100:103], v179 offset:3600
	ds_read_b128 v[80:83], v191 offset:1552
	ds_read_b128 v[104:107], v192 offset:528
	v_cndmask_b32_e32 v112, v72, v76, vcc
	v_cndmask_b32_e32 v113, v73, v77, vcc
	v_cndmask_b32_e32 v114, v74, v78, vcc
	v_cndmask_b32_e32 v115, v75, v79, vcc
	s_nop 1
	v_mov_b32_dpp v142, v72 row_ror:1 row_mask:0xf bank_mask:0xf
	v_mov_b32_dpp v143, v73 row_ror:1 row_mask:0xf bank_mask:0xf
	v_mov_b32_dpp v144, v74 row_ror:1 row_mask:0xf bank_mask:0xf
	v_mov_b32_dpp v145, v75 row_ror:1 row_mask:0xf bank_mask:0xf
	s_nop 1
	v_mov_b32_dpp v146, v112 row_ror:15 row_mask:0xf bank_mask:0xf
	v_mov_b32_dpp v147, v113 row_ror:15 row_mask:0xf bank_mask:0xf
	v_mov_b32_dpp v148, v114 row_ror:15 row_mask:0xf bank_mask:0xf
	v_mov_b32_dpp v149, v115 row_ror:15 row_mask:0xf bank_mask:0xf
	s_waitcnt lgkmcnt(1)
	v_cndmask_b32_e32 v112, v142, v80, vcc
	v_cndmask_b32_e32 v113, v143, v81, vcc
	v_cndmask_b32_e32 v80, v144, v82, vcc
	v_cndmask_b32_e32 v81, v145, v83, vcc
	v_pk_mul_f32 v[82:83], v[84:85], v[112:113]
	v_pk_mul_f32 v[80:81], v[86:87], v[80:81]
	v_pk_fma_f32 v[82:83], v[72:73], v[92:93], v[82:83]
	v_pk_fma_f32 v[80:81], v[74:75], v[94:95], v[80:81]
	v_pk_fma_f32 v[82:83], v[96:97], v[146:147], v[82:83]
	v_pk_fma_f32 v[80:81], v[98:99], v[148:149], v[80:81]
	v_cndmask_b32_e64 v72, v76, v72, s[42:43]
	v_pk_add_f32 v[112:113], v[102:103], v[80:81]
	v_pk_add_f32 v[80:81], v[100:101], v[82:83]
	v_cndmask_b32_e64 v73, v77, v73, s[42:43]
	v_pk_mul_f32 v[80:81], v[136:137], v[80:81]
	v_pk_mul_f32 v[82:83], v[134:135], v[112:113]
	v_cndmask_b32_e64 v74, v78, v74, s[42:43]
	v_cndmask_b32_e64 v75, v79, v75, s[42:43]
	s_nop 1
	v_mov_b32_dpp v134, v72 row_ror:1 row_mask:0xf bank_mask:0xf
	v_mov_b32_dpp v135, v73 row_ror:1 row_mask:0xf bank_mask:0xf
	v_mov_b32_dpp v136, v74 row_ror:1 row_mask:0xf bank_mask:0xf
	v_mov_b32_dpp v137, v75 row_ror:1 row_mask:0xf bank_mask:0xf
	v_cndmask_b32_e32 v112, v76, v68, vcc
	v_cndmask_b32_e32 v113, v77, v69, vcc
	v_pk_mul_f32 v[72:73], v[86:87], v[136:137]
	v_cndmask_b32_e32 v114, v78, v70, vcc
	v_cndmask_b32_e32 v115, v79, v71, vcc
	s_nop 1
	v_mov_b32_dpp v142, v112 row_ror:15 row_mask:0xf bank_mask:0xf
	v_mov_b32_dpp v143, v113 row_ror:15 row_mask:0xf bank_mask:0xf
	v_mov_b32_dpp v144, v114 row_ror:15 row_mask:0xf bank_mask:0xf
	v_mov_b32_dpp v145, v115 row_ror:15 row_mask:0xf bank_mask:0xf
	v_pk_mul_f32 v[74:75], v[84:85], v[134:135]
	v_pk_fma_f32 v[72:73], v[78:79], v[94:95], v[72:73]
	v_pk_fma_f32 v[74:75], v[76:77], v[92:93], v[74:75]
	v_pk_fma_f32 v[72:73], v[98:99], v[144:145], v[72:73]
	v_pk_fma_f32 v[74:75], v[96:97], v[142:143], v[74:75]
	v_pk_add_f32 v[112:113], v[102:103], v[72:73]
	v_cndmask_b32_e64 v76, v68, v76, s[42:43]
	v_cndmask_b32_e64 v77, v69, v77, s[42:43]
	v_pk_add_f32 v[72:73], v[100:101], v[74:75]
	v_pk_mul_f32 v[74:75], v[88:89], v[112:113]
	v_cndmask_b32_e64 v78, v70, v78, s[42:43]
	v_cndmask_b32_e64 v79, v71, v79, s[42:43]
	s_nop 1
	v_mov_b32_dpp v112, v76 row_ror:1 row_mask:0xf bank_mask:0xf
	v_mov_b32_dpp v113, v77 row_ror:1 row_mask:0xf bank_mask:0xf
	v_mov_b32_dpp v114, v78 row_ror:1 row_mask:0xf bank_mask:0xf
	v_mov_b32_dpp v115, v79 row_ror:1 row_mask:0xf bank_mask:0xf
	v_cndmask_b32_e32 v88, v68, v64, vcc
	v_cndmask_b32_e32 v89, v69, v65, vcc
	v_pk_mul_f32 v[76:77], v[86:87], v[114:115]
	v_pk_mul_f32 v[72:73], v[90:91], v[72:73]
	v_cndmask_b32_e32 v90, v70, v66, vcc
	v_cndmask_b32_e32 v91, v71, v67, vcc
	s_nop 1
	v_mov_b32_dpp v134, v88 row_ror:15 row_mask:0xf bank_mask:0xf
	v_mov_b32_dpp v135, v89 row_ror:15 row_mask:0xf bank_mask:0xf
	v_mov_b32_dpp v136, v90 row_ror:15 row_mask:0xf bank_mask:0xf
	v_mov_b32_dpp v137, v91 row_ror:15 row_mask:0xf bank_mask:0xf
	v_pk_mul_f32 v[78:79], v[84:85], v[112:113]
	v_pk_fma_f32 v[76:77], v[70:71], v[94:95], v[76:77]
	v_pk_fma_f32 v[78:79], v[68:69], v[92:93], v[78:79]
	v_pk_fma_f32 v[76:77], v[98:99], v[136:137], v[76:77]
	v_pk_fma_f32 v[78:79], v[96:97], v[134:135], v[78:79]
	v_pk_add_f32 v[88:89], v[102:103], v[76:77]
	v_cndmask_b32_e64 v68, v64, v68, s[42:43]
	v_cndmask_b32_e64 v69, v65, v69, s[42:43]
	v_cndmask_b32_e64 v70, v66, v70, s[42:43]
	v_cndmask_b32_e64 v71, v67, v71, s[42:43]
	v_pk_add_f32 v[76:77], v[100:101], v[78:79]
	v_pk_mul_f32 v[78:79], v[138:139], v[88:89]
	s_nop 1
	v_mov_b32_dpp v88, v68 row_ror:1 row_mask:0xf bank_mask:0xf
	v_mov_b32_dpp v89, v69 row_ror:1 row_mask:0xf bank_mask:0xf
	v_mov_b32_dpp v90, v70 row_ror:1 row_mask:0xf bank_mask:0xf
	v_mov_b32_dpp v91, v71 row_ror:1 row_mask:0xf bank_mask:0xf
	s_nop 1
	v_mov_b32_dpp v112, v64 row_ror:15 row_mask:0xf bank_mask:0xf
	v_mov_b32_dpp v113, v65 row_ror:15 row_mask:0xf bank_mask:0xf
	v_mov_b32_dpp v114, v66 row_ror:15 row_mask:0xf bank_mask:0xf
	v_mov_b32_dpp v115, v67 row_ror:15 row_mask:0xf bank_mask:0xf
	v_cmp_gt_i32_e64 s[44:45], s61, v183
	v_pk_mul_f32 v[70:71], v[86:87], v[90:91]
	v_pk_mul_f32 v[68:69], v[84:85], v[88:89]
	v_pk_fma_f32 v[66:67], v[66:67], v[94:95], v[70:71]
	v_pk_fma_f32 v[64:65], v[64:65], v[92:93], v[68:69]
	s_waitcnt lgkmcnt(0)
	v_cndmask_b32_e64 v70, v114, v106, s[42:43]
	v_cndmask_b32_e64 v71, v115, v107, s[42:43]
	v_cndmask_b32_e64 v68, v112, v104, s[42:43]
	v_cndmask_b32_e64 v69, v113, v105, s[42:43]
	v_pk_fma_f32 v[66:67], v[98:99], v[70:71], v[66:67]
	v_pk_fma_f32 v[64:65], v[96:97], v[68:69], v[64:65]
	v_pk_mul_f32 v[76:77], v[140:141], v[76:77]
	v_pk_add_f32 v[68:69], v[100:101], v[64:65]
	v_pk_add_f32 v[64:65], v[102:103], v[66:67]
	v_pk_mul_f32 v[66:67], v[110:111], v[68:69]
	v_pk_mul_f32 v[64:65], v[108:109], v[64:65]
	s_and_b64 s[44:45], s[0:1], s[44:45]
	s_and_saveexec_b64 s[0:1], s[44:45]
	s_cbranch_execz .Lfp_97
; DI unsigned pack2(float lo, float hi) { f32x2 v = {lo, hi}; bf16x2_t b = __builtin_convertvector(v, bf16x2_t); return __builtin_bit_cast(unsigned, b); }
;     DI void operator()(const f32x4 (&acc)[2][2][4][2], const Unit& u, int wr, int wc, int fr_in, int fq_in) const {
;     ...
;                     u32x2 w; w.x = pack2(ga[m][0], ga[m][1]); w.y = pack2(ga[m][2], ga[m][3]);
;                     if (n == 0) pk0[m] = w;
;                     else if (tr >= 1 && tr <= 254 && g < nrows) {
;                         u32x4 w4; w4.x = pk0[m].x; w4.y = pk0[m].y; w4.z = w.x; w4.w = w.y;
;                         __builtin_nontemporal_store(w4, (u32x4*)(G + (size_t)g * DFF + ch));
	v_cvt_pk_bf16_f32 v70, v80, v81
	v_mov_b64_e32 v[80:81], s[82:83]
	s_movk_i32 s33, 0x1500
	v_mad_i64_i32 v[80:81], s[44:45], v183, s33, v[80:81]
	v_cvt_pk_bf16_f32 v71, v82, v83
	v_cvt_pk_bf16_f32 v68, v116, v117
	v_cvt_pk_bf16_f32 v69, v118, v119
	v_lshl_add_u64 v[80:81], v[160:161], 1, v[80:81]
	global_store_dwordx4 v[80:81], v[68:71], off nt

; #define LAS __attribute__((address_space(3)))
;     DI void operator()(const f32x4 (&acc)[2][2][4][2], const Unit& u, int wr, int wc, int fr_in, int fq_in) const {
;     ...
;         for (int ai = 0; ai < 2; ++ai) {
;             const int blk = 2 * ai + wr;
;             const int tr0 = 128 * ai + 64 * wr + fr;
;             u32x2 pk0[4];
; #pragma unroll
;             for (int n = 0; n < 2; ++n) {
;                 f32x4 ga[4];
; #pragma unroll
;                 for (int bj = 0; bj < 2; ++bj) {
;                     const LAS float* wp = wlb + 128 * bj + qpos + 4 * n;
;                     const f32x4 w0 = *(const LAS f32x4*)(wp), w1 = *(const LAS f32x4*)(wp + 256), w2 = *(const LAS f32x4*)(wp + 512), bb = *(const LAS f32x4*)(wp + 768);
;                     const f32x4 eprev = *(const LAS f32x4*)(exb + (((blk + 3) & 3) * 2 + 1) * 256 + 128 * bj + qpos + 4 * n);
;                     const f32x4 enext = *(const LAS f32x4*)(exb + (((blk + 1) & 3) * 2 + 0) * 256 + 128 * bj + qpos + 4 * n);
; #pragma unroll
;                     for (int m = 0; m < 4; ++m) {
;                         const int g = 254 * u.pm - 1 + tr0 + 16 * m;
;                         const int lmask = (g < NLAT) ? (T - 1) : (CL - 1);
;                         const bool hp = (g & lmask) != 0, hn = ((g + 1) & lmask) != 0;
;                         f32x4 sp = acc[ai][bj][m][n], sn = acc[ai][bj][m][n];
;                         if (m > 0 && fr == 15) sp = acc[ai][bj][m > 0 ? m - 1 : 0][n];
;                         if (m < 3 && fr == 0) sn = acc[ai][bj][m < 3 ? m + 1 : 3][n];
;                         f32x4 pv, nv;
;                         dpp_rot4<0>(pv, sp); dpp_rot4<1>(nv, sn);
;                         if (m == 0 && fr == 0) pv = eprev;
;                         if (m == 3 && fr == 15) nv = enext;
;                         if (!hp) pv = (f32x4){0.f, 0.f, 0.f, 0.f};
;                         if (!hn) nv = (f32x4){0.f, 0.f, 0.f, 0.f};
;                         const f32x4 uu = pv * w0 + acc[ai][bj][m][n] * w1 + nv * w2 + bb;
;                         if (bj == 0) { ga[m][0] = gelu_tanh(uu[0]); ga[m][1] = gelu_tanh(uu[1]); ga[m][2] = gelu_tanh(uu[2]); ga[m][3] = gelu_tanh(uu[3]); }
;                         else ga[m] = ga[m] * uu;
.Lfp_103:
	s_or_b64 exec, exec, s[0:1]
	v_readlane_b32 s0, v254, 50
	s_lshl_b32 s0, s0, 2
	s_add_i32 s38, s38, s0
	v_readlane_b32 s0, v254, 18
	v_add_u32_e32 v93, 0x7f, v180
	v_lshl_add_u32 v100, v181, 2, s38
	v_lshl_add_u32 v101, s0, 2, v182
	ds_read_b128 v[80:83], v179
	ds_read_b128 v[72:75], v179 offset:1024
	ds_read_b128 v[68:71], v179 offset:2048
	ds_read_b128 v[64:67], v179 offset:3072
	ds_read_b128 v[84:87], v100 offset:1024
	ds_read_b128 v[76:79], v101
	v_add_u32_e32 v92, s65, v93
	s_mov_b32 s38, 0x10000
	v_cmp_gt_i32_e64 s[0:1], s38, v92
	v_add_u32_e32 v90, 1, v92
	s_nop 1
	v_mov_b32_dpp v96, v60 row_ror:1 row_mask:0xf bank_mask:0xf
	v_mov_b32_dpp v97, v61 row_ror:1 row_mask:0xf bank_mask:0xf
	v_mov_b32_dpp v98, v62 row_ror:1 row_mask:0xf bank_mask:0xf
	v_mov_b32_dpp v99, v63 row_ror:1 row_mask:0xf bank_mask:0xf
	v_cndmask_b32_e32 v91, v61, v57, vcc
	v_cndmask_b32_e64 v88, v204, v205, s[0:1]
	v_and_b32_e32 v89, v88, v92
	s_waitcnt lgkmcnt(1)
	v_cndmask_b32_e32 v86, v98, v86, vcc
	v_cndmask_b32_e32 v87, v99, v87, vcc
	v_cndmask_b32_e32 v84, v96, v84, vcc
	v_cndmask_b32_e32 v85, v97, v85, vcc
	v_cmp_eq_u32_e64 s[44:45], 0, v89
	v_and_b32_e32 v88, v88, v90
	v_cndmask_b32_e32 v90, v60, v56, vcc
	v_pk_mul_f32 v[86:87], v[82:83], v[86:87]
	v_pk_mul_f32 v[84:85], v[80:81], v[84:85]
	v_cmp_eq_u32_e64 s[46:47], 0, v88
	v_cndmask_b32_e32 v94, v62, v58, vcc
	v_cndmask_b32_e32 v95, v63, v59, vcc
	s_nop 1
	v_mov_b32_dpp v102, v90 row_ror:15 row_mask:0xf bank_mask:0xf
	v_mov_b32_dpp v103, v91 row_ror:15 row_mask:0xf bank_mask:0xf
	v_mov_b32_dpp v104, v94 row_ror:15 row_mask:0xf bank_mask:0xf
	v_mov_b32_dpp v105, v95 row_ror:15 row_mask:0xf bank_mask:0xf
	v_pk_fma_f32 v[84:85], v[60:61], v[72:73], v[84:85]
	v_pk_fma_f32 v[86:87], v[62:63], v[74:75], v[86:87]
	v_pk_fma_f32 v[86:87], v[70:71], v[104:105], v[86:87]
	v_pk_fma_f32 v[84:85], v[68:69], v[102:103], v[84:85]
	v_add_u32_e32 v95, 0x8f, v180
	v_pk_add_f32 v[88:89], v[64:65], v[84:85]
	v_pk_add_f32 v[84:85], v[66:67], v[86:87]
	v_mul_f32_e32 v87, v88, v88
	v_mul_f32_e32 v86, v85, v85
	v_fmamk_f32 v86, v86, 0xbdd2d3e7, v198
	v_fmamk_f32 v87, v87, 0xbdd2d3e7, v198
	v_mul_f32_e32 v90, v89, v89
	v_mul_f32_e32 v86, v85, v86
	v_mul_f32_e32 v87, v88, v87
	v_fmamk_f32 v90, v90, 0xbdd2d3e7, v198
	v_exp_f32_e32 v86, v86
	v_exp_f32_e32 v87, v87
	v_mul_f32_e32 v90, v89, v90
	v_exp_f32_e32 v90, v90
	v_mul_f32_e32 v91, v84, v84
	v_fmamk_f32 v91, v91, 0xbdd2d3e7, v198
	v_mul_f32_e32 v91, v84, v91
	v_add_f32_e32 v86, 1.0, v86
	v_add_f32_e32 v87, 1.0, v87
	v_exp_f32_e32 v91, v91
	v_rcp_f32_e32 v86, v86
	v_rcp_f32_e32 v87, v87
	v_add_f32_e32 v90, 1.0, v90
	v_rcp_f32_e32 v90, v90
	v_add_u32_e32 v94, s65, v95
	v_add_f32_e32 v91, 1.0, v91
	v_cmp_gt_i32_e64 s[0:1], s38, v94
	v_rcp_f32_e32 v91, v91
	v_mul_f32_e32 v85, v85, v86
	v_mul_f32_e32 v86, v88, v87
	v_cndmask_b32_e64 v88, v204, v205, s[0:1]
	v_mul_f32_e32 v87, v89, v90
	v_and_b32_e32 v89, v88, v94
	v_add_u32_e32 v90, 1, v94
	v_cndmask_b32_e64 v60, v56, v60, s[42:43]
	v_cndmask_b32_e64 v61, v57, v61, s[42:43]
	v_cndmask_b32_e64 v62, v58, v62, s[42:43]
	v_cndmask_b32_e64 v63, v59, v63, s[42:43]
	v_cmp_eq_u32_e64 s[48:49], 0, v89
	v_and_b32_e32 v88, v88, v90
	s_nop 1
	v_mov_b32_dpp v98, v60 row_ror:1 row_mask:0xf bank_mask:0xf
	v_mov_b32_dpp v99, v61 row_ror:1 row_mask:0xf bank_mask:0xf
	v_mov_b32_dpp v102, v62 row_ror:1 row_mask:0xf bank_mask:0xf
	v_mov_b32_dpp v103, v63 row_ror:1 row_mask:0xf bank_mask:0xf
	v_mul_f32_e32 v84, v84, v91
	v_cndmask_b32_e32 v90, v56, v52, vcc
	v_cndmask_b32_e32 v91, v57, v53, vcc
	v_pk_mul_f32 v[62:63], v[82:83], v[102:103]
	v_pk_mul_f32 v[60:61], v[80:81], v[98:99]
	v_cmp_eq_u32_e64 s[50:51], 0, v88
	v_cndmask_b32_e32 v96, v58, v54, vcc
	v_cndmask_b32_e32 v97, v59, v55, vcc
	s_nop 1
	v_mov_b32_dpp v104, v90 row_ror:15 row_mask:0xf bank_mask:0xf
	v_mov_b32_dpp v105, v91 row_ror:15 row_mask:0xf bank_mask:0xf
	v_mov_b32_dpp v106, v96 row_ror:15 row_mask:0xf bank_mask:0xf
	v_mov_b32_dpp v107, v97 row_ror:15 row_mask:0xf bank_mask:0xf
	v_pk_fma_f32 v[60:61], v[56:57], v[72:73], v[60:61]
	v_pk_fma_f32 v[62:63], v[58:59], v[74:75], v[62:63]
	v_pk_fma_f32 v[62:63], v[70:71], v[106:107], v[62:63]
	v_pk_fma_f32 v[60:61], v[68:69], v[104:105], v[60:61]
	v_add_u32_e32 v97, 0x9f, v180
	v_pk_add_f32 v[88:89], v[64:65], v[60:61]
	v_pk_add_f32 v[60:61], v[66:67], v[62:63]
	v_mul_f32_e32 v63, v88, v88
	v_mul_f32_e32 v62, v61, v61
	v_fmamk_f32 v62, v62, 0xbdd2d3e7, v198
	v_fmamk_f32 v63, v63, 0xbdd2d3e7, v198
	v_mul_f32_e32 v90, v89, v89
	v_mul_f32_e32 v62, v61, v62
	v_mul_f32_e32 v63, v88, v63
	v_fmamk_f32 v90, v90, 0xbdd2d3e7, v198
	v_exp_f32_e32 v62, v62
	v_exp_f32_e32 v63, v63
	v_mul_f32_e32 v90, v89, v90
	v_exp_f32_e32 v90, v90
	v_mul_f32_e32 v91, v60, v60
	v_fmamk_f32 v91, v91, 0xbdd2d3e7, v198
	v_add_f32_e32 v62, 1.0, v62
	v_add_f32_e32 v63, 1.0, v63
	v_mul_f32_e32 v91, v60, v91
	v_rcp_f32_e32 v62, v62
	v_exp_f32_e32 v91, v91
	v_rcp_f32_e32 v63, v63
	v_add_f32_e32 v90, 1.0, v90
	v_rcp_f32_e32 v90, v90
	v_add_u32_e32 v96, s65, v97
	v_cmp_gt_i32_e64 s[0:1], s38, v96
	v_add_f32_e32 v91, 1.0, v91
	v_mul_f32_e32 v61, v61, v62
	v_mul_f32_e32 v62, v88, v63
	v_cndmask_b32_e64 v88, v204, v205, s[0:1]
	v_rcp_f32_e32 v91, v91
	v_mul_f32_e32 v63, v89, v90
	v_and_b32_e32 v89, v88, v96
	v_add_u32_e32 v90, 1, v96
	v_cndmask_b32_e64 v56, v52, v56, s[42:43]
	v_cndmask_b32_e64 v57, v53, v57, s[42:43]
	v_cmp_eq_u32_e64 s[52:53], 0, v89
	v_and_b32_e32 v88, v88, v90
	v_cndmask_b32_e64 v58, v54, v58, s[42:43]
	v_cndmask_b32_e64 v59, v55, v59, s[42:43]
	s_nop 1
	v_mov_b32_dpp v102, v56 row_ror:1 row_mask:0xf bank_mask:0xf
	v_mov_b32_dpp v103, v57 row_ror:1 row_mask:0xf bank_mask:0xf
; #define LAS __attribute__((address_space(3)))
;     DI void operator()(const f32x4 (&acc)[2][2][4][2], const Unit& u, int wr, int wc, int fr_in, int fq_in) const {
;     ...
;         for (int ai = 0; ai < 2; ++ai) {
;             const int blk = 2 * ai + wr;
;             const int tr0 = 128 * ai + 64 * wr + fr;
;             u32x2 pk0[4];
; #pragma unroll
;             for (int n = 0; n < 2; ++n) {
;                 f32x4 ga[4];
; #pragma unroll
;                 for (int bj = 0; bj < 2; ++bj) {
;                     const LAS float* wp = wlb + 128 * bj + qpos + 4 * n;
;                     const f32x4 w0 = *(const LAS f32x4*)(wp), w1 = *(const LAS f32x4*)(wp + 256), w2 = *(const LAS f32x4*)(wp + 512), bb = *(const LAS f32x4*)(wp + 768);
;                     const f32x4 eprev = *(const LAS f32x4*)(exb + (((blk + 3) & 3) * 2 + 1) * 256 + 128 * bj + qpos + 4 * n);
;                     const f32x4 enext = *(const LAS f32x4*)(exb + (((blk + 1) & 3) * 2 + 0) * 256 + 128 * bj + qpos + 4 * n);
; #pragma unroll
;                     for (int m = 0; m < 4; ++m) {
;                         const int g = 254 * u.pm - 1 + tr0 + 16 * m;
;                         const int lmask = (g < NLAT) ? (T - 1) : (CL - 1);
;                         const bool hp = (g & lmask) != 0, hn = ((g + 1) & lmask) != 0;
;                         f32x4 sp = acc[ai][bj][m][n], sn = acc[ai][bj][m][n];
;                         if (m > 0 && fr == 15) sp = acc[ai][bj][m > 0 ? m - 1 : 0][n];
;                         if (m < 3 && fr == 0) sn = acc[ai][bj][m < 3 ? m + 1 : 3][n];
;                         f32x4 pv, nv;
;                         dpp_rot4<0>(pv, sp); dpp_rot4<1>(nv, sn);
;                         if (m == 0 && fr == 0) pv = eprev;
;                         if (m == 3 && fr == 15) nv = enext;
;                         if (!hp) pv = (f32x4){0.f, 0.f, 0.f, 0.f};
;                         if (!hn) nv = (f32x4){0.f, 0.f, 0.f, 0.f};
;                         const f32x4 uu = pv * w0 + acc[ai][bj][m][n] * w1 + nv * w2 + bb;
;                         if (bj == 0) { ga[m][0] = gelu_tanh(uu[0]); ga[m][1] = gelu_tanh(uu[1]); ga[m][2] = gelu_tanh(uu[2]); ga[m][3] = gelu_tanh(uu[3]); }
;                         else ga[m] = ga[m] * uu;
;                         asm volatile("" : "+v"(ga[m][0]), "+v"(ga[m][1]), "+v"(ga[m][2]), "+v"(ga[m][3]));
;                     }
;                 }
	v_mov_b32_dpp v104, v58 row_ror:1 row_mask:0xf bank_mask:0xf
	v_mov_b32_dpp v105, v59 row_ror:1 row_mask:0xf bank_mask:0xf
	v_cmp_eq_u32_e64 s[54:55], 0, v88
	v_pk_mul_f32 v[56:57], v[80:81], v[102:103]
	v_mul_f32_e32 v60, v60, v91
	v_cndmask_b32_e32 v90, v52, v48, vcc
	v_cndmask_b32_e32 v91, v53, v49, vcc
	v_cndmask_b32_e32 v98, v54, v50, vcc
	v_cndmask_b32_e32 v99, v55, v51, vcc
	s_nop 1
	v_mov_b32_dpp v106, v90 row_ror:15 row_mask:0xf bank_mask:0xf
	v_mov_b32_dpp v107, v91 row_ror:15 row_mask:0xf bank_mask:0xf
	v_mov_b32_dpp v108, v98 row_ror:15 row_mask:0xf bank_mask:0xf
	v_mov_b32_dpp v109, v99 row_ror:15 row_mask:0xf bank_mask:0xf
	v_pk_fma_f32 v[56:57], v[52:53], v[72:73], v[56:57]
	v_pk_fma_f32 v[56:57], v[68:69], v[106:107], v[56:57]
	v_pk_mul_f32 v[58:59], v[82:83], v[104:105]
	v_pk_add_f32 v[56:57], v[64:65], v[56:57]
	v_pk_fma_f32 v[58:59], v[54:55], v[74:75], v[58:59]
	v_mul_f32_e32 v89, v56, v56
	v_pk_fma_f32 v[58:59], v[70:71], v[108:109], v[58:59]
	v_fmamk_f32 v89, v89, 0xbdd2d3e7, v198
	v_mul_f32_e32 v90, v57, v57
	v_mul_f32_e32 v89, v56, v89
	v_fmamk_f32 v90, v90, 0xbdd2d3e7, v198
	v_exp_f32_e32 v89, v89
	v_mul_f32_e32 v90, v57, v90
	v_exp_f32_e32 v90, v90
	v_pk_add_f32 v[58:59], v[66:67], v[58:59]
	v_add_f32_e32 v89, 1.0, v89
	v_mul_f32_e32 v88, v59, v59
	v_mul_f32_e32 v91, v58, v58
	v_fmamk_f32 v88, v88, 0xbdd2d3e7, v198
	v_fmamk_f32 v91, v91, 0xbdd2d3e7, v198
	v_mul_f32_e32 v88, v59, v88
	v_mul_f32_e32 v91, v58, v91
	v_rcp_f32_e32 v98, v89
	v_add_f32_e32 v89, 1.0, v90
	v_exp_f32_e32 v88, v88
	v_exp_f32_e32 v91, v91
	v_rcp_f32_e32 v99, v89
	v_mul_f32_e32 v90, v56, v98
	v_add_f32_e32 v88, 1.0, v88
	v_add_f32_e32 v89, 1.0, v91
	v_mul_f32_e32 v91, v57, v99
	v_add_u32_e32 v99, 0xaf, v180
	v_rcp_f32_e32 v88, v88
	v_rcp_f32_e32 v102, v89
	v_add_u32_e32 v98, s65, v99
	v_cmp_gt_i32_e64 s[0:1], s38, v98
	v_mul_f32_e32 v89, v59, v88
	v_mul_f32_e32 v88, v58, v102
	v_cndmask_b32_e64 v56, v204, v205, s[0:1]
	v_and_b32_e32 v57, v56, v98
	v_add_u32_e32 v58, 1, v98
	v_cndmask_b32_e64 v52, v48, v52, s[42:43]
	v_cndmask_b32_e64 v53, v49, v53, s[42:43]
	v_cndmask_b32_e64 v54, v50, v54, s[42:43]
	v_cndmask_b32_e64 v55, v51, v55, s[42:43]
	v_cmp_eq_u32_e64 s[56:57], 0, v57
	v_and_b32_e32 v56, v56, v58
	s_nop 1
	v_mov_b32_dpp v58, v52 row_ror:1 row_mask:0xf bank_mask:0xf
	v_mov_b32_dpp v59, v53 row_ror:1 row_mask:0xf bank_mask:0xf
	v_mov_b32_dpp v102, v54 row_ror:1 row_mask:0xf bank_mask:0xf
	v_mov_b32_dpp v103, v55 row_ror:1 row_mask:0xf bank_mask:0xf
	s_nop 1
	v_mov_b32_dpp v104, v48 row_ror:15 row_mask:0xf bank_mask:0xf
	v_mov_b32_dpp v105, v49 row_ror:15 row_mask:0xf bank_mask:0xf
	v_mov_b32_dpp v106, v50 row_ror:15 row_mask:0xf bank_mask:0xf
	v_mov_b32_dpp v107, v51 row_ror:15 row_mask:0xf bank_mask:0xf
	v_cmp_eq_u32_e64 s[58:59], 0, v56
	v_pk_mul_f32 v[54:55], v[82:83], v[102:103]
	v_pk_mul_f32 v[52:53], v[80:81], v[58:59]
	v_pk_fma_f32 v[50:51], v[50:51], v[74:75], v[54:55]
	v_pk_fma_f32 v[48:49], v[48:49], v[72:73], v[52:53]
	s_waitcnt lgkmcnt(0)
	v_cndmask_b32_e64 v54, v106, v78, s[42:43]
	v_cndmask_b32_e64 v55, v107, v79, s[42:43]
	v_cndmask_b32_e64 v52, v104, v76, s[42:43]
	v_cndmask_b32_e64 v53, v105, v77, s[42:43]
	v_pk_fma_f32 v[50:51], v[70:71], v[54:55], v[50:51]
	v_pk_fma_f32 v[48:49], v[68:69], v[52:53], v[48:49]
	v_pk_add_f32 v[50:51], v[66:67], v[50:51]
	v_pk_add_f32 v[48:49], v[64:65], v[48:49]
	v_mul_f32_e32 v52, v51, v51
	v_mul_f32_e32 v53, v48, v48
	v_mul_f32_e32 v54, v49, v49
	v_mul_f32_e32 v55, v50, v50
	v_fmamk_f32 v52, v52, 0xbdd2d3e7, v198
	v_fmamk_f32 v53, v53, 0xbdd2d3e7, v198
	v_fmamk_f32 v54, v54, 0xbdd2d3e7, v198
	v_fmamk_f32 v55, v55, 0xbdd2d3e7, v198
	v_mul_f32_e32 v52, v51, v52
	v_mul_f32_e32 v53, v48, v53
	v_mul_f32_e32 v54, v49, v54
	v_mul_f32_e32 v55, v50, v55
	v_exp_f32_e32 v52, v52
	v_exp_f32_e32 v53, v53
	v_exp_f32_e32 v54, v54
	v_exp_f32_e32 v55, v55
	v_add_f32_e32 v52, 1.0, v52
	v_add_f32_e32 v53, 1.0, v53
	v_add_f32_e32 v54, 1.0, v54
	v_add_f32_e32 v55, 1.0, v55
	v_rcp_f32_e32 v52, v52
	v_rcp_f32_e32 v53, v53
	v_rcp_f32_e32 v54, v54
	v_rcp_f32_e32 v55, v55
	v_mul_f32_e32 v81, v51, v52
	v_mul_f32_e32 v82, v48, v53
	v_mul_f32_e32 v83, v49, v54
	v_mul_f32_e32 v80, v50, v55
	ds_read_b128 v[48:51], v179 offset:512
	ds_read_b128 v[64:67], v179 offset:1536
	ds_read_b128 v[68:71], v179 offset:2560
	ds_read_b128 v[72:75], v179 offset:3584
	ds_read_b128 v[52:55], v100 offset:1536
	ds_read_b128 v[76:79], v101 offset:512
	v_cndmask_b32_e32 v56, v44, v40, vcc
	v_cndmask_b32_e32 v57, v45, v41, vcc
	v_cndmask_b32_e32 v58, v46, v42, vcc
	v_cndmask_b32_e32 v59, v47, v43, vcc
	s_nop 1
	v_mov_b32_dpp v102, v44 row_ror:1 row_mask:0xf bank_mask:0xf
	v_mov_b32_dpp v103, v45 row_ror:1 row_mask:0xf bank_mask:0xf
	v_mov_b32_dpp v104, v46 row_ror:1 row_mask:0xf bank_mask:0xf
	v_mov_b32_dpp v105, v47 row_ror:1 row_mask:0xf bank_mask:0xf
	s_nop 1
	v_mov_b32_dpp v106, v56 row_ror:15 row_mask:0xf bank_mask:0xf
	v_mov_b32_dpp v107, v57 row_ror:15 row_mask:0xf bank_mask:0xf
	v_mov_b32_dpp v108, v58 row_ror:15 row_mask:0xf bank_mask:0xf
	v_mov_b32_dpp v109, v59 row_ror:15 row_mask:0xf bank_mask:0xf
	s_movk_i32 s0, 0xfe
	s_waitcnt lgkmcnt(1)
; #define LAS __attribute__((address_space(3)))
;     DI void operator()(const f32x4 (&acc)[2][2][4][2], const Unit& u, int wr, int wc, int fr_in, int fq_in) const {
;     ...
;         for (int ai = 0; ai < 2; ++ai) {
;             const int blk = 2 * ai + wr;
;             const int tr0 = 128 * ai + 64 * wr + fr;
;             u32x2 pk0[4];
; #pragma unroll
;             for (int n = 0; n < 2; ++n) {
;                 f32x4 ga[4];
; #pragma unroll
;                 for (int bj = 0; bj < 2; ++bj) {
;                     const LAS float* wp = wlb + 128 * bj + qpos + 4 * n;
;                     const f32x4 w0 = *(const LAS f32x4*)(wp), w1 = *(const LAS f32x4*)(wp + 256), w2 = *(const LAS f32x4*)(wp + 512), bb = *(const LAS f32x4*)(wp + 768);
;                     const f32x4 eprev = *(const LAS f32x4*)(exb + (((blk + 3) & 3) * 2 + 1) * 256 + 128 * bj + qpos + 4 * n);
;                     const f32x4 enext = *(const LAS f32x4*)(exb + (((blk + 1) & 3) * 2 + 0) * 256 + 128 * bj + qpos + 4 * n);
; #pragma unroll
;                     for (int m = 0; m < 4; ++m) {
;                         const int g = 254 * u.pm - 1 + tr0 + 16 * m;
;                         const int lmask = (g < NLAT) ? (T - 1) : (CL - 1);
;                         const bool hp = (g & lmask) != 0, hn = ((g + 1) & lmask) != 0;
;                         f32x4 sp = acc[ai][bj][m][n], sn = acc[ai][bj][m][n];
;                         if (m > 0 && fr == 15) sp = acc[ai][bj][m > 0 ? m - 1 : 0][n];
;                         if (m < 3 && fr == 0) sn = acc[ai][bj][m < 3 ? m + 1 : 3][n];
;                         f32x4 pv, nv;
;                         dpp_rot4<0>(pv, sp); dpp_rot4<1>(nv, sn);
;                         if (m == 0 && fr == 0) pv = eprev;
;                         if (m == 3 && fr == 15) nv = enext;
;                         if (!hp) pv = (f32x4){0.f, 0.f, 0.f, 0.f};
;                         if (!hn) nv = (f32x4){0.f, 0.f, 0.f, 0.f};
;                         const f32x4 uu = pv * w0 + acc[ai][bj][m][n] * w1 + nv * w2 + bb;
;                         if (bj == 0) { ga[m][0] = gelu_tanh(uu[0]); ga[m][1] = gelu_tanh(uu[1]); ga[m][2] = gelu_tanh(uu[2]); ga[m][3] = gelu_tanh(uu[3]); }
;                         else ga[m] = ga[m] * uu;
;                         asm volatile("" : "+v"(ga[m][0]), "+v"(ga[m][1]), "+v"(ga[m][2]), "+v"(ga[m][3]));
;                     }
;                 }
	v_cndmask_b32_e32 v56, v102, v52, vcc
	v_cndmask_b32_e32 v57, v103, v53, vcc
	v_cndmask_b32_e32 v52, v104, v54, vcc
	v_cndmask_b32_e32 v53, v105, v55, vcc
	v_pk_mul_f32 v[54:55], v[48:49], v[56:57]
	v_pk_mul_f32 v[52:53], v[50:51], v[52:53]
	v_pk_fma_f32 v[54:55], v[44:45], v[64:65], v[54:55]
	v_pk_fma_f32 v[52:53], v[46:47], v[66:67], v[52:53]
	v_pk_fma_f32 v[54:55], v[68:69], v[106:107], v[54:55]
	v_pk_fma_f32 v[52:53], v[70:71], v[108:109], v[52:53]
	v_cndmask_b32_e64 v44, v40, v44, s[42:43]
	v_pk_add_f32 v[56:57], v[74:75], v[52:53]
	v_pk_add_f32 v[52:53], v[72:73], v[54:55]
	v_cndmask_b32_e64 v45, v41, v45, s[42:43]
	v_cndmask_b32_e64 v46, v42, v46, s[42:43]
	v_cndmask_b32_e64 v47, v43, v47, s[42:43]
	v_pk_mul_f32 v[52:53], v[86:87], v[52:53]
	v_pk_mul_f32 v[54:55], v[84:85], v[56:57]
	s_nop 1
	v_mov_b32_dpp v84, v44 row_ror:1 row_mask:0xf bank_mask:0xf
	v_mov_b32_dpp v85, v45 row_ror:1 row_mask:0xf bank_mask:0xf
	v_mov_b32_dpp v86, v46 row_ror:1 row_mask:0xf bank_mask:0xf
	v_mov_b32_dpp v87, v47 row_ror:1 row_mask:0xf bank_mask:0xf
	v_cndmask_b32_e32 v56, v40, v36, vcc
	v_cndmask_b32_e32 v57, v41, v37, vcc
	v_cndmask_b32_e32 v58, v42, v38, vcc
	v_cndmask_b32_e32 v59, v43, v39, vcc
	v_pk_mul_f32 v[46:47], v[48:49], v[84:85]
	v_pk_mul_f32 v[44:45], v[50:51], v[86:87]
	s_nop 1
	v_mov_b32_dpp v102, v56 row_ror:15 row_mask:0xf bank_mask:0xf
	v_mov_b32_dpp v103, v57 row_ror:15 row_mask:0xf bank_mask:0xf
	v_mov_b32_dpp v104, v58 row_ror:15 row_mask:0xf bank_mask:0xf
	v_mov_b32_dpp v105, v59 row_ror:15 row_mask:0xf bank_mask:0xf
	v_pk_fma_f32 v[46:47], v[40:41], v[64:65], v[46:47]
	v_pk_fma_f32 v[44:45], v[42:43], v[66:67], v[44:45]
	v_pk_fma_f32 v[46:47], v[68:69], v[102:103], v[46:47]
	v_pk_fma_f32 v[44:45], v[70:71], v[104:105], v[44:45]
	v_pk_add_f32 v[46:47], v[72:73], v[46:47]
	v_pk_add_f32 v[44:45], v[74:75], v[44:45]
	v_cndmask_b32_e64 v40, v36, v40, s[42:43]
	v_cndmask_b32_e64 v41, v37, v41, s[42:43]
	v_cndmask_b32_e64 v42, v38, v42, s[42:43]
	v_cndmask_b32_e64 v43, v39, v43, s[42:43]
	v_pk_mul_f32 v[56:57], v[62:63], v[46:47]
	v_pk_mul_f32 v[58:59], v[60:61], v[44:45]
	s_nop 1
	v_mov_b32_dpp v60, v40 row_ror:1 row_mask:0xf bank_mask:0xf
	v_mov_b32_dpp v61, v41 row_ror:1 row_mask:0xf bank_mask:0xf
	v_mov_b32_dpp v62, v42 row_ror:1 row_mask:0xf bank_mask:0xf
	v_mov_b32_dpp v63, v43 row_ror:1 row_mask:0xf bank_mask:0xf
	v_cndmask_b32_e32 v44, v36, v32, vcc
	v_cndmask_b32_e32 v45, v37, v33, vcc
	v_cndmask_b32_e32 v46, v38, v34, vcc
	v_cndmask_b32_e32 v47, v39, v35, vcc
	v_pk_mul_f32 v[42:43], v[48:49], v[60:61]
	v_pk_mul_f32 v[40:41], v[50:51], v[62:63]
	s_nop 1
	v_mov_b32_dpp v84, v44 row_ror:15 row_mask:0xf bank_mask:0xf
	v_mov_b32_dpp v85, v45 row_ror:15 row_mask:0xf bank_mask:0xf
	v_mov_b32_dpp v86, v46 row_ror:15 row_mask:0xf bank_mask:0xf
	v_mov_b32_dpp v87, v47 row_ror:15 row_mask:0xf bank_mask:0xf
	v_pk_fma_f32 v[42:43], v[36:37], v[64:65], v[42:43]
	v_pk_fma_f32 v[40:41], v[38:39], v[66:67], v[40:41]
	v_pk_fma_f32 v[42:43], v[68:69], v[84:85], v[42:43]
	v_pk_fma_f32 v[40:41], v[70:71], v[86:87], v[40:41]
	v_pk_add_f32 v[42:43], v[72:73], v[42:43]
	v_pk_add_f32 v[40:41], v[74:75], v[40:41]
	v_cndmask_b32_e64 v36, v32, v36, s[42:43]
	v_cndmask_b32_e64 v37, v33, v37, s[42:43]
	v_cndmask_b32_e64 v38, v34, v38, s[42:43]
	v_cndmask_b32_e64 v39, v35, v39, s[42:43]
	v_pk_mul_f32 v[60:61], v[90:91], v[42:43]
	v_pk_mul_f32 v[62:63], v[88:89], v[40:41]
	s_nop 1
	v_mov_b32_dpp v40, v36 row_ror:1 row_mask:0xf bank_mask:0xf
	v_mov_b32_dpp v41, v37 row_ror:1 row_mask:0xf bank_mask:0xf
	v_mov_b32_dpp v42, v38 row_ror:1 row_mask:0xf bank_mask:0xf
	v_mov_b32_dpp v43, v39 row_ror:1 row_mask:0xf bank_mask:0xf
	s_nop 1
	v_mov_b32_dpp v44, v32 row_ror:15 row_mask:0xf bank_mask:0xf
	v_mov_b32_dpp v45, v33 row_ror:15 row_mask:0xf bank_mask:0xf
	v_mov_b32_dpp v46, v34 row_ror:15 row_mask:0xf bank_mask:0xf
	v_mov_b32_dpp v47, v35 row_ror:15 row_mask:0xf bank_mask:0xf
	s_mov_b32 s33, 0x10000
	v_pk_mul_f32 v[38:39], v[50:51], v[42:43]
	v_pk_mul_f32 v[36:37], v[48:49], v[40:41]
	v_pk_fma_f32 v[34:35], v[34:35], v[66:67], v[38:39]
	v_pk_fma_f32 v[32:33], v[32:33], v[64:65], v[36:37]
	s_waitcnt lgkmcnt(0)
	v_cndmask_b32_e64 v38, v46, v78, s[42:43]
	v_cndmask_b32_e64 v39, v47, v79, s[42:43]
	v_cndmask_b32_e64 v36, v44, v76, s[42:43]
	v_cndmask_b32_e64 v37, v45, v77, s[42:43]
	v_pk_fma_f32 v[34:35], v[70:71], v[38:39], v[34:35]
	v_pk_fma_f32 v[32:33], v[68:69], v[36:37], v[32:33]
	v_pk_add_f32 v[34:35], v[74:75], v[34:35]
	v_pk_add_f32 v[32:33], v[72:73], v[32:33]
	v_pk_mul_f32 v[64:65], v[80:81], v[34:35]
	v_pk_mul_f32 v[66:67], v[82:83], v[32:33]
	s_nop 1
	v_mov_b32_dpp v76, v28 row_ror:1 row_mask:0xf bank_mask:0xf
	v_mov_b32_dpp v77, v29 row_ror:1 row_mask:0xf bank_mask:0xf
	v_mov_b32_dpp v78, v30 row_ror:1 row_mask:0xf bank_mask:0xf
	v_mov_b32_dpp v79, v31 row_ror:1 row_mask:0xf bank_mask:0xf
	v_cndmask_b32_e32 v72, v28, v24, vcc
	ds_read_b128 v[48:51], v179 offset:16
	ds_read_b128 v[40:43], v179 offset:1040
	ds_read_b128 v[36:39], v179 offset:2064
	ds_read_b128 v[32:35], v179 offset:3088
	ds_read_b128 v[68:71], v100 offset:1040
	ds_read_b128 v[44:47], v101 offset:16
	v_cndmask_b32_e32 v73, v29, v25, vcc
	v_cndmask_b32_e32 v74, v30, v26, vcc
	v_cndmask_b32_e32 v75, v31, v27, vcc
	s_waitcnt lgkmcnt(1)
; #define LAS __attribute__((address_space(3)))
;     DI void operator()(const f32x4 (&acc)[2][2][4][2], const Unit& u, int wr, int wc, int fr_in, int fq_in) const {
;     ...
;         for (int ai = 0; ai < 2; ++ai) {
;             const int blk = 2 * ai + wr;
;             const int tr0 = 128 * ai + 64 * wr + fr;
;             u32x2 pk0[4];
; #pragma unroll
;             for (int n = 0; n < 2; ++n) {
;                 f32x4 ga[4];
; #pragma unroll
;                 for (int bj = 0; bj < 2; ++bj) {
;                     const LAS float* wp = wlb + 128 * bj + qpos + 4 * n;
;                     const f32x4 w0 = *(const LAS f32x4*)(wp), w1 = *(const LAS f32x4*)(wp + 256), w2 = *(const LAS f32x4*)(wp + 512), bb = *(const LAS f32x4*)(wp + 768);
;                     const f32x4 eprev = *(const LAS f32x4*)(exb + (((blk + 3) & 3) * 2 + 1) * 256 + 128 * bj + qpos + 4 * n);
;                     const f32x4 enext = *(const LAS f32x4*)(exb + (((blk + 1) & 3) * 2 + 0) * 256 + 128 * bj + qpos + 4 * n);
; #pragma unroll
;                     for (int m = 0; m < 4; ++m) {
;                         const int g = 254 * u.pm - 1 + tr0 + 16 * m;
;                         const int lmask = (g < NLAT) ? (T - 1) : (CL - 1);
;                         const bool hp = (g & lmask) != 0, hn = ((g + 1) & lmask) != 0;
;                         f32x4 sp = acc[ai][bj][m][n], sn = acc[ai][bj][m][n];
;                         if (m > 0 && fr == 15) sp = acc[ai][bj][m > 0 ? m - 1 : 0][n];
;                         if (m < 3 && fr == 0) sn = acc[ai][bj][m < 3 ? m + 1 : 3][n];
;                         f32x4 pv, nv;
;                         dpp_rot4<0>(pv, sp); dpp_rot4<1>(nv, sn);
;                         if (m == 0 && fr == 0) pv = eprev;
;                         if (m == 3 && fr == 15) nv = enext;
;                         if (!hp) pv = (f32x4){0.f, 0.f, 0.f, 0.f};
;                         if (!hn) nv = (f32x4){0.f, 0.f, 0.f, 0.f};
;                         const f32x4 uu = pv * w0 + acc[ai][bj][m][n] * w1 + nv * w2 + bb;
;                         if (bj == 0) { ga[m][0] = gelu_tanh(uu[0]); ga[m][1] = gelu_tanh(uu[1]); ga[m][2] = gelu_tanh(uu[2]); ga[m][3] = gelu_tanh(uu[3]); }
;                         else ga[m] = ga[m] * uu;
;                         asm volatile("" : "+v"(ga[m][0]), "+v"(ga[m][1]), "+v"(ga[m][2]), "+v"(ga[m][3]));
;                     }
;                 }
	v_cndmask_b32_e32 v70, v78, v70, vcc
	v_cndmask_b32_e32 v71, v79, v71, vcc
	v_cndmask_b32_e32 v68, v76, v68, vcc
	v_cndmask_b32_e32 v69, v77, v69, vcc
	v_pk_mul_f32 v[70:71], v[50:51], v[70:71]
	v_pk_mul_f32 v[68:69], v[48:49], v[68:69]
	s_nop 1
	v_mov_b32_dpp v80, v72 row_ror:15 row_mask:0xf bank_mask:0xf
	v_mov_b32_dpp v81, v73 row_ror:15 row_mask:0xf bank_mask:0xf
	v_mov_b32_dpp v82, v74 row_ror:15 row_mask:0xf bank_mask:0xf
	v_mov_b32_dpp v83, v75 row_ror:15 row_mask:0xf bank_mask:0xf
	v_pk_fma_f32 v[70:71], v[30:31], v[42:43], v[70:71]
	v_pk_fma_f32 v[68:69], v[28:29], v[40:41], v[68:69]
	v_pk_fma_f32 v[70:71], v[38:39], v[82:83], v[70:71]
	v_pk_fma_f32 v[68:69], v[36:37], v[80:81], v[68:69]
	v_cndmask_b32_e64 v28, v24, v28, s[42:43]
	v_pk_add_f32 v[72:73], v[32:33], v[68:69]
	v_pk_add_f32 v[68:69], v[34:35], v[70:71]
	v_mul_f32_e32 v71, v72, v72
	v_mul_f32_e32 v70, v69, v69
	v_mul_f32_e32 v74, v73, v73
	v_mul_f32_e32 v75, v68, v68
	v_fmamk_f32 v70, v70, 0xbdd2d3e7, v198
	v_fmamk_f32 v71, v71, 0xbdd2d3e7, v198
	v_fmamk_f32 v74, v74, 0xbdd2d3e7, v198
	v_fmamk_f32 v75, v75, 0xbdd2d3e7, v198
	v_mul_f32_e32 v70, v69, v70
	v_mul_f32_e32 v71, v72, v71
	v_mul_f32_e32 v74, v73, v74
	v_mul_f32_e32 v75, v68, v75
	v_exp_f32_e32 v70, v70
	v_exp_f32_e32 v71, v71
	v_exp_f32_e32 v74, v74
	v_exp_f32_e32 v75, v75
	v_add_f32_e32 v70, 1.0, v70
	v_add_f32_e32 v71, 1.0, v71
	v_add_f32_e32 v74, 1.0, v74
	v_add_f32_e32 v75, 1.0, v75
	v_rcp_f32_e32 v70, v70
	v_rcp_f32_e32 v71, v71
	v_rcp_f32_e32 v74, v74
	v_rcp_f32_e32 v75, v75
	v_cndmask_b32_e64 v29, v25, v29, s[42:43]
	v_cndmask_b32_e64 v30, v26, v30, s[42:43]
	v_cndmask_b32_e64 v31, v27, v31, s[42:43]
	s_nop 1
	v_mov_b32_dpp v76, v28 row_ror:1 row_mask:0xf bank_mask:0xf
	v_mov_b32_dpp v77, v29 row_ror:1 row_mask:0xf bank_mask:0xf
	v_mov_b32_dpp v78, v30 row_ror:1 row_mask:0xf bank_mask:0xf
	v_mov_b32_dpp v79, v31 row_ror:1 row_mask:0xf bank_mask:0xf
	v_mul_f32_e32 v69, v69, v70
	v_mul_f32_e32 v70, v72, v71
	v_mul_f32_e32 v71, v73, v74
	v_mul_f32_e32 v68, v68, v75
	v_cndmask_b32_e32 v72, v24, v20, vcc
	v_cndmask_b32_e32 v73, v25, v21, vcc
	v_cndmask_b32_e32 v74, v26, v22, vcc
	v_cndmask_b32_e32 v75, v27, v23, vcc
	v_pk_mul_f32 v[30:31], v[50:51], v[78:79]
	v_pk_mul_f32 v[28:29], v[48:49], v[76:77]
	s_nop 1
	v_mov_b32_dpp v80, v72 row_ror:15 row_mask:0xf bank_mask:0xf
	v_mov_b32_dpp v81, v73 row_ror:15 row_mask:0xf bank_mask:0xf
	v_mov_b32_dpp v82, v74 row_ror:15 row_mask:0xf bank_mask:0xf
	v_mov_b32_dpp v83, v75 row_ror:15 row_mask:0xf bank_mask:0xf
	v_pk_fma_f32 v[30:31], v[26:27], v[42:43], v[30:31]
	v_pk_fma_f32 v[28:29], v[24:25], v[40:41], v[28:29]
	v_pk_fma_f32 v[30:31], v[38:39], v[82:83], v[30:31]
	v_pk_fma_f32 v[28:29], v[36:37], v[80:81], v[28:29]
	v_cndmask_b32_e64 v24, v20, v24, s[42:43]
	v_pk_add_f32 v[72:73], v[32:33], v[28:29]
	v_pk_add_f32 v[28:29], v[34:35], v[30:31]
	v_mul_f32_e32 v31, v72, v72
	v_mul_f32_e32 v30, v29, v29
	v_mul_f32_e32 v74, v73, v73
	v_fmamk_f32 v30, v30, 0xbdd2d3e7, v198
	v_fmamk_f32 v31, v31, 0xbdd2d3e7, v198
	v_fmamk_f32 v74, v74, 0xbdd2d3e7, v198
	v_mul_f32_e32 v75, v28, v28
	v_mul_f32_e32 v30, v29, v30
	v_mul_f32_e32 v31, v72, v31
	v_mul_f32_e32 v74, v73, v74
	v_fmamk_f32 v75, v75, 0xbdd2d3e7, v198
	v_exp_f32_e32 v30, v30
	v_exp_f32_e32 v31, v31
	v_exp_f32_e32 v74, v74
	v_mul_f32_e32 v75, v28, v75
	v_exp_f32_e32 v75, v75
	v_add_f32_e32 v30, 1.0, v30
	v_add_f32_e32 v31, 1.0, v31
	v_add_f32_e32 v74, 1.0, v74
	v_rcp_f32_e32 v30, v30
	v_rcp_f32_e32 v31, v31
	v_rcp_f32_e32 v74, v74
	v_add_f32_e32 v75, 1.0, v75
	v_rcp_f32_e32 v75, v75
	v_cndmask_b32_e64 v25, v21, v25, s[42:43]
	v_cndmask_b32_e64 v26, v22, v26, s[42:43]
	v_cndmask_b32_e64 v27, v23, v27, s[42:43]
	s_nop 1
	v_mov_b32_dpp v76, v24 row_ror:1 row_mask:0xf bank_mask:0xf
	v_mov_b32_dpp v77, v25 row_ror:1 row_mask:0xf bank_mask:0xf
	v_mov_b32_dpp v78, v26 row_ror:1 row_mask:0xf bank_mask:0xf
	v_mov_b32_dpp v79, v27 row_ror:1 row_mask:0xf bank_mask:0xf
	v_mul_f32_e32 v29, v29, v30
	v_mul_f32_e32 v30, v72, v31
	v_mul_f32_e32 v31, v73, v74
	v_cndmask_b32_e32 v72, v20, v16, vcc
	v_cndmask_b32_e32 v73, v21, v17, vcc
	v_pk_mul_f32 v[24:25], v[48:49], v[76:77]
	v_mul_f32_e32 v28, v28, v75
	v_cndmask_b32_e32 v74, v22, v18, vcc
	v_cndmask_b32_e32 v75, v23, v19, vcc
	s_nop 1
	v_mov_b32_dpp v80, v72 row_ror:15 row_mask:0xf bank_mask:0xf
	v_mov_b32_dpp v81, v73 row_ror:15 row_mask:0xf bank_mask:0xf
	v_mov_b32_dpp v82, v74 row_ror:15 row_mask:0xf bank_mask:0xf
	v_mov_b32_dpp v83, v75 row_ror:15 row_mask:0xf bank_mask:0xf
	v_pk_fma_f32 v[24:25], v[20:21], v[40:41], v[24:25]
	v_pk_mul_f32 v[26:27], v[50:51], v[78:79]
	v_pk_fma_f32 v[24:25], v[36:37], v[80:81], v[24:25]
	v_pk_fma_f32 v[26:27], v[22:23], v[42:43], v[26:27]
	v_pk_add_f32 v[24:25], v[32:33], v[24:25]
	v_pk_fma_f32 v[26:27], v[38:39], v[82:83], v[26:27]
	v_mul_f32_e32 v73, v24, v24
	v_pk_add_f32 v[26:27], v[34:35], v[26:27]
	v_fmamk_f32 v73, v73, 0xbdd2d3e7, v198
	v_mul_f32_e32 v74, v25, v25
	v_mul_f32_e32 v72, v27, v27
	v_mul_f32_e32 v73, v24, v73
	v_fmamk_f32 v74, v74, 0xbdd2d3e7, v198
	v_mul_f32_e32 v75, v26, v26
	v_fmamk_f32 v72, v72, 0xbdd2d3e7, v198
	v_exp_f32_e32 v73, v73
	v_mul_f32_e32 v74, v25, v74
	v_fmamk_f32 v75, v75, 0xbdd2d3e7, v198
	v_mul_f32_e32 v72, v27, v72
	v_exp_f32_e32 v74, v74
	v_mul_f32_e32 v75, v26, v75
	v_exp_f32_e32 v72, v72
	v_exp_f32_e32 v75, v75
	v_add_f32_e32 v73, 1.0, v73
	v_rcp_f32_e32 v76, v73
	v_add_f32_e32 v73, 1.0, v74
	v_add_f32_e32 v72, 1.0, v72
	v_rcp_f32_e32 v77, v73
	v_add_f32_e32 v73, 1.0, v75
	v_rcp_f32_e32 v72, v72
	v_rcp_f32_e32 v78, v73
	v_cndmask_b32_e64 v20, v16, v20, s[42:43]
	v_cndmask_b32_e64 v21, v17, v21, s[42:43]
	v_cndmask_b32_e64 v22, v18, v22, s[42:43]
	v_cndmask_b32_e64 v23, v19, v23, s[42:43]
	v_mul_f32_e32 v73, v27, v72
	v_mul_f32_e32 v74, v24, v76
	v_mul_f32_e32 v75, v25, v77
	v_mul_f32_e32 v72, v26, v78
	s_nop 1
	v_mov_b32_dpp v24, v20 row_ror:1 row_mask:0xf bank_mask:0xf
	v_mov_b32_dpp v25, v21 row_ror:1 row_mask:0xf bank_mask:0xf
	v_mov_b32_dpp v26, v22 row_ror:1 row_mask:0xf bank_mask:0xf
	v_mov_b32_dpp v27, v23 row_ror:1 row_mask:0xf bank_mask:0xf
	s_nop 1
	v_mov_b32_dpp v76, v16 row_ror:15 row_mask:0xf bank_mask:0xf
	v_mov_b32_dpp v77, v17 row_ror:15 row_mask:0xf bank_mask:0xf
	v_mov_b32_dpp v78, v18 row_ror:15 row_mask:0xf bank_mask:0xf
	v_mov_b32_dpp v79, v19 row_ror:15 row_mask:0xf bank_mask:0xf
	s_nop 0
	v_pk_mul_f32 v[22:23], v[50:51], v[26:27]
	v_pk_mul_f32 v[20:21], v[48:49], v[24:25]
	v_pk_fma_f32 v[18:19], v[18:19], v[42:43], v[22:23]
	v_pk_fma_f32 v[16:17], v[16:17], v[40:41], v[20:21]
	s_waitcnt lgkmcnt(0)
;     DI void operator()(const f32x4 (&acc)[2][2][4][2], const Unit& u, int wr, int wc, int fr_in, int fq_in) const {
;     ...
;         for (int ai = 0; ai < 2; ++ai) {
;             const int blk = 2 * ai + wr;
;             const int tr0 = 128 * ai + 64 * wr + fr;
;             u32x2 pk0[4];
; #pragma unroll
;             for (int n = 0; n < 2; ++n) {
;                 f32x4 ga[4];
; #pragma unroll
;                 for (int bj = 0; bj < 2; ++bj) {
;                     const LAS float* wp = wlb + 128 * bj + qpos + 4 * n;
;                     const f32x4 w0 = *(const LAS f32x4*)(wp), w1 = *(const LAS f32x4*)(wp + 256), w2 = *(const LAS f32x4*)(wp + 512), bb = *(const LAS f32x4*)(wp + 768);
;                     const f32x4 eprev = *(const LAS f32x4*)(exb + (((blk + 3) & 3) * 2 + 1) * 256 + 128 * bj + qpos + 4 * n);
;                     const f32x4 enext = *(const LAS f32x4*)(exb + (((blk + 1) & 3) * 2 + 0) * 256 + 128 * bj + qpos + 4 * n);
; #pragma unroll
;                     for (int m = 0; m < 4; ++m) {
;                         const int g = 254 * u.pm - 1 + tr0 + 16 * m;
;                         const int lmask = (g < NLAT) ? (T - 1) : (CL - 1);
;                         const bool hp = (g & lmask) != 0, hn = ((g + 1) & lmask) != 0;
;                         f32x4 sp = acc[ai][bj][m][n], sn = acc[ai][bj][m][n];
;                         if (m > 0 && fr == 15) sp = acc[ai][bj][m > 0 ? m - 1 : 0][n];
;                         if (m < 3 && fr == 0) sn = acc[ai][bj][m < 3 ? m + 1 : 3][n];
;                         f32x4 pv, nv;
;                         dpp_rot4<0>(pv, sp); dpp_rot4<1>(nv, sn);
;                         if (m == 0 && fr == 0) pv = eprev;
;                         if (m == 3 && fr == 15) nv = enext;
;                         if (!hp) pv = (f32x4){0.f, 0.f, 0.f, 0.f};
;                         if (!hn) nv = (f32x4){0.f, 0.f, 0.f, 0.f};
;                         const f32x4 uu = pv * w0 + acc[ai][bj][m][n] * w1 + nv * w2 + bb;
;                         if (bj == 0) { ga[m][0] = gelu_tanh(uu[0]); ga[m][1] = gelu_tanh(uu[1]); ga[m][2] = gelu_tanh(uu[2]); ga[m][3] = gelu_tanh(uu[3]); }
;                         else ga[m] = ga[m] * uu;
;                         asm volatile("" : "+v"(ga[m][0]), "+v"(ga[m][1]), "+v"(ga[m][2]), "+v"(ga[m][3]));
;                     }
;                 }
; #pragma unroll
	v_cndmask_b32_e64 v22, v78, v46, s[42:43]
	v_cndmask_b32_e64 v23, v79, v47, s[42:43]
	v_cndmask_b32_e64 v20, v76, v44, s[42:43]
	v_cndmask_b32_e64 v21, v77, v45, s[42:43]
	v_pk_fma_f32 v[18:19], v[38:39], v[22:23], v[18:19]
	v_pk_fma_f32 v[16:17], v[36:37], v[20:21], v[16:17]
	v_pk_add_f32 v[18:19], v[34:35], v[18:19]
	v_pk_add_f32 v[16:17], v[32:33], v[16:17]
	v_mul_f32_e32 v20, v19, v19
	v_mul_f32_e32 v21, v16, v16
	v_mul_f32_e32 v22, v17, v17
	v_mul_f32_e32 v23, v18, v18
	v_fmamk_f32 v20, v20, 0xbdd2d3e7, v198
	v_fmamk_f32 v21, v21, 0xbdd2d3e7, v198
	v_fmamk_f32 v22, v22, 0xbdd2d3e7, v198
	v_fmamk_f32 v23, v23, 0xbdd2d3e7, v198
	v_mul_f32_e32 v20, v19, v20
	v_mul_f32_e32 v21, v16, v21
	v_mul_f32_e32 v22, v17, v22
	v_mul_f32_e32 v23, v18, v23
	v_exp_f32_e32 v20, v20
	v_exp_f32_e32 v21, v21
	v_exp_f32_e32 v22, v22
	v_exp_f32_e32 v23, v23
	v_add_f32_e32 v20, 1.0, v20
	v_add_f32_e32 v21, 1.0, v21
	v_add_f32_e32 v22, 1.0, v22
	v_add_f32_e32 v23, 1.0, v23
	v_rcp_f32_e32 v20, v20
	v_rcp_f32_e32 v21, v21
	v_rcp_f32_e32 v22, v22
	v_rcp_f32_e32 v23, v23
	v_mul_f32_e32 v45, v19, v20
	v_mul_f32_e32 v46, v16, v21
	v_mul_f32_e32 v47, v17, v22
	v_mul_f32_e32 v44, v18, v23
	ds_read_b128 v[20:23], v179 offset:528
	ds_read_b128 v[24:27], v179 offset:1552
	ds_read_b128 v[32:35], v179 offset:2576
	ds_read_b128 v[36:39], v179 offset:3600
	ds_read_b128 v[16:19], v100 offset:1552
	ds_read_b128 v[40:43], v101 offset:528
	v_cndmask_b32_e32 v48, v12, v8, vcc
	v_cndmask_b32_e32 v49, v13, v9, vcc
	v_cndmask_b32_e32 v50, v14, v10, vcc
	v_cndmask_b32_e32 v51, v15, v11, vcc
	s_nop 1
	v_mov_b32_dpp v76, v12 row_ror:1 row_mask:0xf bank_mask:0xf
	v_mov_b32_dpp v77, v13 row_ror:1 row_mask:0xf bank_mask:0xf
	v_mov_b32_dpp v78, v14 row_ror:1 row_mask:0xf bank_mask:0xf
	v_mov_b32_dpp v79, v15 row_ror:1 row_mask:0xf bank_mask:0xf
	s_nop 1
	v_mov_b32_dpp v80, v48 row_ror:15 row_mask:0xf bank_mask:0xf
	v_mov_b32_dpp v81, v49 row_ror:15 row_mask:0xf bank_mask:0xf
	v_mov_b32_dpp v82, v50 row_ror:15 row_mask:0xf bank_mask:0xf
	v_mov_b32_dpp v83, v51 row_ror:15 row_mask:0xf bank_mask:0xf
	s_waitcnt lgkmcnt(1)
	v_cndmask_b32_e32 v48, v76, v16, vcc
	v_cndmask_b32_e32 v49, v77, v17, vcc
	v_cndmask_b32_e32 v16, v78, v18, vcc
	v_cndmask_b32_e32 v17, v79, v19, vcc
	v_pk_mul_f32 v[18:19], v[20:21], v[48:49]
	v_pk_mul_f32 v[16:17], v[22:23], v[16:17]
	v_pk_fma_f32 v[18:19], v[12:13], v[24:25], v[18:19]
	v_pk_fma_f32 v[16:17], v[14:15], v[26:27], v[16:17]
	v_pk_fma_f32 v[18:19], v[32:33], v[80:81], v[18:19]
	v_pk_fma_f32 v[16:17], v[34:35], v[82:83], v[16:17]
	v_cndmask_b32_e64 v12, v8, v12, s[42:43]
	v_pk_add_f32 v[48:49], v[38:39], v[16:17]
	v_pk_add_f32 v[16:17], v[36:37], v[18:19]
	v_cndmask_b32_e64 v13, v9, v13, s[42:43]
	v_pk_mul_f32 v[16:17], v[70:71], v[16:17]
	v_pk_mul_f32 v[18:19], v[68:69], v[48:49]
	v_cndmask_b32_e64 v14, v10, v14, s[42:43]
	v_cndmask_b32_e64 v15, v11, v15, s[42:43]
	s_nop 1
	v_mov_b32_dpp v68, v12 row_ror:1 row_mask:0xf bank_mask:0xf
	v_mov_b32_dpp v69, v13 row_ror:1 row_mask:0xf bank_mask:0xf
	v_mov_b32_dpp v70, v14 row_ror:1 row_mask:0xf bank_mask:0xf
	v_mov_b32_dpp v71, v15 row_ror:1 row_mask:0xf bank_mask:0xf
	v_cndmask_b32_e32 v48, v8, v4, vcc
	v_cndmask_b32_e32 v49, v9, v5, vcc
	v_pk_mul_f32 v[12:13], v[22:23], v[70:71]
	v_cndmask_b32_e32 v50, v10, v6, vcc
	v_cndmask_b32_e32 v51, v11, v7, vcc
	s_nop 1
	v_mov_b32_dpp v76, v48 row_ror:15 row_mask:0xf bank_mask:0xf
	v_mov_b32_dpp v77, v49 row_ror:15 row_mask:0xf bank_mask:0xf
	v_mov_b32_dpp v78, v50 row_ror:15 row_mask:0xf bank_mask:0xf
	v_mov_b32_dpp v79, v51 row_ror:15 row_mask:0xf bank_mask:0xf
	v_pk_mul_f32 v[14:15], v[20:21], v[68:69]
	v_pk_fma_f32 v[12:13], v[10:11], v[26:27], v[12:13]
	v_pk_fma_f32 v[14:15], v[8:9], v[24:25], v[14:15]
	v_pk_fma_f32 v[12:13], v[34:35], v[78:79], v[12:13]
	v_pk_fma_f32 v[14:15], v[32:33], v[76:77], v[14:15]
	v_pk_add_f32 v[48:49], v[38:39], v[12:13]
	v_cndmask_b32_e64 v8, v4, v8, s[42:43]
	v_cndmask_b32_e64 v9, v5, v9, s[42:43]
	v_pk_add_f32 v[12:13], v[36:37], v[14:15]
	v_pk_mul_f32 v[14:15], v[28:29], v[48:49]
	v_cndmask_b32_e64 v10, v6, v10, s[42:43]
	v_cndmask_b32_e64 v11, v7, v11, s[42:43]
	s_nop 1
	v_mov_b32_dpp v48, v8 row_ror:1 row_mask:0xf bank_mask:0xf
	v_mov_b32_dpp v49, v9 row_ror:1 row_mask:0xf bank_mask:0xf
	v_mov_b32_dpp v50, v10 row_ror:1 row_mask:0xf bank_mask:0xf
	v_mov_b32_dpp v51, v11 row_ror:1 row_mask:0xf bank_mask:0xf
	v_cndmask_b32_e32 v28, v4, v0, vcc
	v_cndmask_b32_e32 v29, v5, v1, vcc
	v_pk_mul_f32 v[8:9], v[22:23], v[50:51]
	v_pk_mul_f32 v[12:13], v[30:31], v[12:13]
	v_cndmask_b32_e32 v30, v6, v2, vcc
	v_cndmask_b32_e32 v31, v7, v3, vcc
	s_nop 1
	v_mov_b32_dpp v68, v28 row_ror:15 row_mask:0xf bank_mask:0xf
	v_mov_b32_dpp v69, v29 row_ror:15 row_mask:0xf bank_mask:0xf
	v_mov_b32_dpp v70, v30 row_ror:15 row_mask:0xf bank_mask:0xf
	v_mov_b32_dpp v71, v31 row_ror:15 row_mask:0xf bank_mask:0xf
	v_pk_mul_f32 v[10:11], v[20:21], v[48:49]
	v_pk_fma_f32 v[8:9], v[6:7], v[26:27], v[8:9]
	v_pk_fma_f32 v[10:11], v[4:5], v[24:25], v[10:11]
	v_pk_fma_f32 v[8:9], v[34:35], v[70:71], v[8:9]
	v_pk_fma_f32 v[10:11], v[32:33], v[68:69], v[10:11]
	v_pk_add_f32 v[28:29], v[38:39], v[8:9]
	v_cndmask_b32_e64 v4, v0, v4, s[42:43]
	v_cndmask_b32_e64 v5, v1, v5, s[42:43]
	v_cndmask_b32_e64 v6, v2, v6, s[42:43]
	v_cndmask_b32_e64 v7, v3, v7, s[42:43]
	v_pk_add_f32 v[8:9], v[36:37], v[10:11]
	v_pk_mul_f32 v[10:11], v[72:73], v[28:29]
	s_nop 1
	v_mov_b32_dpp v28, v4 row_ror:1 row_mask:0xf bank_mask:0xf
	v_mov_b32_dpp v29, v5 row_ror:1 row_mask:0xf bank_mask:0xf
	v_mov_b32_dpp v30, v6 row_ror:1 row_mask:0xf bank_mask:0xf
	v_mov_b32_dpp v31, v7 row_ror:1 row_mask:0xf bank_mask:0xf
	s_nop 1
	v_mov_b32_dpp v48, v0 row_ror:15 row_mask:0xf bank_mask:0xf
	v_mov_b32_dpp v49, v1 row_ror:15 row_mask:0xf bank_mask:0xf
	v_mov_b32_dpp v50, v2 row_ror:15 row_mask:0xf bank_mask:0xf
	v_mov_b32_dpp v51, v3 row_ror:15 row_mask:0xf bank_mask:0xf
	v_cmp_gt_u32_e32 vcc, s0, v93
	v_pk_mul_f32 v[6:7], v[22:23], v[30:31]
	v_pk_mul_f32 v[4:5], v[20:21], v[28:29]
	v_pk_fma_f32 v[2:3], v[2:3], v[26:27], v[6:7]
	v_pk_fma_f32 v[0:1], v[0:1], v[24:25], v[4:5]
	s_waitcnt lgkmcnt(0)
	v_cndmask_b32_e64 v6, v50, v42, s[42:43]
	v_cndmask_b32_e64 v7, v51, v43, s[42:43]
	v_cndmask_b32_e64 v4, v48, v40, s[42:43]
	v_cndmask_b32_e64 v5, v49, v41, s[42:43]
	v_pk_fma_f32 v[2:3], v[34:35], v[6:7], v[2:3]
	v_pk_fma_f32 v[0:1], v[32:33], v[4:5], v[0:1]
	v_cmp_gt_i32_e64 s[0:1], s61, v92
	v_pk_add_f32 v[4:5], v[36:37], v[0:1]
	v_pk_add_f32 v[0:1], v[38:39], v[2:3]
	v_pk_mul_f32 v[8:9], v[74:75], v[8:9]
	v_pk_mul_f32 v[0:1], v[44:45], v[0:1]
	v_pk_mul_f32 v[2:3], v[46:47], v[4:5]
	s_and_b64 s[38:39], vcc, s[0:1]
	s_and_saveexec_b64 s[0:1], s[38:39]
	s_cbranch_execz .Lfp_105
; DI unsigned pack2(float lo, float hi) { f32x2 v = {lo, hi}; bf16x2_t b = __builtin_convertvector(v, bf16x2_t); return __builtin_bit_cast(unsigned, b); }
;     DI void operator()(const f32x4 (&acc)[2][2][4][2], const Unit& u, int wr, int wc, int fr_in, int fq_in) const {
;     ...
;                     u32x2 w; w.x = pack2(ga[m][0], ga[m][1]); w.y = pack2(ga[m][2], ga[m][3]);
;                     if (n == 0) pk0[m] = w;
;                     else if (tr >= 1 && tr <= 254 && g < nrows) {
;                         u32x4 w4; w4.x = pk0[m].x; w4.y = pk0[m].y; w4.z = w.x; w4.w = w.y;
;                         __builtin_nontemporal_store(w4, (u32x4*)(G + (size_t)g * DFF + ch));
;                     }
	v_cvt_pk_bf16_f32 v6, v16, v17
	v_mov_b64_e32 v[16:17], s[82:83]
	s_movk_i32 s38, 0x1500
	v_mad_i64_i32 v[16:17], s[38:39], v92, s38, v[16:17]
	v_cvt_pk_bf16_f32 v7, v18, v19
	v_cvt_pk_bf16_f32 v4, v52, v53
	v_cvt_pk_bf16_f32 v5, v54, v55
	v_lshl_add_u64 v[16:17], v[160:161], 1, v[16:17]
	global_store_dwordx4 v[16:17], v[4:7], off nt

; DI float shx(float v, int k, int lane) { return __builtin_bit_cast(float, __builtin_amdgcn_ds_bpermute((lane ^ k) << 2, __builtin_bit_cast(int, v))); }
; DI float bf2f(unsigned v16) { return __uint_as_float(v16 << 16); }
; template <int MODE, bool FROM_IN>
; DI void rowop_run(const Params& p, int l, int row0, int nrows_run, int r, int lane, bool dry = false) {
;     ...
; #pragma unroll
;         for (int i = 0; i < 4; ++i) {
;             const int c = (i * 64 + lane) * 4;
;             if (HASY) pa[i] = *(const f32x4*)(gate + c) * *(const f32x4*)(pg + c);
;             pb[i] = *(const f32x4*)(pre + c) * (*(const f32x4*)(ad2 + D + c) + 1.0f);
;             pc[i] = *(const f32x4*)(ad2 + c);
;         }
;     }
;     auto xptr = [&](int row) -> const float* { return row < NLAT ? p.x + (size_t)row * D : p.ctx + (size_t)(row - NLAT) * D; };
;     RowBuf cur, nxt;
;     rowop_load<HASY, FROM_IN>(cur, xptr(row0), p.xres + (size_t)row0 * D, p.Y + (size_t)row0 * D, lane);
;     for (int j = 0; j < nrows_run; ++j) {
;         const int row = row0 + j;
;         if (j + 1 < nrows_run) rowop_load<HASY, FROM_IN>(nxt, xptr(row + 1), p.xres + (size_t)(row + 1) * D, p.Y + (size_t)(row + 1) * D, lane);
;         f32x4 xv[4];
; #pragma unroll
;         for (int i = 0; i < 4; ++i) {
;             if (FROM_IN) xv[i] = cur.x[i];
;             else { const u32x2 w = cur.xb[i]; xv[i][0] = bf2f(w.x & 0xffffu); xv[i][1] = bf2f(w.x >> 16); xv[i][2] = bf2f(w.y & 0xffffu); xv[i][3] = bf2f(w.y >> 16); }
;         }
;         if (HASY) {
;             f32x4 yv[4]; float ss = 0.f;
; #pragma unroll
;             for (int i = 0; i < 4; ++i) {
;                 const u32x2 w = cur.y[i];
;                 yv[i][0] = bf2f(w.x & 0xffffu); yv[i][1] = bf2f(w.x >> 16); yv[i][2] = bf2f(w.y & 0xffffu); yv[i][3] = bf2f(w.y >> 16);
;                 ss += yv[i][0] * yv[i][0] + yv[i][1] * yv[i][1] + yv[i][2] * yv[i][2] + yv[i][3] * yv[i][3];
;             }
; #pragma unroll
;             for (int o = 32; o >= 1; o >>= 1) ss += shx(ss, o, lane);
.LBB0_122:
	v_ashrrev_i32_e32 v0, 7, v19
	v_readlane_b32 s0, v254, 28
	v_ashrrev_i32_e32 v1, 31, v0
	v_readlane_b32 s1, v254, 29
	v_mov_b64_e32 v[2:3], s[84:85]
	v_mov_b32_e32 v31, v129
	v_lshl_add_u64 v[0:1], s[0:1], 0, v[0:1]
	v_mad_u64_u32 v[2:3], s[0:1], v0, s3, v[2:3]
	v_mov_b32_e32 v0, v3
	v_mad_u64_u32 v[0:1], s[0:1], v1, s3, v[0:1]
	v_mov_b32_e32 v3, v0
	s_mov_b64 s[0:1], 0x3000
	v_lshl_add_u64 v[70:71], v[2:3], 0, s[0:1]
	s_mov_b64 s[0:1], 0x2000
	v_lshl_add_u64 v[60:61], v[2:3], 0, s[0:1]
	s_mov_b64 s[0:1], 0x4000
	v_lshl_add_u64 v[0:1], v[60:61], 0, v[128:129]
	v_lshl_add_u64 v[66:67], v[2:3], 0, s[0:1]
	global_load_dwordx4 v[0:3], v[0:1], off
	s_nop 0
	global_load_dwordx4 v[4:7], v[20:21], off
	v_mov_b32_e32 v33, v129
	v_mov_b32_e32 v35, v129
	v_lshlrev_b32_e32 v68, 5, v19
	v_ashrrev_i32_e32 v69, 31, v68
	v_lshlrev_b64 v[68:69], 11, v[68:69]
	s_mov_b32 s23, 0
	s_waitcnt vmcnt(0)
	v_pk_mul_f32 v[38:39], v[0:1], v[4:5]
	v_lshl_add_u64 v[4:5], v[66:67], 0, v[128:129]
	v_pk_mul_f32 v[36:37], v[2:3], v[6:7]
	global_load_dwordx4 v[4:7], v[4:5], off
	s_waitcnt vmcnt(0)
	v_pk_add_f32 v[4:5], v[4:5], 1.0 op_sel_hi:[1,0]
	global_load_dwordx4 v[0:3], v[22:23], off
	v_pk_add_f32 v[6:7], v[6:7], 1.0 op_sel_hi:[1,0]
	s_waitcnt vmcnt(0)
	v_pk_mul_f32 v[42:43], v[0:1], v[4:5]
	v_lshl_add_u64 v[0:1], v[70:71], 0, v[128:129]
	v_lshl_add_u64 v[4:5], v[60:61], 0, v[30:31]
	v_pk_mul_f32 v[40:41], v[2:3], v[6:7]
	global_load_dwordx4 v[0:3], v[0:1], off
	s_nop 0
	global_load_dwordx4 v[4:7], v[4:5], off
	s_nop 0
	global_load_dwordx4 v[8:11], v[20:21], off offset:1024
	s_waitcnt vmcnt(0)
	v_pk_mul_f32 v[46:47], v[4:5], v[8:9]
	v_lshl_add_u64 v[8:9], v[66:67], 0, v[30:31]
	v_pk_mul_f32 v[44:45], v[6:7], v[10:11]
	global_load_dwordx4 v[8:11], v[8:9], off
	s_waitcnt vmcnt(0)
	v_pk_add_f32 v[8:9], v[8:9], 1.0 op_sel_hi:[1,0]
	global_load_dwordx4 v[4:7], v[22:23], off offset:1024
	v_pk_add_f32 v[10:11], v[10:11], 1.0 op_sel_hi:[1,0]
	s_waitcnt vmcnt(0)
	v_pk_mul_f32 v[50:51], v[4:5], v[8:9]
	v_lshl_add_u64 v[4:5], v[70:71], 0, v[30:31]
	v_lshl_add_u64 v[8:9], v[60:61], 0, v[32:33]
	v_pk_mul_f32 v[48:49], v[6:7], v[10:11]
	global_load_dwordx4 v[4:7], v[4:5], off
	s_nop 0
	global_load_dwordx4 v[8:11], v[8:9], off
	s_nop 0
	global_load_dwordx4 v[12:15], v[20:21], off offset:2048
	s_waitcnt vmcnt(0)
	v_pk_mul_f32 v[54:55], v[8:9], v[12:13]
	v_lshl_add_u64 v[12:13], v[66:67], 0, v[32:33]
	v_pk_mul_f32 v[52:53], v[10:11], v[14:15]
	global_load_dwordx4 v[12:15], v[12:13], off
	s_waitcnt vmcnt(0)
	v_pk_add_f32 v[12:13], v[12:13], 1.0 op_sel_hi:[1,0]
	global_load_dwordx4 v[8:11], v[22:23], off offset:2048
	v_pk_add_f32 v[14:15], v[14:15], 1.0 op_sel_hi:[1,0]
	s_waitcnt vmcnt(0)
	v_pk_mul_f32 v[58:59], v[8:9], v[12:13]
	v_lshl_add_u64 v[8:9], v[70:71], 0, v[32:33]
	v_lshl_add_u64 v[12:13], v[60:61], 0, v[34:35]
	v_pk_mul_f32 v[56:57], v[10:11], v[14:15]
	global_load_dwordx4 v[8:11], v[8:9], off
	s_nop 0
	global_load_dwordx4 v[12:15], v[12:13], off
	s_nop 0
	global_load_dwordx4 v[62:65], v[20:21], off offset:3072
	s_waitcnt vmcnt(0)
	v_pk_mul_f32 v[60:61], v[14:15], v[64:65]
	v_lshl_add_u64 v[64:65], v[66:67], 0, v[34:35]
	global_load_dwordx4 v[64:67], v[64:65], off
	v_pk_mul_f32 v[62:63], v[12:13], v[62:63]
	global_load_dwordx4 v[12:15], v[22:23], off offset:3072
	s_waitcnt vmcnt(1)
	v_pk_add_f32 v[66:67], v[66:67], 1.0 op_sel_hi:[1,0]
	v_pk_add_f32 v[72:73], v[64:65], 1.0 op_sel_hi:[1,0]
	s_waitcnt vmcnt(0)
	v_pk_mul_f32 v[64:65], v[14:15], v[66:67]
	v_pk_mul_f32 v[66:67], v[12:13], v[72:73]
	v_lshl_add_u64 v[12:13], v[70:71], 0, v[34:35]
	v_lshl_add_u64 v[70:71], v[24:25], 0, v[68:69]
	v_lshl_add_u64 v[68:69], v[26:27], 0, v[68:69]
	global_load_dwordx4 v[12:15], v[12:13], off
	s_nop 0
	global_load_dwordx2 v[92:93], v[70:71], off nt
	global_load_dwordx2 v[90:91], v[70:71], off offset:512 nt
	global_load_dwordx2 v[88:89], v[70:71], off offset:1024 nt
	global_load_dwordx2 v[84:85], v[70:71], off offset:1536 nt
	global_load_dwordx2 v[100:101], v[68:69], off nt
	global_load_dwordx2 v[98:99], v[68:69], off offset:512 nt
	global_load_dwordx2 v[94:95], v[68:69], off offset:1024 nt
	global_load_dwordx2 v[96:97], v[68:69], off offset:1536 nt
	s_waitcnt vmcnt(0)
	s_branch .LBB0_124
.LBB0_123:
	v_and_b32_e32 v105, 0xffff0000, v100
	v_and_b32_e32 v104, 0xffff0000, v98
	v_lshlrev_b32_e32 v103, 16, v100
	v_lshlrev_b32_e32 v102, 16, v98
	v_lshlrev_b32_e32 v106, 16, v99
	v_and_b32_e32 v100, 0xffff0000, v99
	v_pk_mul_f32 v[98:99], v[104:105], v[104:105]
	v_and_b32_e32 v111, 0xffff0000, v96
	v_and_b32_e32 v110, 0xffff0000, v94
	v_lshlrev_b32_e32 v107, 16, v101
	v_pk_fma_f32 v[98:99], v[102:103], v[102:103], v[98:99]
	v_lshlrev_b32_e32 v109, 16, v96
	v_lshlrev_b32_e32 v108, 16, v94
	v_lshlrev_b32_e32 v112, 16, v95
	v_and_b32_e32 v96, 0xffff0000, v95
	v_pk_mul_f32 v[94:95], v[110:111], v[110:111]
	v_and_b32_e32 v101, 0xffff0000, v101
	v_pk_fma_f32 v[98:99], v[106:107], v[106:107], v[98:99]
	v_lshlrev_b32_e32 v113, 16, v97
	v_pk_fma_f32 v[94:95], v[108:109], v[108:109], v[94:95]
	v_pk_fma_f32 v[98:99], v[100:101], v[100:101], v[98:99]
	v_and_b32_e32 v97, 0xffff0000, v97
	v_pk_fma_f32 v[94:95], v[112:113], v[112:113], v[94:95]
	v_add_f32_e32 v31, v98, v99
	v_pk_fma_f32 v[94:95], v[96:97], v[96:97], v[94:95]
	v_mov_b32_e32 v130, v103
	v_add_f32_e32 v31, v94, v31
	v_add_f32_e32 v31, v31, v95
	ds_bpermute_b32 v33, v121, v31
	v_mov_b32_e32 v103, v104
	v_lshlrev_b32_e32 v98, 16, v90
	v_and_b32_e32 v99, 0xffff0000, v90
	v_mov_b32_e32 v131, v105
	s_waitcnt lgkmcnt(0)
	v_add_f32_e32 v31, v31, v33
	ds_bpermute_b32 v33, v122, v31
	v_mov_b32_e32 v132, v107
	v_mov_b32_e32 v107, v100
	v_lshlrev_b32_e32 v94, 16, v92
	v_and_b32_e32 v95, 0xffff0000, v92
	s_waitcnt lgkmcnt(0)
; DI float shx(float v, int k, int lane) { return __builtin_bit_cast(float, __builtin_amdgcn_ds_bpermute((lane ^ k) << 2, __builtin_bit_cast(int, v))); }
; DI unsigned pack2(float lo, float hi) { f32x2 v = {lo, hi}; bf16x2_t b = __builtin_convertvector(v, bf16x2_t); return __builtin_bit_cast(unsigned, b); }
; template <int MODE, bool FROM_IN>
; DI void rowop_run(const Params& p, int l, int row0, int nrows_run, int r, int lane, bool dry = false) {
;     ...
;             for (int o = 32; o >= 1; o >>= 1) ss += shx(ss, o, lane);
;             const float rinv = rsqrtf(ss * (1.0f / D) + EPS);
; #pragma unroll
;             for (int i = 0; i < 4; ++i) xv[i] = xv[i] + pa[i] * (yv[i] * rinv);
;             if (last) {
; #pragma unroll
;                 for (int i = 0; i < 4; ++i) __builtin_nontemporal_store(xv[i], (f32x4*)(p.out + (size_t)row * D + (i * 64 + lane) * 4));
;             } else if (!dry) {
; #pragma unroll
;                 for (int i = 0; i < 4; ++i) { u32x2 w; w.x = pack2(xv[i][0], xv[i][1]); w.y = pack2(xv[i][2], xv[i][3]); __builtin_nontemporal_store(w, (u32x2*)(p.xres + (size_t)row * D + (i * 64 + lane) * 4)); }
;             }
;         }
;         if (!last) {
;             float ss = 0.f;
; #pragma unroll
;             for (int i = 0; i < 4; ++i) ss += xv[i][0] * xv[i][0] + xv[i][1] * xv[i][1] + xv[i][2] * xv[i][2] + xv[i][3] * xv[i][3];
; #pragma unroll
;             for (int o = 32; o >= 1; o >>= 1) ss += shx(ss, o, lane);
;             const float rinv = rsqrtf(ss * (1.0f / D) + EPS);
; #pragma unroll
;             for (int i = 0; i < 4; ++i) {
;                 const f32x4 hv = xv[i] * rinv * pb[i] + pc[i];
;                 u32x2 w; w.x = pack2(hv[0], hv[1]); w.y = pack2(hv[2], hv[3]);
;                 *(u32x2*)(p.H + (size_t)row * D + (i * 64 + lane) * 4) = w;
;             }
;         }
;         cur = nxt;
	v_add_f32_e32 v31, v31, v33
	ds_bpermute_b32 v33, v123, v31
	v_lshlrev_b32_e32 v90, 16, v91
	v_and_b32_e32 v91, 0xffff0000, v91
	v_mov_b32_e32 v133, v101
	v_lshlrev_b32_e32 v114, 16, v88
	s_waitcnt lgkmcnt(0)
	v_add_f32_e32 v31, v31, v33
	ds_bpermute_b32 v33, v124, v31
	v_and_b32_e32 v115, 0xffff0000, v88
	v_lshlrev_b32_e32 v88, 16, v89
	v_and_b32_e32 v89, 0xffff0000, v89
	v_lshlrev_b32_e32 v92, 16, v93
	s_waitcnt lgkmcnt(0)
	v_add_f32_e32 v31, v31, v33
	ds_bpermute_b32 v33, v125, v31
	v_and_b32_e32 v93, 0xffff0000, v93
	v_lshlrev_b32_e32 v116, 16, v84
	v_and_b32_e32 v117, 0xffff0000, v84
	v_lshlrev_b32_e32 v84, 16, v85
	s_waitcnt lgkmcnt(0)
	v_add_f32_e32 v31, v31, v33
	ds_bpermute_b32 v33, v126, v31
	v_and_b32_e32 v85, 0xffff0000, v85
	v_ashrrev_i32_e32 v87, 31, v86
	v_lshlrev_b64 v[86:87], 11, v[86:87]
	s_add_i32 s23, s23, 1
	s_waitcnt lgkmcnt(0)
	v_add_f32_e32 v31, v31, v33
	v_fmamk_f32 v31, v31, 0x3a800000, v170
	v_mul_f32_e32 v33, 0x4b800000, v31
	v_cmp_gt_f32_e64 s[0:1], s75, v31
	s_cmp_lg_u32 s23, 32
	s_nop 0
	v_cndmask_b32_e64 v31, v31, v33, s[0:1]
	v_rsq_f32_e32 v31, v31
	s_nop 0
	v_mul_f32_e32 v33, 0x45800000, v31
	v_cndmask_b32_e64 v118, v31, v33, s[0:1]
	v_pk_mul_f32 v[102:103], v[102:103], v[118:119] op_sel_hi:[1,0]
	v_pk_mul_f32 v[130:131], v[130:131], v[118:119] op_sel_hi:[1,0]
	v_pk_mul_f32 v[100:101], v[106:107], v[118:119] op_sel_hi:[1,0]
	v_pk_fma_f32 v[98:99], v[46:47], v[102:103], v[98:99]
	v_mov_b32_e32 v102, v112
	v_mov_b32_e32 v103, v96
	v_pk_fma_f32 v[94:95], v[38:39], v[130:131], v[94:95]
	v_pk_fma_f32 v[90:91], v[44:45], v[100:101], v[90:91]
	v_mov_b32_e32 v101, v110
	v_pk_mul_f32 v[102:103], v[102:103], v[118:119] op_sel_hi:[1,0]
	v_mov_b32_e32 v110, v109
	v_mov_b32_e32 v96, v113
	v_pk_mul_f32 v[132:133], v[132:133], v[118:119] op_sel_hi:[1,0]
	v_mov_b32_e32 v100, v108
	v_pk_fma_f32 v[88:89], v[52:53], v[102:103], v[88:89]
	v_pk_mul_f32 v[102:103], v[110:111], v[118:119] op_sel_hi:[1,0]
	v_pk_mul_f32 v[96:97], v[96:97], v[118:119] op_sel_hi:[1,0]
	v_mov_b32_e32 v104, v95
	v_mov_b32_e32 v105, v99
	v_pk_fma_f32 v[92:93], v[36:37], v[132:133], v[92:93]
	v_pk_mul_f32 v[100:101], v[100:101], v[118:119] op_sel_hi:[1,0]
	v_pk_fma_f32 v[84:85], v[60:61], v[96:97], v[84:85]
	v_pk_fma_f32 v[96:97], v[62:63], v[102:103], v[116:117]
	v_mov_b32_e32 v102, v94
	v_mov_b32_e32 v103, v98
	v_pk_mul_f32 v[104:105], v[104:105], v[104:105]
	v_pk_fma_f32 v[100:101], v[54:55], v[100:101], v[114:115]
	v_pk_fma_f32 v[102:103], v[102:103], v[102:103], v[104:105]
	v_mov_b32_e32 v104, v92
	v_mov_b32_e32 v105, v90
	v_pk_fma_f32 v[102:103], v[104:105], v[104:105], v[102:103]
	v_mov_b32_e32 v104, v93
	v_mov_b32_e32 v105, v91
	v_mov_b32_e32 v106, v97
	v_mov_b32_e32 v107, v101
	v_pk_fma_f32 v[102:103], v[104:105], v[104:105], v[102:103]
	v_mov_b32_e32 v104, v96
	v_mov_b32_e32 v105, v100
	v_pk_mul_f32 v[106:107], v[106:107], v[106:107]
	v_add_f32_e32 v31, v102, v103
	v_pk_fma_f32 v[104:105], v[104:105], v[104:105], v[106:107]
	v_mov_b32_e32 v106, v84
	v_mov_b32_e32 v107, v88
	v_pk_fma_f32 v[104:105], v[106:107], v[106:107], v[104:105]
	v_mov_b32_e32 v106, v85
	v_mov_b32_e32 v107, v89
	v_pk_fma_f32 v[104:105], v[106:107], v[106:107], v[104:105]
	v_cvt_pk_bf16_f32 v102, v94, v95
	v_add_f32_e32 v31, v105, v31
	v_add_f32_e32 v31, v104, v31
	ds_bpermute_b32 v33, v121, v31
	v_cvt_pk_bf16_f32 v103, v92, v93
	v_lshl_add_u64 v[104:105], v[24:25], 0, v[86:87]
	global_store_dwordx2 v[104:105], v[102:103], off nt
	v_cvt_pk_bf16_f32 v102, v98, v99
	s_waitcnt lgkmcnt(0)
	v_add_f32_e32 v31, v31, v33
	ds_bpermute_b32 v33, v122, v31
	v_cvt_pk_bf16_f32 v103, v90, v91
	global_store_dwordx2 v[104:105], v[102:103], off offset:512 nt
	v_cvt_pk_bf16_f32 v102, v100, v101
	v_cvt_pk_bf16_f32 v103, v88, v89
	s_waitcnt lgkmcnt(0)
	v_add_f32_e32 v31, v31, v33
	ds_bpermute_b32 v33, v123, v31
	global_store_dwordx2 v[104:105], v[102:103], off offset:1024 nt
	v_cvt_pk_bf16_f32 v102, v96, v97
	v_cvt_pk_bf16_f32 v103, v84, v85
	global_store_dwordx2 v[104:105], v[102:103], off offset:1536 nt
	s_waitcnt lgkmcnt(0)
	v_add_f32_e32 v31, v31, v33
	ds_bpermute_b32 v33, v124, v31
	v_lshl_add_u64 v[86:87], v[28:29], 0, v[86:87]
	s_waitcnt lgkmcnt(0)
	v_add_f32_e32 v31, v31, v33
	ds_bpermute_b32 v33, v125, v31
	s_waitcnt lgkmcnt(0)
	v_add_f32_e32 v31, v31, v33
	ds_bpermute_b32 v33, v126, v31
	s_waitcnt lgkmcnt(0)
	v_add_f32_e32 v31, v31, v33
	v_fmamk_f32 v31, v31, 0x3a800000, v170
	v_mul_f32_e32 v33, 0x4b800000, v31
	v_cmp_gt_f32_e64 s[0:1], s75, v31
	s_nop 1
	v_cndmask_b32_e64 v31, v31, v33, s[0:1]
	v_rsq_f32_e32 v31, v31
	s_nop 0
	v_mul_f32_e32 v33, 0x45800000, v31
	v_cndmask_b32_e64 v102, v31, v33, s[0:1]
	v_pk_mul_f32 v[94:95], v[94:95], v[102:103] op_sel_hi:[1,0]
	v_pk_mul_f32 v[92:93], v[92:93], v[102:103] op_sel_hi:[1,0]
	v_pk_fma_f32 v[94:95], v[42:43], v[94:95], v[0:1]
	v_pk_fma_f32 v[92:93], v[40:41], v[92:93], v[2:3]
	v_cvt_pk_bf16_f32 v94, v94, v95
	v_cvt_pk_bf16_f32 v95, v92, v93
	v_pk_mul_f32 v[92:93], v[98:99], v[102:103] op_sel_hi:[1,0]
	v_pk_mul_f32 v[90:91], v[90:91], v[102:103] op_sel_hi:[1,0]
	v_pk_fma_f32 v[92:93], v[50:51], v[92:93], v[4:5]
	v_pk_fma_f32 v[90:91], v[48:49], v[90:91], v[6:7]
	v_cvt_pk_bf16_f32 v92, v92, v93
	v_cvt_pk_bf16_f32 v93, v90, v91
	v_pk_mul_f32 v[90:91], v[100:101], v[102:103] op_sel_hi:[1,0]
	v_pk_mul_f32 v[88:89], v[88:89], v[102:103] op_sel_hi:[1,0]
	v_pk_fma_f32 v[90:91], v[58:59], v[90:91], v[8:9]
	v_pk_fma_f32 v[88:89], v[56:57], v[88:89], v[10:11]
	v_cvt_pk_bf16_f32 v90, v90, v91
	v_cvt_pk_bf16_f32 v91, v88, v89
	v_pk_mul_f32 v[88:89], v[96:97], v[102:103] op_sel_hi:[1,0]
	v_pk_mul_f32 v[84:85], v[84:85], v[102:103] op_sel_hi:[1,0]
	v_pk_fma_f32 v[88:89], v[66:67], v[88:89], v[12:13]
	v_pk_fma_f32 v[84:85], v[64:65], v[84:85], v[14:15]
	v_cvt_pk_bf16_f32 v88, v88, v89
	v_cvt_pk_bf16_f32 v89, v84, v85
	global_store_dwordx2 v[86:87], v[94:95], off
	global_store_dwordx2 v[86:87], v[92:93], off offset:512
	global_store_dwordx2 v[86:87], v[90:91], off offset:1024
	global_store_dwordx2 v[86:87], v[88:89], off offset:1536
	s_waitcnt vmcnt(8)
	v_mov_b64_e32 v[94:95], v[80:81]
	v_mov_b64_e32 v[98:99], v[78:79]
	v_mov_b64_e32 v[100:101], v[76:77]
	v_mov_b64_e32 v[84:85], v[74:75]
	v_mov_b64_e32 v[88:89], v[72:73]
	v_mov_b64_e32 v[90:91], v[70:71]
	v_mov_b64_e32 v[92:93], v[68:69]
	v_mov_b64_e32 v[96:97], v[82:83]
	s_cbranch_scc0 .LBB0_121

; DI float bf2f(unsigned v16) { return __uint_as_float(v16 << 16); }
; template <int MODE, bool FROM_IN>
; DI void rowop_run(const Params& p, int l, int row0, int nrows_run, int r, int lane, bool dry = false) {
;     ...
; #pragma unroll
;         for (int i = 0; i < 4; ++i) {
;             const int c = (i * 64 + lane) * 4;
;             if (HASY) pa[i] = *(const f32x4*)(gate + c) * *(const f32x4*)(pg + c);
;             pb[i] = *(const f32x4*)(pre + c) * (*(const f32x4*)(ad2 + D + c) + 1.0f);
;             pc[i] = *(const f32x4*)(ad2 + c);
;         }
;     }
;     auto xptr = [&](int row) -> const float* { return row < NLAT ? p.x + (size_t)row * D : p.ctx + (size_t)(row - NLAT) * D; };
;     RowBuf cur, nxt;
;     rowop_load<HASY, FROM_IN>(cur, xptr(row0), p.xres + (size_t)row0 * D, p.Y + (size_t)row0 * D, lane);
;     for (int j = 0; j < nrows_run; ++j) {
;         const int row = row0 + j;
;         if (j + 1 < nrows_run) rowop_load<HASY, FROM_IN>(nxt, xptr(row + 1), p.xres + (size_t)(row + 1) * D, p.Y + (size_t)(row + 1) * D, lane);
;         f32x4 xv[4];
; #pragma unroll
;         for (int i = 0; i < 4; ++i) {
;             if (FROM_IN) xv[i] = cur.x[i];
;             else { const u32x2 w = cur.xb[i]; xv[i][0] = bf2f(w.x & 0xffffu); xv[i][1] = bf2f(w.x >> 16); xv[i][2] = bf2f(w.y & 0xffffu); xv[i][3] = bf2f(w.y >> 16); }
.LBB0_129:
	global_load_dwordx4 v[0:3], v[20:21], off
	global_load_dwordx4 v[4:7], v[22:23], off
	v_lshlrev_b32_e32 v88, 1, v120
	v_add_u32_e32 v50, 0x10000, v88
	v_ashrrev_i32_e32 v51, 31, v50
	s_mov_b32 s22, 0
	s_mov_b64 s[40:41], -1
	s_mov_b64 s[38:39], 0
	s_waitcnt vmcnt(0)
	v_pk_mul_f32 v[52:53], v[2:3], v[6:7]
	v_pk_mul_f32 v[54:55], v[0:1], v[4:5]
	global_load_dwordx4 v[0:3], v[24:25], off
	global_load_dwordx4 v[4:7], v[26:27], off
	s_waitcnt vmcnt(0)
	v_pk_add_f32 v[6:7], v[6:7], 1.0 op_sel_hi:[1,0]
	v_pk_add_f32 v[4:5], v[4:5], 1.0 op_sel_hi:[1,0]
	v_pk_mul_f32 v[56:57], v[2:3], v[6:7]
	v_pk_mul_f32 v[58:59], v[0:1], v[4:5]
	global_load_dwordx4 v[0:3], v[28:29], off
	global_load_dwordx4 v[4:7], v[30:31], off
	global_load_dwordx4 v[8:11], v[22:23], off offset:1024
	s_waitcnt vmcnt(0)
	v_pk_mul_f32 v[60:61], v[6:7], v[10:11]
	v_pk_mul_f32 v[62:63], v[4:5], v[8:9]
	global_load_dwordx4 v[4:7], v[24:25], off offset:1024
	global_load_dwordx4 v[8:11], v[32:33], off
	s_waitcnt vmcnt(0)
	v_pk_add_f32 v[10:11], v[10:11], 1.0 op_sel_hi:[1,0]
	v_pk_add_f32 v[8:9], v[8:9], 1.0 op_sel_hi:[1,0]
	v_pk_mul_f32 v[64:65], v[6:7], v[10:11]
	v_pk_mul_f32 v[66:67], v[4:5], v[8:9]
	global_load_dwordx4 v[4:7], v[34:35], off
	global_load_dwordx4 v[8:11], v[36:37], off
	global_load_dwordx4 v[12:15], v[22:23], off offset:2048
	s_waitcnt vmcnt(0)
	v_pk_mul_f32 v[68:69], v[10:11], v[14:15]
	v_pk_mul_f32 v[70:71], v[8:9], v[12:13]
	global_load_dwordx4 v[8:11], v[24:25], off offset:2048
	global_load_dwordx4 v[12:15], v[38:39], off
	s_waitcnt vmcnt(0)
	v_pk_add_f32 v[14:15], v[14:15], 1.0 op_sel_hi:[1,0]
	v_pk_add_f32 v[12:13], v[12:13], 1.0 op_sel_hi:[1,0]
	v_pk_mul_f32 v[72:73], v[10:11], v[14:15]
	v_pk_mul_f32 v[74:75], v[8:9], v[12:13]
	global_load_dwordx4 v[8:11], v[40:41], off
	global_load_dwordx4 v[12:15], v[18:19], off
	global_load_dwordx4 v[78:81], v[22:23], off offset:3072
	s_waitcnt vmcnt(0)
	v_pk_mul_f32 v[76:77], v[14:15], v[80:81]
	v_pk_mul_f32 v[78:79], v[12:13], v[78:79]
	global_load_dwordx4 v[12:15], v[24:25], off offset:3072
	global_load_dwordx4 v[80:83], v[42:43], off
	s_waitcnt vmcnt(0)
	v_pk_add_f32 v[82:83], v[82:83], 1.0 op_sel_hi:[1,0]
	v_pk_add_f32 v[84:85], v[80:81], 1.0 op_sel_hi:[1,0]
	v_pk_mul_f32 v[80:81], v[14:15], v[82:83]
	v_pk_mul_f32 v[82:83], v[12:13], v[84:85]
	v_lshlrev_b64 v[84:85], 11, v[50:51]
	v_lshl_add_u64 v[86:87], v[46:47], 0, v[84:85]
	v_lshl_add_u64 v[84:85], v[48:49], 0, v[84:85]
	global_load_dwordx4 v[12:15], v[44:45], off
	global_load_dwordx2 v[110:111], v[86:87], off nt
	global_load_dwordx2 v[108:109], v[86:87], off offset:512 nt
	global_load_dwordx2 v[106:107], v[86:87], off offset:1024 nt
	global_load_dwordx2 v[104:105], v[86:87], off offset:1536 nt
	global_load_dwordx2 v[118:119], v[84:85], off nt
	global_load_dwordx2 v[116:117], v[84:85], off offset:512 nt
	global_load_dwordx2 v[112:113], v[84:85], off offset:1024 nt
	global_load_dwordx2 v[114:115], v[84:85], off offset:1536 nt
	v_add_u32_e32 v84, 0x10001, v88
	v_ashrrev_i32_e32 v85, 31, v84
	v_lshlrev_b64 v[86:87], 11, v[84:85]
	v_lshl_add_u64 v[84:85], v[46:47], 0, v[86:87]
	v_lshl_add_u64 v[86:87], v[48:49], 0, v[86:87]
	s_waitcnt vmcnt(0)
	s_branch .LBB0_131
.LBB0_130:
	v_and_b32_e32 v133, 0xffff0000, v118
	v_and_b32_e32 v132, 0xffff0000, v116
	v_lshlrev_b32_e32 v131, 16, v118
	v_lshlrev_b32_e32 v130, 16, v116
	v_lshlrev_b32_e32 v134, 16, v117
	v_and_b32_e32 v118, 0xffff0000, v117
	v_pk_mul_f32 v[116:117], v[132:133], v[132:133]
	v_and_b32_e32 v139, 0xffff0000, v114
	v_and_b32_e32 v138, 0xffff0000, v112
	v_lshlrev_b32_e32 v135, 16, v119
	v_pk_fma_f32 v[116:117], v[130:131], v[130:131], v[116:117]
	v_lshlrev_b32_e32 v137, 16, v114
	v_lshlrev_b32_e32 v136, 16, v112
	v_lshlrev_b32_e32 v140, 16, v113
	v_and_b32_e32 v114, 0xffff0000, v113
	v_pk_mul_f32 v[112:113], v[138:139], v[138:139]
	v_and_b32_e32 v119, 0xffff0000, v119
	v_pk_fma_f32 v[116:117], v[134:135], v[134:135], v[116:117]
	v_lshlrev_b32_e32 v141, 16, v115
	v_pk_fma_f32 v[112:113], v[136:137], v[136:137], v[112:113]
	v_pk_fma_f32 v[116:117], v[118:119], v[118:119], v[116:117]
	v_and_b32_e32 v115, 0xffff0000, v115
	v_pk_fma_f32 v[112:113], v[140:141], v[140:141], v[112:113]
	v_add_f32_e32 v51, v116, v117
	v_pk_fma_f32 v[112:113], v[114:115], v[114:115], v[112:113]
	v_mov_b32_e32 v146, v131
	v_add_f32_e32 v51, v112, v51
	v_add_f32_e32 v51, v51, v113
	ds_bpermute_b32 v112, v121, v51
	v_mov_b32_e32 v131, v132
	v_lshlrev_b32_e32 v116, 16, v108
	v_mov_b32_e32 v147, v133
	v_mov_b32_e32 v148, v135
	s_waitcnt lgkmcnt(0)
	v_add_f32_e32 v51, v51, v112
	ds_bpermute_b32 v112, v122, v51
	v_mov_b32_e32 v135, v118
	v_mov_b32_e32 v149, v119
	v_lshlrev_b32_e32 v142, 16, v106
	v_and_b32_e32 v143, 0xffff0000, v106
	s_waitcnt lgkmcnt(0)
	v_add_f32_e32 v51, v51, v112
	ds_bpermute_b32 v113, v123, v51
	v_lshlrev_b32_e32 v112, 16, v110
	v_lshlrev_b32_e32 v106, 16, v107
	v_and_b32_e32 v107, 0xffff0000, v107
	v_lshlrev_b32_e32 v144, 16, v104
	s_waitcnt lgkmcnt(0)
	v_add_f32_e32 v51, v51, v113
	ds_bpermute_b32 v117, v124, v51
	v_and_b32_e32 v113, 0xffff0000, v110
	v_lshlrev_b32_e32 v110, 16, v111
	v_and_b32_e32 v111, 0xffff0000, v111
	v_and_b32_e32 v145, 0xffff0000, v104
	s_waitcnt lgkmcnt(0)
	v_add_f32_e32 v51, v51, v117
	ds_bpermute_b32 v127, v125, v51
	v_and_b32_e32 v117, 0xffff0000, v108
	v_lshlrev_b32_e32 v108, 16, v109
	v_and_b32_e32 v109, 0xffff0000, v109
	v_lshlrev_b32_e32 v104, 16, v105
	s_waitcnt lgkmcnt(0)
	v_add_f32_e32 v51, v51, v127
	ds_bpermute_b32 v127, v126, v51
	v_and_b32_e32 v105, 0xffff0000, v105
	s_mov_b64 s[40:41], 0
	s_waitcnt lgkmcnt(0)
; DI float shx(float v, int k, int lane) { return __builtin_bit_cast(float, __builtin_amdgcn_ds_bpermute((lane ^ k) << 2, __builtin_bit_cast(int, v))); }
; DI unsigned pack2(float lo, float hi) { f32x2 v = {lo, hi}; bf16x2_t b = __builtin_convertvector(v, bf16x2_t); return __builtin_bit_cast(unsigned, b); }
; DI float bf2f(unsigned v16) { return __uint_as_float(v16 << 16); }
; template <int MODE, bool FROM_IN>
; DI void rowop_run(const Params& p, int l, int row0, int nrows_run, int r, int lane, bool dry = false) {
;     ...
;         if (HASY) {
;             f32x4 yv[4]; float ss = 0.f;
; #pragma unroll
;             for (int i = 0; i < 4; ++i) {
;                 const u32x2 w = cur.y[i];
;                 yv[i][0] = bf2f(w.x & 0xffffu); yv[i][1] = bf2f(w.x >> 16); yv[i][2] = bf2f(w.y & 0xffffu); yv[i][3] = bf2f(w.y >> 16);
;                 ss += yv[i][0] * yv[i][0] + yv[i][1] * yv[i][1] + yv[i][2] * yv[i][2] + yv[i][3] * yv[i][3];
;             }
; #pragma unroll
;             for (int o = 32; o >= 1; o >>= 1) ss += shx(ss, o, lane);
;             const float rinv = rsqrtf(ss * (1.0f / D) + EPS);
; #pragma unroll
;             for (int i = 0; i < 4; ++i) xv[i] = xv[i] + pa[i] * (yv[i] * rinv);
;             if (last) {
; #pragma unroll
;                 for (int i = 0; i < 4; ++i) __builtin_nontemporal_store(xv[i], (f32x4*)(p.out + (size_t)row * D + (i * 64 + lane) * 4));
;             } else if (!dry) {
; #pragma unroll
;                 for (int i = 0; i < 4; ++i) { u32x2 w; w.x = pack2(xv[i][0], xv[i][1]); w.y = pack2(xv[i][2], xv[i][3]); __builtin_nontemporal_store(w, (u32x2*)(p.xres + (size_t)row * D + (i * 64 + lane) * 4)); }
;             }
;         }
;         if (!last) {
;             float ss = 0.f;
; #pragma unroll
;             for (int i = 0; i < 4; ++i) ss += xv[i][0] * xv[i][0] + xv[i][1] * xv[i][1] + xv[i][2] * xv[i][2] + xv[i][3] * xv[i][3];
; #pragma unroll
;             for (int o = 32; o >= 1; o >>= 1) ss += shx(ss, o, lane);
;             const float rinv = rsqrtf(ss * (1.0f / D) + EPS);
; #pragma unroll
;             for (int i = 0; i < 4; ++i) {
;                 const f32x4 hv = xv[i] * rinv * pb[i] + pc[i];
;                 u32x2 w; w.x = pack2(hv[0], hv[1]); w.y = pack2(hv[2], hv[3]);
;                 *(u32x2*)(p.H + (size_t)row * D + (i * 64 + lane) * 4) = w;
;             }
;         }
;         cur = nxt;
	v_add_f32_e32 v51, v51, v127
	v_fmamk_f32 v51, v51, 0x3a800000, v170
	v_mul_f32_e32 v127, 0x4b800000, v51
	v_cmp_gt_f32_e32 vcc, s75, v51
	s_nop 1
	v_cndmask_b32_e32 v51, v51, v127, vcc
	v_rsq_f32_e32 v51, v51
	s_nop 0
	v_mul_f32_e32 v127, 0x45800000, v51
	v_cndmask_b32_e32 v128, v51, v127, vcc
	v_pk_mul_f32 v[130:131], v[130:131], v[128:129] op_sel_hi:[1,0]
	v_pk_mul_f32 v[146:147], v[146:147], v[128:129] op_sel_hi:[1,0]
	v_pk_mul_f32 v[118:119], v[134:135], v[128:129] op_sel_hi:[1,0]
	v_pk_fma_f32 v[116:117], v[62:63], v[130:131], v[116:117]
	v_mov_b32_e32 v130, v140
	v_mov_b32_e32 v131, v114
	v_pk_fma_f32 v[112:113], v[54:55], v[146:147], v[112:113]
	v_pk_fma_f32 v[108:109], v[60:61], v[118:119], v[108:109]
	v_mov_b32_e32 v119, v138
	v_pk_mul_f32 v[130:131], v[130:131], v[128:129] op_sel_hi:[1,0]
	v_mov_b32_e32 v138, v137
	v_mov_b32_e32 v114, v141
	v_pk_mul_f32 v[148:149], v[148:149], v[128:129] op_sel_hi:[1,0]
	v_mov_b32_e32 v118, v136
	v_pk_fma_f32 v[106:107], v[68:69], v[130:131], v[106:107]
	v_pk_mul_f32 v[130:131], v[138:139], v[128:129] op_sel_hi:[1,0]
	v_pk_mul_f32 v[114:115], v[114:115], v[128:129] op_sel_hi:[1,0]
	v_mov_b32_e32 v132, v113
	v_mov_b32_e32 v133, v117
	v_pk_fma_f32 v[110:111], v[52:53], v[148:149], v[110:111]
	v_pk_mul_f32 v[118:119], v[118:119], v[128:129] op_sel_hi:[1,0]
	v_pk_fma_f32 v[104:105], v[76:77], v[114:115], v[104:105]
	v_pk_fma_f32 v[114:115], v[78:79], v[130:131], v[144:145]
	v_mov_b32_e32 v130, v112
	v_mov_b32_e32 v131, v116
	v_pk_mul_f32 v[132:133], v[132:133], v[132:133]
	v_pk_fma_f32 v[118:119], v[70:71], v[118:119], v[142:143]
	v_pk_fma_f32 v[130:131], v[130:131], v[130:131], v[132:133]
	v_mov_b32_e32 v132, v110
	v_mov_b32_e32 v133, v108
	v_pk_fma_f32 v[130:131], v[132:133], v[132:133], v[130:131]
	v_mov_b32_e32 v132, v111
	v_mov_b32_e32 v133, v109
	v_mov_b32_e32 v134, v115
	v_mov_b32_e32 v135, v119
	v_pk_fma_f32 v[130:131], v[132:133], v[132:133], v[130:131]
	v_mov_b32_e32 v132, v114
	v_mov_b32_e32 v133, v118
	v_pk_mul_f32 v[134:135], v[134:135], v[134:135]
	v_add_f32_e32 v51, v130, v131
	v_pk_fma_f32 v[132:133], v[132:133], v[132:133], v[134:135]
	v_mov_b32_e32 v134, v104
	v_mov_b32_e32 v135, v106
	v_pk_fma_f32 v[132:133], v[134:135], v[134:135], v[132:133]
	v_mov_b32_e32 v134, v105
	v_mov_b32_e32 v135, v107
	v_pk_fma_f32 v[132:133], v[134:135], v[134:135], v[132:133]
	v_or_b32_e32 v130, s22, v50
	v_add_f32_e32 v51, v133, v51
	v_add_f32_e32 v51, v132, v51
	ds_bpermute_b32 v127, v121, v51
	v_ashrrev_i32_e32 v131, 31, v130
	v_lshlrev_b64 v[130:131], 11, v[130:131]
	v_cvt_pk_bf16_f32 v132, v112, v113
	v_cvt_pk_bf16_f32 v133, v110, v111
	s_waitcnt lgkmcnt(0)
	v_add_f32_e32 v51, v51, v127
	ds_bpermute_b32 v127, v122, v51
	v_lshl_add_u64 v[134:135], v[46:47], 0, v[130:131]
	global_store_dwordx2 v[134:135], v[132:133], off nt
	v_cvt_pk_bf16_f32 v132, v116, v117
	v_cvt_pk_bf16_f32 v133, v108, v109
	s_waitcnt lgkmcnt(0)
	v_add_f32_e32 v51, v51, v127
	ds_bpermute_b32 v127, v123, v51
	global_store_dwordx2 v[134:135], v[132:133], off offset:512 nt
	v_cvt_pk_bf16_f32 v132, v118, v119
	v_cvt_pk_bf16_f32 v133, v106, v107
	global_store_dwordx2 v[134:135], v[132:133], off offset:1024 nt
	s_waitcnt lgkmcnt(0)
	v_add_f32_e32 v51, v51, v127
	ds_bpermute_b32 v127, v124, v51
	v_cvt_pk_bf16_f32 v132, v114, v115
	v_cvt_pk_bf16_f32 v133, v104, v105
	global_store_dwordx2 v[134:135], v[132:133], off offset:1536 nt
	s_mov_b32 s22, 1
	s_waitcnt lgkmcnt(0)
	v_add_f32_e32 v51, v51, v127
	ds_bpermute_b32 v127, v125, v51
	s_waitcnt lgkmcnt(0)
	v_add_f32_e32 v51, v51, v127
	ds_bpermute_b32 v127, v126, v51
	s_waitcnt lgkmcnt(0)
	v_add_f32_e32 v51, v51, v127
	v_fmamk_f32 v51, v51, 0x3a800000, v170
	v_mul_f32_e32 v127, 0x4b800000, v51
	v_cmp_gt_f32_e32 vcc, s75, v51
	s_nop 1
	v_cndmask_b32_e32 v51, v51, v127, vcc
	v_rsq_f32_e32 v51, v51
	s_nop 0
	v_mul_f32_e32 v127, 0x45800000, v51
	v_cndmask_b32_e32 v128, v51, v127, vcc
	v_pk_mul_f32 v[112:113], v[112:113], v[128:129] op_sel_hi:[1,0]
	v_pk_mul_f32 v[110:111], v[110:111], v[128:129] op_sel_hi:[1,0]
	v_pk_fma_f32 v[112:113], v[58:59], v[112:113], v[0:1]
	v_pk_fma_f32 v[110:111], v[56:57], v[110:111], v[2:3]
	v_cvt_pk_bf16_f32 v112, v112, v113
	v_cvt_pk_bf16_f32 v113, v110, v111
	v_lshl_add_u64 v[110:111], v[16:17], 0, v[130:131]
	global_store_dwordx2 v[110:111], v[112:113], off
	v_pk_mul_f32 v[112:113], v[116:117], v[128:129] op_sel_hi:[1,0]
	v_pk_mul_f32 v[108:109], v[108:109], v[128:129] op_sel_hi:[1,0]
	v_pk_fma_f32 v[112:113], v[66:67], v[112:113], v[4:5]
	v_pk_fma_f32 v[108:109], v[64:65], v[108:109], v[6:7]
	v_cvt_pk_bf16_f32 v112, v112, v113
	v_cvt_pk_bf16_f32 v113, v108, v109
	v_pk_mul_f32 v[108:109], v[118:119], v[128:129] op_sel_hi:[1,0]
	v_pk_mul_f32 v[106:107], v[106:107], v[128:129] op_sel_hi:[1,0]
	v_pk_fma_f32 v[108:109], v[74:75], v[108:109], v[8:9]
	v_pk_fma_f32 v[106:107], v[72:73], v[106:107], v[10:11]
	v_cvt_pk_bf16_f32 v108, v108, v109
	v_cvt_pk_bf16_f32 v109, v106, v107
	v_pk_mul_f32 v[106:107], v[114:115], v[128:129] op_sel_hi:[1,0]
	v_pk_mul_f32 v[104:105], v[104:105], v[128:129] op_sel_hi:[1,0]
	v_pk_fma_f32 v[106:107], v[82:83], v[106:107], v[12:13]
	v_pk_fma_f32 v[104:105], v[80:81], v[104:105], v[14:15]
	v_cvt_pk_bf16_f32 v106, v106, v107
	v_cvt_pk_bf16_f32 v107, v104, v105
	global_store_dwordx2 v[110:111], v[112:113], off offset:512
	global_store_dwordx2 v[110:111], v[108:109], off offset:1024
	global_store_dwordx2 v[110:111], v[106:107], off offset:1536
	s_andn2_b64 vcc, exec, s[38:39]
	s_waitcnt vmcnt(8)
	v_mov_b64_e32 v[112:113], v[100:101]
	v_mov_b64_e32 v[116:117], v[98:99]
	v_mov_b64_e32 v[118:119], v[96:97]
	v_mov_b64_e32 v[104:105], v[94:95]
	v_mov_b64_e32 v[106:107], v[92:93]
	v_mov_b64_e32 v[108:109], v[90:91]
	v_mov_b64_e32 v[110:111], v[88:89]
	v_mov_b64_e32 v[114:115], v[102:103]
	s_mov_b64 s[38:39], -1
	s_cbranch_vccz .LBB0_128

; #define LAS __attribute__((address_space(3)))
; DI unsigned pack2(float lo, float hi) { f32x2 v = {lo, hi}; bf16x2_t b = __builtin_convertvector(v, bf16x2_t); return __builtin_bit_cast(unsigned, b); }
; #define MFMA32(a, b, c) __builtin_amdgcn_mfma_f32_32x32x16_bf16((a), (b), (c), 0, 0, 0)
; DI float fast_exp2(float x) { return __builtin_amdgcn_exp2f(x); }
; template <bool FIRST, bool MASKED>
; DI void attn2_step(f32x16 (&o)[2][2], float (&m_ref)[2], float (&lsum)[2], const bf16x8 (&qf)[2][4], const lchar* Kl, const lchar* Vl, int lane, int kp0, int qw0, float m_init, float l0) {
;     ...
;     bf16x8 pf[2][4];
; #pragma unroll
;     for (int q = 0; q < 2; ++q) {
;         float ps = 0.f;
; #pragma unroll
;         for (int kt = 0; kt < 2; ++kt)
; #pragma unroll
;             for (int i = 0; i < 16; ++i) { const float pv = fast_exp2(sc[q][kt][i]); sc[q][kt][i] = pv; ps += pv; }
;         lsum[q] += ps;
; #pragma unroll
;         for (int s = 0; s < 4; ++s) {
;             u32x4 w;
;             const int kt = s >> 1, b = 8 * (s & 1);
;             w.x = pack2(sc[q][kt][b + 0], sc[q][kt][b + 1]); w.y = pack2(sc[q][kt][b + 2], sc[q][kt][b + 3]);
;             w.z = pack2(sc[q][kt][b + 4], sc[q][kt][b + 5]); w.w = pack2(sc[q][kt][b + 6], sc[q][kt][b + 7]);
;             pf[q][s] = __builtin_bit_cast(bf16x8, w);
;         }
;     }
;     {
;         const int qq = (lane & 15) >> 2, pp = lane & 3, g16 = (lane >> 4) & 1;
;         const lchar* vb = Vl + (4 * h + qq) * VSTR + (16 * g16 + 4 * pp) * 2;
; #pragma unroll
;         for (int s = 0; s < 4; ++s)
; #pragma unroll
;             for (int dt = 0; dt < 2; ++dt) {
;                 const s16x4 lo = __builtin_amdgcn_ds_read_tr16_b64_v4i16((LAS s16x4*)(vb + (16 * s) * VSTR + dt * 64));
;                 const s16x4 hi = __builtin_amdgcn_ds_read_tr16_b64_v4i16((LAS s16x4*)(vb + (16 * s + 8) * VSTR + dt * 64));
;                 const bf16x8 vf = __builtin_shufflevector(lo, hi, 0, 1, 2, 3, 4, 5, 6, 7);
; #pragma unroll
;                 for (int q = 0; q < 2; ++q) o[q][dt] = MFMA32(vf, pf[q][s], o[q][dt]);
;             }
;     }
.LBB0_208:
	s_mulk_i32 s99, 0x3000
	v_or_b32_e32 v244, s99, v192
	ds_read_b64_tr_b16 v[208:209], v244 offset:18432
	ds_read_b64_tr_b16 v[210:211], v244 offset:19968
	ds_read_b64_tr_b16 v[212:213], v244 offset:18496
	ds_read_b64_tr_b16 v[214:215], v244 offset:20032
	ds_read_b64_tr_b16 v[216:217], v244 offset:21504
	ds_read_b64_tr_b16 v[218:219], v244 offset:23040
	ds_read_b64_tr_b16 v[220:221], v244 offset:21568
	ds_read_b64_tr_b16 v[222:223], v244 offset:23104
	ds_read_b64_tr_b16 v[224:225], v244 offset:24576
	ds_read_b64_tr_b16 v[226:227], v244 offset:26112
	ds_read_b64_tr_b16 v[228:229], v244 offset:24640
	ds_read_b64_tr_b16 v[230:231], v244 offset:26176
	ds_read_b64_tr_b16 v[232:233], v244 offset:27648
	ds_read_b64_tr_b16 v[234:235], v244 offset:29184
	ds_read_b64_tr_b16 v[236:237], v244 offset:27712
	ds_read_b64_tr_b16 v[238:239], v244 offset:29248
	v_exp_f32_e32 v112, v112
	v_exp_f32_e32 v113, v113
	v_exp_f32_e32 v114, v114
	v_exp_f32_e32 v115, v115
	v_add_f32_e32 v240, v112, v114
	v_add_f32_e32 v241, v113, v115
	v_exp_f32_e32 v116, v116
	v_exp_f32_e32 v117, v117
	v_exp_f32_e32 v118, v118
	v_exp_f32_e32 v119, v119
	v_add_f32_e32 v240, v240, v116
	v_add_f32_e32 v241, v241, v117
	v_add_f32_e32 v240, v240, v118
	v_add_f32_e32 v241, v241, v119
	v_cvt_pk_bf16_f32 v112, v112, v113
	v_cvt_pk_bf16_f32 v113, v114, v115
	v_cvt_pk_bf16_f32 v114, v116, v117
	v_cvt_pk_bf16_f32 v115, v118, v119
	v_exp_f32_e32 v96, v96
	v_exp_f32_e32 v97, v97
	v_exp_f32_e32 v98, v98
	v_exp_f32_e32 v99, v99
	s_waitcnt lgkmcnt(0)
	v_mfma_f32_32x32x16_bf16 v[32:47], v[208:211], v[112:115], v[32:47]
	v_add_f32_e32 v242, v96, v98
	v_add_f32_e32 v243, v97, v99
	v_exp_f32_e32 v100, v100
	v_exp_f32_e32 v101, v101
	v_exp_f32_e32 v102, v102
	v_exp_f32_e32 v103, v103
	v_add_f32_e32 v242, v242, v100
	v_add_f32_e32 v243, v243, v101
	v_mfma_f32_32x32x16_bf16 v[48:63], v[212:215], v[112:115], v[48:63]
	v_add_f32_e32 v242, v242, v102
	v_add_f32_e32 v243, v243, v103
	v_cvt_pk_bf16_f32 v96, v96, v97
	v_cvt_pk_bf16_f32 v97, v98, v99
	v_cvt_pk_bf16_f32 v98, v100, v101
	v_cvt_pk_bf16_f32 v99, v102, v103
	v_exp_f32_e32 v120, v120
	v_exp_f32_e32 v121, v121
	v_exp_f32_e32 v122, v122
	v_exp_f32_e32 v123, v123
	v_mfma_f32_32x32x16_bf16 v[16:31], v[208:211], v[96:99], v[16:31]
	v_add_f32_e32 v240, v240, v120
	v_add_f32_e32 v241, v241, v121
	v_exp_f32_e32 v124, v124
	v_exp_f32_e32 v125, v125
	v_add_f32_e32 v240, v240, v122
	v_add_f32_e32 v241, v241, v123
	v_exp_f32_e32 v126, v126
	v_exp_f32_e32 v127, v127
	v_add_f32_e32 v240, v240, v124
	v_add_f32_e32 v241, v241, v125
	v_mfma_f32_32x32x16_bf16 v[0:15], v[212:215], v[96:99], v[0:15]
	v_add_f32_e32 v240, v240, v126
	v_add_f32_e32 v241, v241, v127
	v_cvt_pk_bf16_f32 v120, v120, v121
	v_cvt_pk_bf16_f32 v121, v122, v123
	v_cvt_pk_bf16_f32 v122, v124, v125
	v_cvt_pk_bf16_f32 v123, v126, v127
	v_exp_f32_e32 v104, v104
	v_exp_f32_e32 v105, v105
	v_exp_f32_e32 v106, v106
	v_exp_f32_e32 v107, v107
	v_mfma_f32_32x32x16_bf16 v[32:47], v[216:219], v[120:123], v[32:47]
	v_add_f32_e32 v242, v242, v104
	v_add_f32_e32 v243, v243, v105
	v_exp_f32_e32 v108, v108
	v_exp_f32_e32 v109, v109
	v_add_f32_e32 v242, v242, v106
	v_add_f32_e32 v243, v243, v107
	v_exp_f32_e32 v110, v110
	v_exp_f32_e32 v111, v111
	v_add_f32_e32 v242, v242, v108
	v_add_f32_e32 v243, v243, v109
	v_mfma_f32_32x32x16_bf16 v[48:63], v[220:223], v[120:123], v[48:63]
	v_add_f32_e32 v242, v242, v110
	v_add_f32_e32 v243, v243, v111
	v_cvt_pk_bf16_f32 v104, v104, v105
	v_cvt_pk_bf16_f32 v105, v106, v107
	v_cvt_pk_bf16_f32 v106, v108, v109
	v_cvt_pk_bf16_f32 v107, v110, v111
	v_exp_f32_e32 v80, v80
	v_exp_f32_e32 v81, v81
	v_exp_f32_e32 v82, v82
	v_exp_f32_e32 v83, v83
	v_mfma_f32_32x32x16_bf16 v[16:31], v[216:219], v[104:107], v[16:31]
	v_add_f32_e32 v240, v240, v80
	v_add_f32_e32 v241, v241, v81
	v_exp_f32_e32 v84, v84
	v_exp_f32_e32 v85, v85
	v_add_f32_e32 v240, v240, v82
	v_add_f32_e32 v241, v241, v83
	v_exp_f32_e32 v86, v86
	v_exp_f32_e32 v87, v87
	v_add_f32_e32 v240, v240, v84
	v_add_f32_e32 v241, v241, v85
	v_mfma_f32_32x32x16_bf16 v[0:15], v[220:223], v[104:107], v[0:15]
	v_add_f32_e32 v240, v240, v86
	v_add_f32_e32 v241, v241, v87
	v_cvt_pk_bf16_f32 v80, v80, v81
	v_cvt_pk_bf16_f32 v81, v82, v83
	v_cvt_pk_bf16_f32 v82, v84, v85
	v_cvt_pk_bf16_f32 v83, v86, v87
	v_exp_f32_e32 v64, v64
	v_exp_f32_e32 v65, v65
	v_exp_f32_e32 v66, v66
	v_exp_f32_e32 v67, v67
	v_mfma_f32_32x32x16_bf16 v[32:47], v[224:227], v[80:83], v[32:47]
	v_add_f32_e32 v242, v242, v64
	v_add_f32_e32 v243, v243, v65
	v_exp_f32_e32 v68, v68
	v_exp_f32_e32 v69, v69
	v_add_f32_e32 v242, v242, v66
	v_add_f32_e32 v243, v243, v67
	v_exp_f32_e32 v70, v70
	v_exp_f32_e32 v71, v71
	v_add_f32_e32 v242, v242, v68
	v_add_f32_e32 v243, v243, v69
	v_mfma_f32_32x32x16_bf16 v[48:63], v[228:231], v[80:83], v[48:63]
	v_add_f32_e32 v242, v242, v70
	v_add_f32_e32 v243, v243, v71
	v_cvt_pk_bf16_f32 v64, v64, v65
	v_cvt_pk_bf16_f32 v65, v66, v67
	v_cvt_pk_bf16_f32 v66, v68, v69
	v_cvt_pk_bf16_f32 v67, v70, v71
	v_exp_f32_e32 v88, v88
	v_exp_f32_e32 v89, v89
	v_exp_f32_e32 v90, v90
	v_exp_f32_e32 v91, v91
	v_mfma_f32_32x32x16_bf16 v[16:31], v[224:227], v[64:67], v[16:31]
	v_add_f32_e32 v240, v240, v88
	v_add_f32_e32 v241, v241, v89
	v_exp_f32_e32 v92, v92
	v_exp_f32_e32 v93, v93
	v_add_f32_e32 v240, v240, v90
	v_add_f32_e32 v241, v241, v91
	v_exp_f32_e32 v94, v94
	v_exp_f32_e32 v95, v95
	v_add_f32_e32 v240, v240, v92
	v_add_f32_e32 v241, v241, v93
	v_mfma_f32_32x32x16_bf16 v[0:15], v[228:231], v[64:67], v[0:15]
	v_add_f32_e32 v240, v240, v94
	v_add_f32_e32 v241, v241, v95
	v_cvt_pk_bf16_f32 v88, v88, v89
	v_cvt_pk_bf16_f32 v89, v90, v91
	v_cvt_pk_bf16_f32 v90, v92, v93
	v_cvt_pk_bf16_f32 v91, v94, v95
	v_exp_f32_e32 v72, v72
	v_exp_f32_e32 v73, v73
	v_exp_f32_e32 v74, v74
	v_exp_f32_e32 v75, v75
	v_mfma_f32_32x32x16_bf16 v[32:47], v[232:235], v[88:91], v[32:47]
	v_add_f32_e32 v242, v242, v72
	v_add_f32_e32 v243, v243, v73
	v_exp_f32_e32 v76, v76
	v_exp_f32_e32 v77, v77
	v_add_f32_e32 v242, v242, v74
	v_add_f32_e32 v243, v243, v75
	v_exp_f32_e32 v78, v78
	v_exp_f32_e32 v79, v79
	v_add_f32_e32 v242, v242, v76
	v_add_f32_e32 v243, v243, v77
	v_mfma_f32_32x32x16_bf16 v[48:63], v[236:239], v[88:91], v[48:63]
	v_add_f32_e32 v242, v242, v78
	v_add_f32_e32 v243, v243, v79
	v_cvt_pk_bf16_f32 v72, v72, v73
	v_cvt_pk_bf16_f32 v73, v74, v75
	v_cvt_pk_bf16_f32 v74, v76, v77
	v_cvt_pk_bf16_f32 v75, v78, v79
	v_add_f32_e32 v240, v240, v241
	v_add_f32_e32 v242, v242, v243
	v_mfma_f32_32x32x16_bf16 v[16:31], v[232:235], v[72:75], v[16:31]
	v_add_f32_e32 v181, v181, v240
	v_add_f32_e32 v180, v180, v242
	v_mfma_f32_32x32x16_bf16 v[0:15], v[236:239], v[72:75], v[0:15]

; DI float shx(float v, int k, int lane) { return __builtin_bit_cast(float, __builtin_amdgcn_ds_bpermute((lane ^ k) << 2, __builtin_bit_cast(int, v))); }
; DI float fast_exp2(float x) { return __builtin_amdgcn_exp2f(x); }
; template <bool FIRST, bool MASKED>
; DI void attn2_step(f32x16 (&o)[2][2], float (&m_ref)[2], float (&lsum)[2], const bf16x8 (&qf)[2][4], const lchar* Kl, const lchar* Vl, int lane, int kp0, int qw0, float m_init, float l0) {
;     ...
;     float mx[2];
; #pragma unroll
;     for (int q = 0; q < 2; ++q) {
;         float m = fmaxf(sc[q][0][0], sc[q][1][0]);
; #pragma unroll
;         for (int i = 1; i < 16; ++i) m = fmaxf(m, fmaxf(sc[q][0][i], sc[q][1][i]));
;         mx[q] = fmaxf(m, shx(m, 32, lane));
;     }
;     ...
;     } else if (__builtin_amdgcn_ballot_w64(fmaxf(mx[0], mx[1]) > ATT_THR) != 0ull) {
; #pragma unroll
;         for (int q = 0; q < 2; ++q) {
;             const float delta = fmaxf(mx[q], 0.f), alpha = fast_exp2(-delta);
; #pragma unroll
;             for (int dt = 0; dt < 2; ++dt)
; #pragma unroll
;                 for (int i = 0; i < 16; ++i) o[q][dt][i] *= alpha;
;             lsum[q] *= alpha;
; #pragma unroll
;             for (int kt = 0; kt < 2; ++kt)
; #pragma unroll
;                 for (int i = 0; i < 16; ++i) sc[q][kt][i] -= delta;
;             m_ref[q] += delta;
;         }
;     }
.LBB0_216:
	s_nop 8
	v_max3_f32 v193, v112, v113, v114
	v_max3_f32 v193, v193, v115, v116
	v_max3_f32 v193, v193, v117, v118
	v_max3_f32 v193, v193, v119, v120
	v_max3_f32 v193, v193, v121, v122
	v_max3_f32 v193, v193, v123, v124
	v_max3_f32 v193, v193, v125, v126
	v_max3_f32 v193, v193, v127, v80
	v_max3_f32 v193, v193, v81, v82
	v_max3_f32 v193, v193, v83, v84
	v_max3_f32 v193, v193, v85, v86
	v_max3_f32 v193, v193, v87, v88
	v_max3_f32 v193, v193, v89, v90
	v_max3_f32 v193, v193, v91, v92
	v_max3_f32 v193, v193, v93, v94
	v_max_f32_e32 v193, v193, v95
	v_mov_b32_e32 v195, v193
	v_max3_f32 v194, v96, v97, v98
	v_max3_f32 v194, v194, v99, v100
	v_max3_f32 v194, v194, v101, v102
	v_max3_f32 v194, v194, v103, v104
	v_max3_f32 v194, v194, v105, v106
	v_max3_f32 v194, v194, v107, v108
	v_max3_f32 v194, v194, v109, v110
	v_max3_f32 v194, v194, v111, v64
	v_max3_f32 v194, v194, v65, v66
	v_max3_f32 v194, v194, v67, v68
	v_max3_f32 v194, v194, v69, v70
	v_max3_f32 v194, v194, v71, v72
	v_max3_f32 v194, v194, v73, v74
	v_max3_f32 v194, v194, v75, v76
	v_max3_f32 v194, v194, v77, v78
	v_max_f32_e32 v194, v194, v79
	v_permlane32_swap_b32_e32 v195, v193
	v_max_f32_e32 v193, v193, v195
	v_mov_b32_e32 v196, v194
	s_mov_b32 s0, 0x41000000
	s_nop 1
	v_permlane32_swap_b32_e32 v196, v194
	v_max_f32_e32 v194, v194, v196
	v_max_f32_e32 v195, v193, v194
	v_cmp_lt_f32_e32 vcc, s0, v195
	s_cbranch_vccz .LBB0_208
	v_max_f32_e32 v193, v193, v193
	v_max_f32_e32 v196, 0, v193
	v_max_f32_e32 v193, v194, v194
	v_max_f32_e32 v194, 0, v193
	v_exp_f32_e64 v208, -v196
	v_exp_f32_e64 v210, -v194
	v_pk_add_f32 v[96:97], v[96:97], v[194:195] op_sel_hi:[1,0] neg_lo:[0,1] neg_hi:[0,1]
	v_pk_add_f32 v[98:99], v[98:99], v[194:195] op_sel_hi:[1,0] neg_lo:[0,1] neg_hi:[0,1]
	v_pk_add_f32 v[100:101], v[100:101], v[194:195] op_sel_hi:[1,0] neg_lo:[0,1] neg_hi:[0,1]
	v_pk_mul_f32 v[30:31], v[30:31], v[210:211] op_sel_hi:[1,0]
	v_pk_mul_f32 v[28:29], v[28:29], v[210:211] op_sel_hi:[1,0]
	v_pk_mul_f32 v[26:27], v[26:27], v[210:211] op_sel_hi:[1,0]
	v_pk_mul_f32 v[24:25], v[24:25], v[210:211] op_sel_hi:[1,0]
	v_pk_mul_f32 v[22:23], v[22:23], v[210:211] op_sel_hi:[1,0]
	v_pk_mul_f32 v[20:21], v[20:21], v[210:211] op_sel_hi:[1,0]
	v_pk_mul_f32 v[18:19], v[18:19], v[210:211] op_sel_hi:[1,0]
	v_pk_mul_f32 v[16:17], v[16:17], v[210:211] op_sel_hi:[1,0]
	v_pk_mul_f32 v[14:15], v[14:15], v[210:211] op_sel_hi:[1,0]
	v_pk_mul_f32 v[12:13], v[12:13], v[210:211] op_sel_hi:[1,0]
	v_pk_mul_f32 v[10:11], v[10:11], v[210:211] op_sel_hi:[1,0]
	v_pk_mul_f32 v[8:9], v[8:9], v[210:211] op_sel_hi:[1,0]
	v_pk_mul_f32 v[6:7], v[6:7], v[210:211] op_sel_hi:[1,0]
	v_pk_mul_f32 v[4:5], v[4:5], v[210:211] op_sel_hi:[1,0]
	v_pk_mul_f32 v[2:3], v[2:3], v[210:211] op_sel_hi:[1,0]
	v_pk_mul_f32 v[0:1], v[0:1], v[210:211] op_sel_hi:[1,0]
	v_mov_b32_e32 v211, v208
	v_pk_add_f32 v[102:103], v[102:103], v[194:195] op_sel_hi:[1,0] neg_lo:[0,1] neg_hi:[0,1]
	v_pk_add_f32 v[104:105], v[104:105], v[194:195] op_sel_hi:[1,0] neg_lo:[0,1] neg_hi:[0,1]
	v_pk_add_f32 v[106:107], v[106:107], v[194:195] op_sel_hi:[1,0] neg_lo:[0,1] neg_hi:[0,1]
	v_pk_add_f32 v[108:109], v[108:109], v[194:195] op_sel_hi:[1,0] neg_lo:[0,1] neg_hi:[0,1]
	v_pk_add_f32 v[110:111], v[110:111], v[194:195] op_sel_hi:[1,0] neg_lo:[0,1] neg_hi:[0,1]
	v_pk_add_f32 v[64:65], v[64:65], v[194:195] op_sel_hi:[1,0] neg_lo:[0,1] neg_hi:[0,1]
	v_pk_add_f32 v[66:67], v[66:67], v[194:195] op_sel_hi:[1,0] neg_lo:[0,1] neg_hi:[0,1]
	v_pk_add_f32 v[68:69], v[68:69], v[194:195] op_sel_hi:[1,0] neg_lo:[0,1] neg_hi:[0,1]
	v_pk_add_f32 v[70:71], v[70:71], v[194:195] op_sel_hi:[1,0] neg_lo:[0,1] neg_hi:[0,1]
	v_pk_add_f32 v[72:73], v[72:73], v[194:195] op_sel_hi:[1,0] neg_lo:[0,1] neg_hi:[0,1]
	v_pk_add_f32 v[74:75], v[74:75], v[194:195] op_sel_hi:[1,0] neg_lo:[0,1] neg_hi:[0,1]
	v_pk_add_f32 v[76:77], v[76:77], v[194:195] op_sel_hi:[1,0] neg_lo:[0,1] neg_hi:[0,1]
	v_pk_add_f32 v[78:79], v[78:79], v[194:195] op_sel_hi:[1,0] neg_lo:[0,1] neg_hi:[0,1]
	v_mov_b32_e32 v195, v196
	v_pk_mul_f32 v[46:47], v[46:47], v[208:209] op_sel_hi:[1,0]
	v_pk_mul_f32 v[44:45], v[44:45], v[208:209] op_sel_hi:[1,0]
	v_pk_mul_f32 v[42:43], v[42:43], v[208:209] op_sel_hi:[1,0]
	v_pk_mul_f32 v[40:41], v[40:41], v[208:209] op_sel_hi:[1,0]
	v_pk_mul_f32 v[38:39], v[38:39], v[208:209] op_sel_hi:[1,0]
	v_pk_mul_f32 v[36:37], v[36:37], v[208:209] op_sel_hi:[1,0]
	v_pk_mul_f32 v[34:35], v[34:35], v[208:209] op_sel_hi:[1,0]
	v_pk_mul_f32 v[32:33], v[32:33], v[208:209] op_sel_hi:[1,0]
	v_pk_mul_f32 v[62:63], v[62:63], v[208:209] op_sel_hi:[1,0]
	v_pk_mul_f32 v[60:61], v[60:61], v[208:209] op_sel_hi:[1,0]
	v_pk_mul_f32 v[58:59], v[58:59], v[208:209] op_sel_hi:[1,0]
	v_pk_mul_f32 v[56:57], v[56:57], v[208:209] op_sel_hi:[1,0]
	v_pk_mul_f32 v[54:55], v[54:55], v[208:209] op_sel_hi:[1,0]
	v_pk_mul_f32 v[52:53], v[52:53], v[208:209] op_sel_hi:[1,0]
	v_pk_mul_f32 v[50:51], v[50:51], v[208:209] op_sel_hi:[1,0]
	v_pk_mul_f32 v[48:49], v[48:49], v[208:209] op_sel_hi:[1,0]
	v_pk_add_f32 v[112:113], v[112:113], v[196:197] op_sel_hi:[1,0] neg_lo:[0,1] neg_hi:[0,1]
	v_pk_add_f32 v[114:115], v[114:115], v[196:197] op_sel_hi:[1,0] neg_lo:[0,1] neg_hi:[0,1]
	v_pk_add_f32 v[116:117], v[116:117], v[196:197] op_sel_hi:[1,0] neg_lo:[0,1] neg_hi:[0,1]
	v_pk_add_f32 v[118:119], v[118:119], v[196:197] op_sel_hi:[1,0] neg_lo:[0,1] neg_hi:[0,1]
	v_pk_add_f32 v[120:121], v[120:121], v[196:197] op_sel_hi:[1,0] neg_lo:[0,1] neg_hi:[0,1]
	v_pk_add_f32 v[122:123], v[122:123], v[196:197] op_sel_hi:[1,0] neg_lo:[0,1] neg_hi:[0,1]
	v_pk_add_f32 v[124:125], v[124:125], v[196:197] op_sel_hi:[1,0] neg_lo:[0,1] neg_hi:[0,1]
	v_pk_add_f32 v[126:127], v[126:127], v[196:197] op_sel_hi:[1,0] neg_lo:[0,1] neg_hi:[0,1]
	v_pk_add_f32 v[80:81], v[80:81], v[196:197] op_sel_hi:[1,0] neg_lo:[0,1] neg_hi:[0,1]
	v_pk_add_f32 v[82:83], v[82:83], v[196:197] op_sel_hi:[1,0] neg_lo:[0,1] neg_hi:[0,1]
	v_pk_add_f32 v[84:85], v[84:85], v[196:197] op_sel_hi:[1,0] neg_lo:[0,1] neg_hi:[0,1]
	v_pk_add_f32 v[86:87], v[86:87], v[196:197] op_sel_hi:[1,0] neg_lo:[0,1] neg_hi:[0,1]
	v_pk_add_f32 v[88:89], v[88:89], v[196:197] op_sel_hi:[1,0] neg_lo:[0,1] neg_hi:[0,1]
	v_pk_add_f32 v[90:91], v[90:91], v[196:197] op_sel_hi:[1,0] neg_lo:[0,1] neg_hi:[0,1]
	v_pk_add_f32 v[92:93], v[92:93], v[196:197] op_sel_hi:[1,0] neg_lo:[0,1] neg_hi:[0,1]
	v_pk_add_f32 v[94:95], v[94:95], v[196:197] op_sel_hi:[1,0] neg_lo:[0,1] neg_hi:[0,1]
	v_pk_mul_f32 v[180:181], v[180:181], v[210:211]
	v_pk_add_f32 v[182:183], v[182:183], v[194:195]
	s_branch .LBB0_208

; DI float bf2f(unsigned v16) { return __uint_as_float(v16 << 16); }
; template <int MODE, bool FROM_IN>
; DI void rowop_run(const Params& p, int l, int row0, int nrows_run, int r, int lane, bool dry = false) {
;     ...
; #pragma unroll
;         for (int i = 0; i < 4; ++i) {
;             const int c = (i * 64 + lane) * 4;
;             if (HASY) pa[i] = *(const f32x4*)(gate + c) * *(const f32x4*)(pg + c);
;             pb[i] = *(const f32x4*)(pre + c) * (*(const f32x4*)(ad2 + D + c) + 1.0f);
;             pc[i] = *(const f32x4*)(ad2 + c);
;         }
;     }
;     auto xptr = [&](int row) -> const float* { return row < NLAT ? p.x + (size_t)row * D : p.ctx + (size_t)(row - NLAT) * D; };
;     RowBuf cur, nxt;
;     rowop_load<HASY, FROM_IN>(cur, xptr(row0), p.xres + (size_t)row0 * D, p.Y + (size_t)row0 * D, lane);
;     for (int j = 0; j < nrows_run; ++j) {
;         const int row = row0 + j;
;         if (j + 1 < nrows_run) rowop_load<HASY, FROM_IN>(nxt, xptr(row + 1), p.xres + (size_t)(row + 1) * D, p.Y + (size_t)(row + 1) * D, lane);
;         f32x4 xv[4];
; #pragma unroll
;         for (int i = 0; i < 4; ++i) {
;             if (FROM_IN) xv[i] = cur.x[i];
;             else { const u32x2 w = cur.xb[i]; xv[i][0] = bf2f(w.x & 0xffffu); xv[i][1] = bf2f(w.x >> 16); xv[i][2] = bf2f(w.y & 0xffffu); xv[i][3] = bf2f(w.y >> 16); }
.LBB0_318:
	global_load_dwordx4 v[0:3], v[16:17], off
	global_load_dwordx4 v[4:7], v[18:19], off
	v_lshlrev_b32_e32 v88, 1, v120
	v_add_u32_e32 v50, 0x10000, v88
	v_ashrrev_i32_e32 v51, 31, v50
	s_mov_b32 s22, 0
	s_mov_b64 s[38:39], -1
	s_mov_b64 s[34:35], 0
	s_waitcnt vmcnt(0)
	v_pk_mul_f32 v[52:53], v[2:3], v[6:7]
	v_pk_mul_f32 v[54:55], v[0:1], v[4:5]
	global_load_dwordx4 v[0:3], v[20:21], off
	global_load_dwordx4 v[4:7], v[22:23], off
	s_waitcnt vmcnt(0)
	v_pk_add_f32 v[6:7], v[6:7], 1.0 op_sel_hi:[1,0]
	v_pk_add_f32 v[4:5], v[4:5], 1.0 op_sel_hi:[1,0]
	v_pk_mul_f32 v[56:57], v[2:3], v[6:7]
	v_pk_mul_f32 v[58:59], v[0:1], v[4:5]
	global_load_dwordx4 v[0:3], v[24:25], off
	global_load_dwordx4 v[4:7], v[26:27], off
	global_load_dwordx4 v[8:11], v[18:19], off offset:1024
	s_waitcnt vmcnt(0)
	v_pk_mul_f32 v[60:61], v[6:7], v[10:11]
	v_pk_mul_f32 v[62:63], v[4:5], v[8:9]
	global_load_dwordx4 v[4:7], v[20:21], off offset:1024
	global_load_dwordx4 v[8:11], v[28:29], off
	s_waitcnt vmcnt(0)
	v_pk_add_f32 v[10:11], v[10:11], 1.0 op_sel_hi:[1,0]
	v_pk_add_f32 v[8:9], v[8:9], 1.0 op_sel_hi:[1,0]
	v_pk_mul_f32 v[64:65], v[6:7], v[10:11]
	v_pk_mul_f32 v[66:67], v[4:5], v[8:9]
	global_load_dwordx4 v[4:7], v[30:31], off
	global_load_dwordx4 v[8:11], v[36:37], off
	global_load_dwordx4 v[12:15], v[18:19], off offset:2048
	s_waitcnt vmcnt(0)
	v_pk_mul_f32 v[68:69], v[10:11], v[14:15]
	v_pk_mul_f32 v[70:71], v[8:9], v[12:13]
	global_load_dwordx4 v[8:11], v[20:21], off offset:2048
	global_load_dwordx4 v[12:15], v[38:39], off
	s_waitcnt vmcnt(0)
	v_pk_add_f32 v[14:15], v[14:15], 1.0 op_sel_hi:[1,0]
	v_pk_add_f32 v[12:13], v[12:13], 1.0 op_sel_hi:[1,0]
	v_pk_mul_f32 v[72:73], v[10:11], v[14:15]
	v_pk_mul_f32 v[74:75], v[8:9], v[12:13]
	global_load_dwordx4 v[8:11], v[40:41], off
	global_load_dwordx4 v[12:15], v[34:35], off
	global_load_dwordx4 v[78:81], v[18:19], off offset:3072
	s_waitcnt vmcnt(0)
	v_pk_mul_f32 v[76:77], v[14:15], v[80:81]
	v_pk_mul_f32 v[78:79], v[12:13], v[78:79]
	global_load_dwordx4 v[12:15], v[20:21], off offset:3072
	global_load_dwordx4 v[80:83], v[42:43], off
	s_waitcnt vmcnt(0)
	v_pk_add_f32 v[82:83], v[82:83], 1.0 op_sel_hi:[1,0]
	v_pk_add_f32 v[84:85], v[80:81], 1.0 op_sel_hi:[1,0]
	v_pk_mul_f32 v[80:81], v[14:15], v[82:83]
	v_pk_mul_f32 v[82:83], v[12:13], v[84:85]
	v_lshlrev_b64 v[84:85], 11, v[50:51]
	v_lshl_add_u64 v[86:87], v[46:47], 0, v[84:85]
	v_lshl_add_u64 v[84:85], v[48:49], 0, v[84:85]
	global_load_dwordx4 v[12:15], v[44:45], off
	global_load_dwordx2 v[110:111], v[86:87], off nt
	global_load_dwordx2 v[108:109], v[86:87], off offset:512 nt
	global_load_dwordx2 v[106:107], v[86:87], off offset:1024 nt
	global_load_dwordx2 v[104:105], v[86:87], off offset:1536 nt
	global_load_dwordx2 v[118:119], v[84:85], off nt
	global_load_dwordx2 v[116:117], v[84:85], off offset:512 nt
	global_load_dwordx2 v[112:113], v[84:85], off offset:1024 nt
	global_load_dwordx2 v[114:115], v[84:85], off offset:1536 nt
	v_add_u32_e32 v84, 0x10001, v88
	v_ashrrev_i32_e32 v85, 31, v84
	v_lshlrev_b64 v[86:87], 11, v[84:85]
	v_lshl_add_u64 v[84:85], v[46:47], 0, v[86:87]
	v_lshl_add_u64 v[86:87], v[48:49], 0, v[86:87]
	s_waitcnt vmcnt(0)
	s_branch .LBB0_320
.LBB0_319:
	v_and_b32_e32 v133, 0xffff0000, v118
	v_and_b32_e32 v132, 0xffff0000, v116
	v_lshlrev_b32_e32 v131, 16, v118
	v_lshlrev_b32_e32 v130, 16, v116
	v_lshlrev_b32_e32 v134, 16, v117
	v_and_b32_e32 v118, 0xffff0000, v117
	v_pk_mul_f32 v[116:117], v[132:133], v[132:133]
	v_and_b32_e32 v139, 0xffff0000, v114
	v_and_b32_e32 v138, 0xffff0000, v112
	v_lshlrev_b32_e32 v135, 16, v119
	v_pk_fma_f32 v[116:117], v[130:131], v[130:131], v[116:117]
	v_lshlrev_b32_e32 v137, 16, v114
	v_lshlrev_b32_e32 v136, 16, v112
	v_lshlrev_b32_e32 v140, 16, v113
	v_and_b32_e32 v114, 0xffff0000, v113
	v_pk_mul_f32 v[112:113], v[138:139], v[138:139]
	v_and_b32_e32 v119, 0xffff0000, v119
	v_pk_fma_f32 v[116:117], v[134:135], v[134:135], v[116:117]
	v_lshlrev_b32_e32 v141, 16, v115
	v_pk_fma_f32 v[112:113], v[136:137], v[136:137], v[112:113]
	v_pk_fma_f32 v[116:117], v[118:119], v[118:119], v[116:117]
	v_and_b32_e32 v115, 0xffff0000, v115
	v_pk_fma_f32 v[112:113], v[140:141], v[140:141], v[112:113]
	v_add_f32_e32 v51, v116, v117
	v_pk_fma_f32 v[112:113], v[114:115], v[114:115], v[112:113]
	v_mov_b32_e32 v146, v131
	v_add_f32_e32 v51, v112, v51
	v_add_f32_e32 v51, v51, v113
	ds_bpermute_b32 v112, v121, v51
	v_mov_b32_e32 v131, v132
	v_lshlrev_b32_e32 v116, 16, v108
	v_mov_b32_e32 v147, v133
	v_mov_b32_e32 v148, v135
	s_waitcnt lgkmcnt(0)
	v_add_f32_e32 v51, v51, v112
	ds_bpermute_b32 v112, v122, v51
	v_mov_b32_e32 v135, v118
	v_mov_b32_e32 v149, v119
	v_lshlrev_b32_e32 v142, 16, v106
	v_and_b32_e32 v143, 0xffff0000, v106
	s_waitcnt lgkmcnt(0)
	v_add_f32_e32 v51, v51, v112
	ds_bpermute_b32 v113, v123, v51
	v_lshlrev_b32_e32 v112, 16, v110
	v_lshlrev_b32_e32 v106, 16, v107
	v_and_b32_e32 v107, 0xffff0000, v107
	v_lshlrev_b32_e32 v144, 16, v104
	s_waitcnt lgkmcnt(0)
	v_add_f32_e32 v51, v51, v113
	ds_bpermute_b32 v117, v124, v51
	v_and_b32_e32 v113, 0xffff0000, v110
	v_lshlrev_b32_e32 v110, 16, v111
	v_and_b32_e32 v111, 0xffff0000, v111
	v_and_b32_e32 v145, 0xffff0000, v104
	s_waitcnt lgkmcnt(0)
	v_add_f32_e32 v51, v51, v117
	ds_bpermute_b32 v127, v125, v51
	v_and_b32_e32 v117, 0xffff0000, v108
	v_lshlrev_b32_e32 v108, 16, v109
	v_and_b32_e32 v109, 0xffff0000, v109
	v_lshlrev_b32_e32 v104, 16, v105
	s_waitcnt lgkmcnt(0)
	v_add_f32_e32 v51, v51, v127
	ds_bpermute_b32 v127, v126, v51
	v_and_b32_e32 v105, 0xffff0000, v105
	s_mov_b64 s[38:39], 0
	s_waitcnt lgkmcnt(0)
; DI float shx(float v, int k, int lane) { return __builtin_bit_cast(float, __builtin_amdgcn_ds_bpermute((lane ^ k) << 2, __builtin_bit_cast(int, v))); }
; DI unsigned pack2(float lo, float hi) { f32x2 v = {lo, hi}; bf16x2_t b = __builtin_convertvector(v, bf16x2_t); return __builtin_bit_cast(unsigned, b); }
; DI float bf2f(unsigned v16) { return __uint_as_float(v16 << 16); }
; template <int MODE, bool FROM_IN>
; DI void rowop_run(const Params& p, int l, int row0, int nrows_run, int r, int lane, bool dry = false) {
;     ...
;         if (HASY) {
;             f32x4 yv[4]; float ss = 0.f;
; #pragma unroll
;             for (int i = 0; i < 4; ++i) {
;                 const u32x2 w = cur.y[i];
;                 yv[i][0] = bf2f(w.x & 0xffffu); yv[i][1] = bf2f(w.x >> 16); yv[i][2] = bf2f(w.y & 0xffffu); yv[i][3] = bf2f(w.y >> 16);
;                 ss += yv[i][0] * yv[i][0] + yv[i][1] * yv[i][1] + yv[i][2] * yv[i][2] + yv[i][3] * yv[i][3];
;             }
; #pragma unroll
;             for (int o = 32; o >= 1; o >>= 1) ss += shx(ss, o, lane);
;             const float rinv = rsqrtf(ss * (1.0f / D) + EPS);
; #pragma unroll
;             for (int i = 0; i < 4; ++i) xv[i] = xv[i] + pa[i] * (yv[i] * rinv);
;             if (last) {
; #pragma unroll
;                 for (int i = 0; i < 4; ++i) __builtin_nontemporal_store(xv[i], (f32x4*)(p.out + (size_t)row * D + (i * 64 + lane) * 4));
;             } else if (!dry) {
; #pragma unroll
;                 for (int i = 0; i < 4; ++i) { u32x2 w; w.x = pack2(xv[i][0], xv[i][1]); w.y = pack2(xv[i][2], xv[i][3]); __builtin_nontemporal_store(w, (u32x2*)(p.xres + (size_t)row * D + (i * 64 + lane) * 4)); }
;             }
;         }
;         if (!last) {
;             float ss = 0.f;
; #pragma unroll
;             for (int i = 0; i < 4; ++i) ss += xv[i][0] * xv[i][0] + xv[i][1] * xv[i][1] + xv[i][2] * xv[i][2] + xv[i][3] * xv[i][3];
; #pragma unroll
;             for (int o = 32; o >= 1; o >>= 1) ss += shx(ss, o, lane);
;             const float rinv = rsqrtf(ss * (1.0f / D) + EPS);
; #pragma unroll
;             for (int i = 0; i < 4; ++i) {
;                 const f32x4 hv = xv[i] * rinv * pb[i] + pc[i];
;                 u32x2 w; w.x = pack2(hv[0], hv[1]); w.y = pack2(hv[2], hv[3]);
;                 *(u32x2*)(p.H + (size_t)row * D + (i * 64 + lane) * 4) = w;
;             }
;         }
;         cur = nxt;
	v_add_f32_e32 v51, v51, v127
	v_fmamk_f32 v51, v51, 0x3a800000, v170
	v_mul_f32_e32 v127, 0x4b800000, v51
	v_cmp_gt_f32_e32 vcc, s75, v51
	s_nop 1
	v_cndmask_b32_e32 v51, v51, v127, vcc
	v_rsq_f32_e32 v51, v51
	s_nop 0
	v_mul_f32_e32 v127, 0x45800000, v51
	v_cndmask_b32_e32 v128, v51, v127, vcc
	v_pk_mul_f32 v[130:131], v[130:131], v[128:129] op_sel_hi:[1,0]
	v_pk_mul_f32 v[146:147], v[146:147], v[128:129] op_sel_hi:[1,0]
	v_pk_mul_f32 v[118:119], v[134:135], v[128:129] op_sel_hi:[1,0]
	v_pk_fma_f32 v[116:117], v[62:63], v[130:131], v[116:117]
	v_mov_b32_e32 v130, v140
	v_mov_b32_e32 v131, v114
	v_pk_fma_f32 v[112:113], v[54:55], v[146:147], v[112:113]
	v_pk_fma_f32 v[108:109], v[60:61], v[118:119], v[108:109]
	v_mov_b32_e32 v119, v138
	v_pk_mul_f32 v[130:131], v[130:131], v[128:129] op_sel_hi:[1,0]
	v_mov_b32_e32 v138, v137
	v_mov_b32_e32 v114, v141
	v_pk_mul_f32 v[148:149], v[148:149], v[128:129] op_sel_hi:[1,0]
	v_mov_b32_e32 v118, v136
	v_pk_fma_f32 v[106:107], v[68:69], v[130:131], v[106:107]
	v_pk_mul_f32 v[130:131], v[138:139], v[128:129] op_sel_hi:[1,0]
	v_pk_mul_f32 v[114:115], v[114:115], v[128:129] op_sel_hi:[1,0]
	v_mov_b32_e32 v132, v113
	v_mov_b32_e32 v133, v117
	v_pk_fma_f32 v[110:111], v[52:53], v[148:149], v[110:111]
	v_pk_mul_f32 v[118:119], v[118:119], v[128:129] op_sel_hi:[1,0]
	v_pk_fma_f32 v[104:105], v[76:77], v[114:115], v[104:105]
	v_pk_fma_f32 v[114:115], v[78:79], v[130:131], v[144:145]
	v_mov_b32_e32 v130, v112
	v_mov_b32_e32 v131, v116
	v_pk_mul_f32 v[132:133], v[132:133], v[132:133]
	v_pk_fma_f32 v[118:119], v[70:71], v[118:119], v[142:143]
	v_pk_fma_f32 v[130:131], v[130:131], v[130:131], v[132:133]
	v_mov_b32_e32 v132, v110
	v_mov_b32_e32 v133, v108
	v_pk_fma_f32 v[130:131], v[132:133], v[132:133], v[130:131]
	v_mov_b32_e32 v132, v111
	v_mov_b32_e32 v133, v109
	v_mov_b32_e32 v134, v115
	v_mov_b32_e32 v135, v119
	v_pk_fma_f32 v[130:131], v[132:133], v[132:133], v[130:131]
	v_mov_b32_e32 v132, v114
	v_mov_b32_e32 v133, v118
	v_pk_mul_f32 v[134:135], v[134:135], v[134:135]
	v_add_f32_e32 v51, v130, v131
	v_pk_fma_f32 v[132:133], v[132:133], v[132:133], v[134:135]
	v_mov_b32_e32 v134, v104
	v_mov_b32_e32 v135, v106
	v_pk_fma_f32 v[132:133], v[134:135], v[134:135], v[132:133]
	v_mov_b32_e32 v134, v105
	v_mov_b32_e32 v135, v107
	v_pk_fma_f32 v[132:133], v[134:135], v[134:135], v[132:133]
	v_or_b32_e32 v130, s22, v50
	v_add_f32_e32 v51, v133, v51
	v_add_f32_e32 v51, v132, v51
	ds_bpermute_b32 v127, v121, v51
	v_ashrrev_i32_e32 v131, 31, v130
	v_lshlrev_b64 v[130:131], 11, v[130:131]
	v_cvt_pk_bf16_f32 v132, v112, v113
	v_cvt_pk_bf16_f32 v133, v110, v111
	s_waitcnt lgkmcnt(0)
	v_add_f32_e32 v51, v51, v127
	ds_bpermute_b32 v127, v122, v51
	v_lshl_add_u64 v[134:135], v[46:47], 0, v[130:131]
	global_store_dwordx2 v[134:135], v[132:133], off nt
	v_cvt_pk_bf16_f32 v132, v116, v117
	v_cvt_pk_bf16_f32 v133, v108, v109
	s_waitcnt lgkmcnt(0)
	v_add_f32_e32 v51, v51, v127
	ds_bpermute_b32 v127, v123, v51
	global_store_dwordx2 v[134:135], v[132:133], off offset:512 nt
	v_cvt_pk_bf16_f32 v132, v118, v119
	v_cvt_pk_bf16_f32 v133, v106, v107
	global_store_dwordx2 v[134:135], v[132:133], off offset:1024 nt
	s_waitcnt lgkmcnt(0)
	v_add_f32_e32 v51, v51, v127
	ds_bpermute_b32 v127, v124, v51
	v_cvt_pk_bf16_f32 v132, v114, v115
	v_cvt_pk_bf16_f32 v133, v104, v105
	global_store_dwordx2 v[134:135], v[132:133], off offset:1536 nt
	s_mov_b32 s22, 1
	s_waitcnt lgkmcnt(0)
	v_add_f32_e32 v51, v51, v127
	ds_bpermute_b32 v127, v125, v51
	s_waitcnt lgkmcnt(0)
	v_add_f32_e32 v51, v51, v127
	ds_bpermute_b32 v127, v126, v51
	s_waitcnt lgkmcnt(0)
	v_add_f32_e32 v51, v51, v127
	v_fmamk_f32 v51, v51, 0x3a800000, v170
	v_mul_f32_e32 v127, 0x4b800000, v51
	v_cmp_gt_f32_e32 vcc, s75, v51
	s_nop 1
	v_cndmask_b32_e32 v51, v51, v127, vcc
	v_rsq_f32_e32 v51, v51
	s_nop 0
	v_mul_f32_e32 v127, 0x45800000, v51
	v_cndmask_b32_e32 v128, v51, v127, vcc
	v_pk_mul_f32 v[112:113], v[112:113], v[128:129] op_sel_hi:[1,0]
	v_pk_mul_f32 v[110:111], v[110:111], v[128:129] op_sel_hi:[1,0]
	v_pk_fma_f32 v[112:113], v[58:59], v[112:113], v[0:1]
	v_pk_fma_f32 v[110:111], v[56:57], v[110:111], v[2:3]
	v_cvt_pk_bf16_f32 v112, v112, v113
	v_cvt_pk_bf16_f32 v113, v110, v111
	v_lshl_add_u64 v[110:111], v[32:33], 0, v[130:131]
	global_store_dwordx2 v[110:111], v[112:113], off
	v_pk_mul_f32 v[112:113], v[116:117], v[128:129] op_sel_hi:[1,0]
	v_pk_mul_f32 v[108:109], v[108:109], v[128:129] op_sel_hi:[1,0]
	v_pk_fma_f32 v[112:113], v[66:67], v[112:113], v[4:5]
	v_pk_fma_f32 v[108:109], v[64:65], v[108:109], v[6:7]
	v_cvt_pk_bf16_f32 v112, v112, v113
	v_cvt_pk_bf16_f32 v113, v108, v109
	v_pk_mul_f32 v[108:109], v[118:119], v[128:129] op_sel_hi:[1,0]
	v_pk_mul_f32 v[106:107], v[106:107], v[128:129] op_sel_hi:[1,0]
	v_pk_fma_f32 v[108:109], v[74:75], v[108:109], v[8:9]
	v_pk_fma_f32 v[106:107], v[72:73], v[106:107], v[10:11]
	v_cvt_pk_bf16_f32 v108, v108, v109
	v_cvt_pk_bf16_f32 v109, v106, v107
	v_pk_mul_f32 v[106:107], v[114:115], v[128:129] op_sel_hi:[1,0]
	v_pk_mul_f32 v[104:105], v[104:105], v[128:129] op_sel_hi:[1,0]
	v_pk_fma_f32 v[106:107], v[82:83], v[106:107], v[12:13]
	v_pk_fma_f32 v[104:105], v[80:81], v[104:105], v[14:15]
	v_cvt_pk_bf16_f32 v106, v106, v107
	v_cvt_pk_bf16_f32 v107, v104, v105
	global_store_dwordx2 v[110:111], v[112:113], off offset:512
	global_store_dwordx2 v[110:111], v[108:109], off offset:1024
	global_store_dwordx2 v[110:111], v[106:107], off offset:1536
	s_andn2_b64 vcc, exec, s[34:35]
	s_waitcnt vmcnt(8)
	v_mov_b64_e32 v[112:113], v[100:101]
	v_mov_b64_e32 v[116:117], v[98:99]
	v_mov_b64_e32 v[118:119], v[96:97]
	v_mov_b64_e32 v[104:105], v[94:95]
	v_mov_b64_e32 v[106:107], v[92:93]
	v_mov_b64_e32 v[108:109], v[90:91]
	v_mov_b64_e32 v[110:111], v[88:89]
	v_mov_b64_e32 v[114:115], v[102:103]
	s_mov_b64 s[34:35], -1
	s_cbranch_vccz .LBB0_317

; __global__ void __launch_bounds__(NTHR, 2) fwd_megakernel(Params p) {
;     __shared__ __attribute__((aligned(16))) char smem[LDS_BYTES];
	.amdhsa_kernel _Z14fwd_megakernel6Params
		.amdhsa_group_segment_fixed_size 155664
		.amdhsa_private_segment_fixed_size 0
		.amdhsa_kernarg_size 544
		.amdhsa_user_sgpr_count 2
		.amdhsa_user_sgpr_dispatch_ptr 0
		.amdhsa_user_sgpr_queue_ptr 0
		.amdhsa_user_sgpr_kernarg_segment_ptr 1
		.amdhsa_user_sgpr_dispatch_id 0
		.amdhsa_user_sgpr_kernarg_preload_length 0
		.amdhsa_user_sgpr_kernarg_preload_offset 0
		.amdhsa_user_sgpr_private_segment_size 0
		.amdhsa_uses_dynamic_stack 0
		.amdhsa_enable_private_segment 0
		.amdhsa_system_sgpr_workgroup_id_x 1
		.amdhsa_system_sgpr_workgroup_id_y 0
		.amdhsa_system_sgpr_workgroup_id_z 0
		.amdhsa_system_sgpr_workgroup_info 0
		.amdhsa_system_vgpr_workitem_id 2
		.amdhsa_next_free_vgpr 256
		.amdhsa_next_free_sgpr 102
		.amdhsa_accum_offset 256
		.amdhsa_reserve_vcc 1
		.amdhsa_float_round_mode_32 0
		.amdhsa_float_round_mode_16_64 0
		.amdhsa_float_denorm_mode_32 3
		.amdhsa_float_denorm_mode_16_64 3
		.amdhsa_dx10_clamp 1
		.amdhsa_ieee_mode 1
		.amdhsa_fp16_overflow 0
		.amdhsa_tg_split 0
		.amdhsa_exception_fp_ieee_invalid_op 0
		.amdhsa_exception_fp_denorm_src 0
		.amdhsa_exception_fp_ieee_div_zero 0
		.amdhsa_exception_fp_ieee_overflow 0
		.amdhsa_exception_fp_ieee_underflow 0
		.amdhsa_exception_fp_ieee_inexact 0
		.amdhsa_exception_int_div_zero 0
	.end_amdhsa_kernel

amdhsa.kernels:
  - .agpr_count:     0
    .args:
      - .offset:         0
        .size:           288
        .value_kind:     by_value
      - .offset:         288
        .size:           4
        .value_kind:     hidden_block_count_x
      - .offset:         292
        .size:           4
        .value_kind:     hidden_block_count_y
      - .offset:         296
        .size:           4
        .value_kind:     hidden_block_count_z
      - .offset:         300
        .size:           2
        .value_kind:     hidden_group_size_x
      - .offset:         302
        .size:           2
        .value_kind:     hidden_group_size_y
      - .offset:         304
        .size:           2
        .value_kind:     hidden_group_size_z
      - .offset:         306
        .size:           2
        .value_kind:     hidden_remainder_x
      - .offset:         308
        .size:           2
        .value_kind:     hidden_remainder_y
      - .offset:         310
        .size:           2
        .value_kind:     hidden_remainder_z
      - .offset:         328
        .size:           8
        .value_kind:     hidden_global_offset_x
      - .offset:         336
        .size:           8
        .value_kind:     hidden_global_offset_y
      - .offset:         344
        .size:           8
        .value_kind:     hidden_global_offset_z
      - .offset:         352
        .size:           2
        .value_kind:     hidden_grid_dims
      - .offset:         376
        .size:           8
        .value_kind:     hidden_multigrid_sync_arg
    .group_segment_fixed_size: 155664
    .kernarg_segment_align: 8
    .kernarg_segment_size: 544
    .language:       OpenCL C
    .language_version:
      - 2
      - 0
    .max_flat_workgroup_size: 512
    .name:           _Z14fwd_megakernel6Params
    .private_segment_fixed_size: 0
    .sgpr_count:     108
    .sgpr_spill_count: 263
    .symbol:         _Z14fwd_megakernel6Params.kd
    .uniform_work_group_size: 1
    .uses_dynamic_stack: false
    .vgpr_count:     256
    .vgpr_spill_count: 0
    .wavefront_size: 64
